# GEMM K-loops: chained 64-bit VGPR address adds for LDS-DMA replaced by SGPR base snapshots + scalar adds (64 more sites)
# speedup vs baseline: 1.0129x; 1.0026x over previous
.LBB0_398:
	s_add_u32 s48, s10, 0xfffc0080
	s_addc_u32 s49, s11, -1
	s_add_i32 s83, 0, 0x10000
	s_cmp_eq_u32 s67, 12
	s_cselect_b32 s61, s9, s49
	s_cselect_b32 s60, s55, s48
	v_add_u32_e32 v128, s83, v173
	s_cselect_b32 s49, s53, s66
	s_cselect_b32 s48, s64, s65
	s_add_i32 s85, 0, 0x14000
	ds_read_b128 v[168:171], v128
	ds_read_b128 v[176:179], v128 offset:1024
	ds_read_b128 v[180:183], v128 offset:2048
	ds_read_b128 v[184:187], v128 offset:3072
	v_add_u32_e32 v128, s85, v173
	ds_read_b128 v[188:191], v128
	ds_read_b128 v[192:195], v128 offset:1024
	ds_read_b128 v[196:199], v128 offset:2048
	ds_read_b128 v[202:205], v128 offset:3072
	s_add_i32 m0, s63, 0xc000
	ds_read_b128 v[206:209], v200
	ds_read_b128 v[210:213], v200 offset:1024
	ds_read_b128 v[218:221], v200 offset:2048
	ds_read_b128 v[222:225], v200 offset:3072
	ds_read_b128 v[226:229], v200 offset:4096
	ds_read_b128 v[234:237], v200 offset:5120
	ds_read_b128 v[238:241], v200 offset:6144
	ds_read_b128 v[242:245], v200 offset:7168
	global_load_lds_dwordx4 v148, s[10:11]
	s_add_i32 m0, s63, 0xe000
	s_nop 0
	global_load_lds_dwordx4 v150, s[10:11]
	s_waitcnt vmcnt(8)
	s_waitcnt lgkmcnt(0)
	s_barrier
	s_setprio 1
	s_waitcnt lgkmcnt(0)
	v_mfma_f32_16x16x32_bf16 v[124:127], v[168:171], v[206:209], v[124:127]
	v_mfma_f32_16x16x32_bf16 v[120:123], v[180:183], v[206:209], v[120:123]
	v_mfma_f32_16x16x32_bf16 v[108:111], v[168:171], v[218:221], v[108:111]
	v_mfma_f32_16x16x32_bf16 v[104:107], v[180:183], v[218:221], v[104:107]
	v_mfma_f32_16x16x32_bf16 v[92:95], v[168:171], v[226:229], v[92:95]
	v_mfma_f32_16x16x32_bf16 v[88:91], v[180:183], v[226:229], v[88:91]
	v_mfma_f32_16x16x32_bf16 v[76:79], v[168:171], v[238:241], v[76:79]
	v_mfma_f32_16x16x32_bf16 v[72:75], v[180:183], v[238:241], v[72:75]
	v_mfma_f32_16x16x32_bf16 v[124:127], v[176:179], v[210:213], v[124:127]
	v_mfma_f32_16x16x32_bf16 v[120:123], v[184:187], v[210:213], v[120:123]
	v_mfma_f32_16x16x32_bf16 v[108:111], v[176:179], v[222:225], v[108:111]
	v_mfma_f32_16x16x32_bf16 v[104:107], v[184:187], v[222:225], v[104:107]
	v_mfma_f32_16x16x32_bf16 v[92:95], v[176:179], v[234:237], v[92:95]
	v_mfma_f32_16x16x32_bf16 v[88:91], v[184:187], v[234:237], v[88:91]
	v_mfma_f32_16x16x32_bf16 v[76:79], v[176:179], v[242:245], v[76:79]
	v_mfma_f32_16x16x32_bf16 v[72:75], v[184:187], v[242:245], v[72:75]
	s_setprio 0
	s_setprio 1
	v_mfma_f32_16x16x32_bf16 v[116:119], v[188:191], v[206:209], v[116:119]
	v_mfma_f32_16x16x32_bf16 v[112:115], v[196:199], v[206:209], v[112:115]
	v_mfma_f32_16x16x32_bf16 v[100:103], v[188:191], v[218:221], v[100:103]
	v_mfma_f32_16x16x32_bf16 v[96:99], v[196:199], v[218:221], v[96:99]
	v_mfma_f32_16x16x32_bf16 v[84:87], v[188:191], v[226:229], v[84:87]
	v_mfma_f32_16x16x32_bf16 v[80:83], v[196:199], v[226:229], v[80:83]
	v_mfma_f32_16x16x32_bf16 v[68:71], v[188:191], v[238:241], v[68:71]
	v_mfma_f32_16x16x32_bf16 v[64:67], v[196:199], v[238:241], v[64:67]
	v_mfma_f32_16x16x32_bf16 v[116:119], v[192:195], v[210:213], v[116:119]
	v_mfma_f32_16x16x32_bf16 v[112:115], v[202:205], v[210:213], v[112:115]
	v_mfma_f32_16x16x32_bf16 v[100:103], v[192:195], v[222:225], v[100:103]
	v_mfma_f32_16x16x32_bf16 v[96:99], v[202:205], v[222:225], v[96:99]
	v_mfma_f32_16x16x32_bf16 v[84:87], v[192:195], v[234:237], v[84:87]
	v_mfma_f32_16x16x32_bf16 v[80:83], v[202:205], v[234:237], v[80:83]
	v_mfma_f32_16x16x32_bf16 v[68:71], v[192:195], v[242:245], v[68:71]
	v_mfma_f32_16x16x32_bf16 v[64:67], v[202:205], v[242:245], v[64:67]
	s_setprio 0
	s_barrier
	s_add_i32 s83, s83, s74
	s_mov_b64 s[98:99], s[48:49]
	s_mov_b32 m0, s83
	ds_read_b128 v[206:209], v200 offset:16384
	ds_read_b128 v[210:213], v200 offset:17408
	ds_read_b128 v[218:221], v200 offset:18432
	ds_read_b128 v[222:225], v200 offset:19456
	ds_read_b128 v[226:229], v200 offset:20480
	ds_read_b128 v[234:237], v200 offset:21504
	ds_read_b128 v[238:241], v200 offset:22528
	ds_read_b128 v[242:245], v200 offset:23552
	global_load_lds_dwordx4 v136, s[48:49]
	s_add_i32 m0, s83, 0x2000
	s_add_u32 s86, s48, 0x40000
	s_addc_u32 s87, s49, 0
	s_add_i32 s83, s85, s74
	global_load_lds_dwordx4 v140, s[48:49]
	s_mov_b32 m0, s83
	s_mov_b64 s[100:101], s[60:61]
	global_load_lds_dwordx4 v136, s[86:87]
	s_add_i32 m0, s83, 0x2000
	s_nop 0
	global_load_lds_dwordx4 v140, s[86:87]
	s_mov_b32 m0, s63
	s_nop 0
	global_load_lds_dwordx4 v134, s[60:61]
	s_mov_b32 m0, s75
	s_nop 0
	global_load_lds_dwordx4 v138, s[60:61]
	s_waitcnt vmcnt(8)
	s_waitcnt lgkmcnt(0)
	s_barrier
	s_setprio 1
	s_waitcnt lgkmcnt(0)
	v_mfma_f32_16x16x32_bf16 v[60:63], v[168:171], v[206:209], v[60:63]
	v_mfma_f32_16x16x32_bf16 v[56:59], v[180:183], v[206:209], v[56:59]
	v_mfma_f32_16x16x32_bf16 v[44:47], v[168:171], v[218:221], v[44:47]
	v_mfma_f32_16x16x32_bf16 v[40:43], v[180:183], v[218:221], v[40:43]
	v_mfma_f32_16x16x32_bf16 v[28:31], v[168:171], v[226:229], v[28:31]
	v_mfma_f32_16x16x32_bf16 v[24:27], v[180:183], v[226:229], v[24:27]
	v_mfma_f32_16x16x32_bf16 v[12:15], v[168:171], v[238:241], v[12:15]
	v_mfma_f32_16x16x32_bf16 v[8:11], v[180:183], v[238:241], v[8:11]
	v_mfma_f32_16x16x32_bf16 v[60:63], v[176:179], v[210:213], v[60:63]
	v_mfma_f32_16x16x32_bf16 v[56:59], v[184:187], v[210:213], v[56:59]
	v_mfma_f32_16x16x32_bf16 v[44:47], v[176:179], v[222:225], v[44:47]
	v_mfma_f32_16x16x32_bf16 v[40:43], v[184:187], v[222:225], v[40:43]
	v_mfma_f32_16x16x32_bf16 v[28:31], v[176:179], v[234:237], v[28:31]
	v_mfma_f32_16x16x32_bf16 v[24:27], v[184:187], v[234:237], v[24:27]
	v_mfma_f32_16x16x32_bf16 v[12:15], v[176:179], v[242:245], v[12:15]
	v_mfma_f32_16x16x32_bf16 v[8:11], v[184:187], v[242:245], v[8:11]
	s_setprio 0
	s_setprio 1
	v_mfma_f32_16x16x32_bf16 v[52:55], v[188:191], v[206:209], v[52:55]
	v_mfma_f32_16x16x32_bf16 v[48:51], v[196:199], v[206:209], v[48:51]
	v_mfma_f32_16x16x32_bf16 v[36:39], v[188:191], v[218:221], v[36:39]
	v_mfma_f32_16x16x32_bf16 v[32:35], v[196:199], v[218:221], v[32:35]
	v_mfma_f32_16x16x32_bf16 v[20:23], v[188:191], v[226:229], v[20:23]
	v_mfma_f32_16x16x32_bf16 v[16:19], v[196:199], v[226:229], v[16:19]
	v_mfma_f32_16x16x32_bf16 v[4:7], v[188:191], v[238:241], v[4:7]
	v_mfma_f32_16x16x32_bf16 v[0:3], v[196:199], v[238:241], v[0:3]
	v_mfma_f32_16x16x32_bf16 v[52:55], v[192:195], v[210:213], v[52:55]
	v_mfma_f32_16x16x32_bf16 v[48:51], v[202:205], v[210:213], v[48:51]
	v_mfma_f32_16x16x32_bf16 v[36:39], v[192:195], v[222:225], v[36:39]
	v_mfma_f32_16x16x32_bf16 v[32:35], v[202:205], v[222:225], v[32:35]
	v_mfma_f32_16x16x32_bf16 v[20:23], v[192:195], v[234:237], v[20:23]
	v_mfma_f32_16x16x32_bf16 v[16:19], v[202:205], v[234:237], v[16:19]
	v_mfma_f32_16x16x32_bf16 v[4:7], v[192:195], v[242:245], v[4:7]
	v_mfma_f32_16x16x32_bf16 v[0:3], v[202:205], v[242:245], v[0:3]
	s_setprio 0
	s_barrier
	v_add_u32_e32 v128, s0, v173
	s_add_i32 s83, 0, 0x1c000
	ds_read_b128 v[168:171], v128
	ds_read_b128 v[176:179], v128 offset:1024
	ds_read_b128 v[180:183], v128 offset:2048
	ds_read_b128 v[184:187], v128 offset:3072
	v_add_u32_e32 v128, s83, v173
	ds_read_b128 v[188:191], v128
	ds_read_b128 v[192:195], v128 offset:1024
	ds_read_b128 v[196:199], v128 offset:2048
	ds_read_b128 v[202:205], v128 offset:3072
	s_add_u32 s60, s60, 0x40000
	s_addc_u32 s61, s61, 0
	s_mov_b32 m0, s76
	ds_read_b128 v[206:209], v200 offset:32768
	ds_read_b128 v[210:213], v200 offset:33792
	ds_read_b128 v[218:221], v200 offset:34816
	ds_read_b128 v[222:225], v200 offset:35840
	ds_read_b128 v[226:229], v200 offset:36864
	ds_read_b128 v[234:237], v200 offset:37888
	ds_read_b128 v[238:241], v200 offset:38912
	ds_read_b128 v[242:245], v200 offset:39936
	global_load_lds_dwordx4 v134, s[60:61]
	v_lshl_add_u64 v[250:251], s[60:61], 0, v[138:139]
	s_mov_b32 m0, s77
	s_nop 0
	global_load_lds_dwordx4 v[250:251], off
	s_waitcnt vmcnt(8)
	s_waitcnt lgkmcnt(0)
	s_barrier
	s_setprio 1
	s_waitcnt lgkmcnt(0)
	v_mfma_f32_16x16x32_bf16 v[124:127], v[168:171], v[206:209], v[124:127]
	v_mfma_f32_16x16x32_bf16 v[120:123], v[180:183], v[206:209], v[120:123]
	v_mfma_f32_16x16x32_bf16 v[108:111], v[168:171], v[218:221], v[108:111]
	v_mfma_f32_16x16x32_bf16 v[104:107], v[180:183], v[218:221], v[104:107]
	v_mfma_f32_16x16x32_bf16 v[92:95], v[168:171], v[226:229], v[92:95]
	v_mfma_f32_16x16x32_bf16 v[88:91], v[180:183], v[226:229], v[88:91]
	v_mfma_f32_16x16x32_bf16 v[76:79], v[168:171], v[238:241], v[76:79]
	v_mfma_f32_16x16x32_bf16 v[72:75], v[180:183], v[238:241], v[72:75]
	v_mfma_f32_16x16x32_bf16 v[124:127], v[176:179], v[210:213], v[124:127]
	v_mfma_f32_16x16x32_bf16 v[120:123], v[184:187], v[210:213], v[120:123]
	v_mfma_f32_16x16x32_bf16 v[108:111], v[176:179], v[222:225], v[108:111]
	v_mfma_f32_16x16x32_bf16 v[104:107], v[184:187], v[222:225], v[104:107]
	v_mfma_f32_16x16x32_bf16 v[92:95], v[176:179], v[234:237], v[92:95]
	v_mfma_f32_16x16x32_bf16 v[88:91], v[184:187], v[234:237], v[88:91]
	v_mfma_f32_16x16x32_bf16 v[76:79], v[176:179], v[242:245], v[76:79]
	v_mfma_f32_16x16x32_bf16 v[72:75], v[184:187], v[242:245], v[72:75]
	s_setprio 0
	s_setprio 1
	v_mfma_f32_16x16x32_bf16 v[116:119], v[188:191], v[206:209], v[116:119]
	v_mfma_f32_16x16x32_bf16 v[112:115], v[196:199], v[206:209], v[112:115]
	v_mfma_f32_16x16x32_bf16 v[100:103], v[188:191], v[218:221], v[100:103]
	v_mfma_f32_16x16x32_bf16 v[96:99], v[196:199], v[218:221], v[96:99]
	v_mfma_f32_16x16x32_bf16 v[84:87], v[188:191], v[226:229], v[84:87]
	v_mfma_f32_16x16x32_bf16 v[80:83], v[196:199], v[226:229], v[80:83]
	v_mfma_f32_16x16x32_bf16 v[68:71], v[188:191], v[238:241], v[68:71]
	v_mfma_f32_16x16x32_bf16 v[64:67], v[196:199], v[238:241], v[64:67]
	v_mfma_f32_16x16x32_bf16 v[116:119], v[192:195], v[210:213], v[116:119]
	v_mfma_f32_16x16x32_bf16 v[112:115], v[202:205], v[210:213], v[112:115]
	v_mfma_f32_16x16x32_bf16 v[100:103], v[192:195], v[222:225], v[100:103]
	v_mfma_f32_16x16x32_bf16 v[96:99], v[202:205], v[222:225], v[96:99]
	v_mfma_f32_16x16x32_bf16 v[84:87], v[192:195], v[234:237], v[84:87]
	v_mfma_f32_16x16x32_bf16 v[80:83], v[202:205], v[234:237], v[80:83]
	v_mfma_f32_16x16x32_bf16 v[68:71], v[192:195], v[242:245], v[68:71]
	v_mfma_f32_16x16x32_bf16 v[64:67], v[202:205], v[242:245], v[64:67]
	s_setprio 0
	s_barrier
	s_add_i32 s60, s0, s74
	s_add_u32 s98, s98, s12
	s_addc_u32 s99, s99, s13
	s_mov_b32 m0, s60
	ds_read_b128 v[206:209], v200 offset:49152
	ds_read_b128 v[210:213], v200 offset:50176
	ds_read_b128 v[218:221], v200 offset:51200
	ds_read_b128 v[222:225], v200 offset:52224
	ds_read_b128 v[226:229], v200 offset:53248
	ds_read_b128 v[234:237], v200 offset:54272
	ds_read_b128 v[238:241], v200 offset:55296
	ds_read_b128 v[242:245], v200 offset:56320
	global_load_lds_dwordx4 v136, s[98:99]
	s_add_i32 m0, s60, 0x2000
	s_add_u32 s48, s48, 0x40080
	s_addc_u32 s49, s49, 0
	s_add_i32 s60, s83, s74
	global_load_lds_dwordx4 v140, s[98:99]
	s_mov_b32 m0, s60
	s_nop 0
	global_load_lds_dwordx4 v136, s[48:49]
	s_add_i32 m0, s60, 0x2000
	s_nop 0
	global_load_lds_dwordx4 v140, s[48:49]
	s_add_u32 s100, s100, s12
	s_addc_u32 s101, s101, s13
	s_mov_b32 m0, s78
	s_nop 0
	global_load_lds_dwordx4 v134, s[100:101]
	s_mov_b32 m0, s79
	s_nop 0
	global_load_lds_dwordx4 v138, s[100:101]
	s_waitcnt vmcnt(8)
	s_waitcnt lgkmcnt(0)
	s_barrier
	s_setprio 1
	s_waitcnt lgkmcnt(0)
	v_mfma_f32_16x16x32_bf16 v[60:63], v[168:171], v[206:209], v[60:63]
	v_mfma_f32_16x16x32_bf16 v[56:59], v[180:183], v[206:209], v[56:59]
	v_mfma_f32_16x16x32_bf16 v[44:47], v[168:171], v[218:221], v[44:47]
	v_mfma_f32_16x16x32_bf16 v[40:43], v[180:183], v[218:221], v[40:43]
	v_mfma_f32_16x16x32_bf16 v[28:31], v[168:171], v[226:229], v[28:31]
	v_mfma_f32_16x16x32_bf16 v[24:27], v[180:183], v[226:229], v[24:27]
	v_mfma_f32_16x16x32_bf16 v[12:15], v[168:171], v[238:241], v[12:15]
	v_mfma_f32_16x16x32_bf16 v[8:11], v[180:183], v[238:241], v[8:11]
	v_mfma_f32_16x16x32_bf16 v[60:63], v[176:179], v[210:213], v[60:63]
	v_mfma_f32_16x16x32_bf16 v[56:59], v[184:187], v[210:213], v[56:59]
	v_mfma_f32_16x16x32_bf16 v[44:47], v[176:179], v[222:225], v[44:47]
	v_mfma_f32_16x16x32_bf16 v[40:43], v[184:187], v[222:225], v[40:43]
	v_mfma_f32_16x16x32_bf16 v[28:31], v[176:179], v[234:237], v[28:31]
	v_mfma_f32_16x16x32_bf16 v[24:27], v[184:187], v[234:237], v[24:27]
	v_mfma_f32_16x16x32_bf16 v[12:15], v[176:179], v[242:245], v[12:15]
	v_mfma_f32_16x16x32_bf16 v[8:11], v[184:187], v[242:245], v[8:11]
	s_setprio 0
	s_setprio 1
	v_mfma_f32_16x16x32_bf16 v[52:55], v[188:191], v[206:209], v[52:55]
	v_mfma_f32_16x16x32_bf16 v[48:51], v[196:199], v[206:209], v[48:51]
	v_mfma_f32_16x16x32_bf16 v[36:39], v[188:191], v[218:221], v[36:39]
	v_mfma_f32_16x16x32_bf16 v[32:35], v[196:199], v[218:221], v[32:35]
	v_mfma_f32_16x16x32_bf16 v[20:23], v[188:191], v[226:229], v[20:23]
	v_mfma_f32_16x16x32_bf16 v[16:19], v[196:199], v[226:229], v[16:19]
	v_mfma_f32_16x16x32_bf16 v[4:7], v[188:191], v[238:241], v[4:7]
	v_mfma_f32_16x16x32_bf16 v[0:3], v[196:199], v[238:241], v[0:3]
	v_mfma_f32_16x16x32_bf16 v[52:55], v[192:195], v[210:213], v[52:55]
	v_mfma_f32_16x16x32_bf16 v[48:51], v[202:205], v[210:213], v[48:51]
	v_mfma_f32_16x16x32_bf16 v[36:39], v[192:195], v[222:225], v[36:39]
	v_mfma_f32_16x16x32_bf16 v[32:35], v[202:205], v[222:225], v[32:35]
	v_mfma_f32_16x16x32_bf16 v[20:23], v[192:195], v[234:237], v[20:23]
	v_mfma_f32_16x16x32_bf16 v[16:19], v[202:205], v[234:237], v[16:19]
	v_mfma_f32_16x16x32_bf16 v[4:7], v[192:195], v[242:245], v[4:7]
	v_mfma_f32_16x16x32_bf16 v[0:3], v[202:205], v[242:245], v[0:3]
	s_setprio 0
	s_barrier
	s_add_i32 s67, s67, 2
	s_add_u32 s10, s10, 0x100
	s_addc_u32 s11, s11, 0
	s_add_u32 s65, s65, 0x100
	s_addc_u32 s66, s66, 0
	s_cmp_gt_u32 s67, 13
	s_cbranch_scc0 .LBB0_398
	s_and_b64 vcc, exec, s[50:51]
	s_cbranch_vccz .LBB0_401
	s_barrier

.LBB0_479:
	s_add_u32 s66, s48, 0xfffe0080
	s_addc_u32 s67, s49, -1
	s_add_i32 s90, 0, 0x10000
	s_cmp_eq_u32 vcc_lo, 4
	s_cselect_b32 s71, s9, s67
	s_cselect_b32 s70, s61, s66
	s_cselect_b32 s67, s59, s83
	s_cselect_b32 s66, s72, s73
	s_add_i32 vcc_hi, 0, 0x14000
	v_add_u32_e32 v140, s90, v225
	v_add_u32_e32 v144, vcc_hi, v225
	ds_read_b128 v[128:131], v140
	ds_read_b128 v[132:135], v140 offset:1024
	ds_read_b128 v[136:139], v140 offset:2048
	ds_read_b128 v[140:143], v140 offset:3072
	ds_read_b128 v[174:177], v144
	ds_read_b128 v[178:181], v144 offset:1024
	ds_read_b128 v[182:185], v144 offset:2048
	ds_read_b128 v[186:189], v144 offset:3072
	s_add_i32 m0, s4, 0xc000
	ds_read_b128 v[190:193], v228
	ds_read_b128 v[194:197], v228 offset:1024
	ds_read_b128 v[198:201], v228 offset:2048
	ds_read_b128 v[202:205], v228 offset:3072
	ds_read_b128 v[206:209], v228 offset:4096
	ds_read_b128 v[210:213], v228 offset:5120
	ds_read_b128 v[234:237], v228 offset:6144
	ds_read_b128 v[238:241], v228 offset:7168
	global_load_lds_dwordx4 v168, s[48:49]
	s_add_i32 m0, s4, 0xe000
	s_nop 0
	global_load_lds_dwordx4 v170, s[48:49]
	s_waitcnt vmcnt(8)
	s_waitcnt lgkmcnt(0)
	s_barrier
	s_setprio 1
	s_waitcnt lgkmcnt(0)
	v_mfma_i32_16x16x64_i8 v[124:127], v[128:131], v[190:193], v[124:127]
	v_mfma_i32_16x16x64_i8 v[120:123], v[136:139], v[190:193], v[120:123]
	v_mfma_i32_16x16x64_i8 v[116:119], v[128:131], v[198:201], v[116:119]
	v_mfma_i32_16x16x64_i8 v[112:115], v[136:139], v[198:201], v[112:115]
	v_mfma_i32_16x16x64_i8 v[108:111], v[128:131], v[206:209], v[108:111]
	v_mfma_i32_16x16x64_i8 v[104:107], v[136:139], v[206:209], v[104:107]
	v_mfma_i32_16x16x64_i8 v[100:103], v[128:131], v[234:237], v[100:103]
	v_mfma_i32_16x16x64_i8 v[96:99], v[136:139], v[234:237], v[96:99]
	v_mfma_i32_16x16x64_i8 v[124:127], v[132:135], v[194:197], v[124:127]
	v_mfma_i32_16x16x64_i8 v[120:123], v[140:143], v[194:197], v[120:123]
	v_mfma_i32_16x16x64_i8 v[116:119], v[132:135], v[202:205], v[116:119]
	v_mfma_i32_16x16x64_i8 v[112:115], v[140:143], v[202:205], v[112:115]
	v_mfma_i32_16x16x64_i8 v[108:111], v[132:135], v[210:213], v[108:111]
	v_mfma_i32_16x16x64_i8 v[104:107], v[140:143], v[210:213], v[104:107]
	v_mfma_i32_16x16x64_i8 v[100:103], v[132:135], v[238:241], v[100:103]
	v_mfma_i32_16x16x64_i8 v[96:99], v[140:143], v[238:241], v[96:99]
	s_setprio 0
	s_setprio 1
	v_mfma_i32_16x16x64_i8 v[92:95], v[174:177], v[190:193], v[92:95]
	v_mfma_i32_16x16x64_i8 v[88:91], v[182:185], v[190:193], v[88:91]
	v_mfma_i32_16x16x64_i8 v[84:87], v[174:177], v[198:201], v[84:87]
	v_mfma_i32_16x16x64_i8 v[80:83], v[182:185], v[198:201], v[80:83]
	v_mfma_i32_16x16x64_i8 v[76:79], v[174:177], v[206:209], v[76:79]
	v_mfma_i32_16x16x64_i8 v[72:75], v[182:185], v[206:209], v[72:75]
	v_mfma_i32_16x16x64_i8 v[68:71], v[174:177], v[234:237], v[68:71]
	v_mfma_i32_16x16x64_i8 v[64:67], v[182:185], v[234:237], v[64:67]
	v_mfma_i32_16x16x64_i8 v[92:95], v[178:181], v[194:197], v[92:95]
	v_mfma_i32_16x16x64_i8 v[88:91], v[186:189], v[194:197], v[88:91]
	v_mfma_i32_16x16x64_i8 v[84:87], v[178:181], v[202:205], v[84:87]
	v_mfma_i32_16x16x64_i8 v[80:83], v[186:189], v[202:205], v[80:83]
	v_mfma_i32_16x16x64_i8 v[76:79], v[178:181], v[210:213], v[76:79]
	v_mfma_i32_16x16x64_i8 v[72:75], v[186:189], v[210:213], v[72:75]
	v_mfma_i32_16x16x64_i8 v[68:71], v[178:181], v[238:241], v[68:71]
	v_mfma_i32_16x16x64_i8 v[64:67], v[186:189], v[238:241], v[64:67]
	s_setprio 0
	s_barrier
	s_add_i32 s90, s90, s77
	s_mov_b64 s[98:99], s[66:67]
	s_mov_b32 m0, s90
	ds_read_b128 v[190:193], v228 offset:16384
	ds_read_b128 v[194:197], v228 offset:17408
	ds_read_b128 v[198:201], v228 offset:18432
	ds_read_b128 v[202:205], v228 offset:19456
	ds_read_b128 v[206:209], v228 offset:20480
	ds_read_b128 v[210:213], v228 offset:21504
	ds_read_b128 v[234:237], v228 offset:22528
	ds_read_b128 v[238:241], v228 offset:23552
	global_load_lds_dwordx4 v154, s[66:67]
	s_add_i32 m0, s90, 0x2000
	s_add_u32 s90, s66, 0x20000
	s_addc_u32 s91, s67, 0
	s_add_i32 vcc_hi, vcc_hi, s77
	global_load_lds_dwordx4 v158, s[66:67]
	s_mov_b32 m0, vcc_hi
	s_mov_b64 s[100:101], s[70:71]
	global_load_lds_dwordx4 v154, s[90:91]
	s_add_i32 m0, vcc_hi, 0x2000
	s_nop 0
	global_load_lds_dwordx4 v158, s[90:91]
	s_mov_b32 m0, s4
	s_nop 0
	global_load_lds_dwordx4 v152, s[70:71]
	s_mov_b32 m0, s5
	s_nop 0
	global_load_lds_dwordx4 v156, s[70:71]
	s_waitcnt vmcnt(8)
	s_waitcnt lgkmcnt(0)
	s_barrier
	s_setprio 1
	s_waitcnt lgkmcnt(0)
	v_mfma_i32_16x16x64_i8 v[60:63], v[128:131], v[190:193], v[60:63]
	v_mfma_i32_16x16x64_i8 v[56:59], v[136:139], v[190:193], v[56:59]
	v_mfma_i32_16x16x64_i8 v[52:55], v[128:131], v[198:201], v[52:55]
	v_mfma_i32_16x16x64_i8 v[48:51], v[136:139], v[198:201], v[48:51]
	v_mfma_i32_16x16x64_i8 v[44:47], v[128:131], v[206:209], v[44:47]
	v_mfma_i32_16x16x64_i8 v[40:43], v[136:139], v[206:209], v[40:43]
	v_mfma_i32_16x16x64_i8 v[36:39], v[128:131], v[234:237], v[36:39]
	v_mfma_i32_16x16x64_i8 v[32:35], v[136:139], v[234:237], v[32:35]
	v_mfma_i32_16x16x64_i8 v[60:63], v[132:135], v[194:197], v[60:63]
	v_mfma_i32_16x16x64_i8 v[56:59], v[140:143], v[194:197], v[56:59]
	v_mfma_i32_16x16x64_i8 v[52:55], v[132:135], v[202:205], v[52:55]
	v_mfma_i32_16x16x64_i8 v[48:51], v[140:143], v[202:205], v[48:51]
	v_mfma_i32_16x16x64_i8 v[44:47], v[132:135], v[210:213], v[44:47]
	v_mfma_i32_16x16x64_i8 v[40:43], v[140:143], v[210:213], v[40:43]
	v_mfma_i32_16x16x64_i8 v[36:39], v[132:135], v[238:241], v[36:39]
	v_mfma_i32_16x16x64_i8 v[32:35], v[140:143], v[238:241], v[32:35]
	s_setprio 0
	s_setprio 1
	v_mfma_i32_16x16x64_i8 v[28:31], v[174:177], v[190:193], v[28:31]
	v_mfma_i32_16x16x64_i8 v[24:27], v[182:185], v[190:193], v[24:27]
	v_mfma_i32_16x16x64_i8 v[20:23], v[174:177], v[198:201], v[20:23]
	v_mfma_i32_16x16x64_i8 v[16:19], v[182:185], v[198:201], v[16:19]
	v_mfma_i32_16x16x64_i8 v[12:15], v[174:177], v[206:209], v[12:15]
	v_mfma_i32_16x16x64_i8 v[8:11], v[182:185], v[206:209], v[8:11]
	v_mfma_i32_16x16x64_i8 v[4:7], v[174:177], v[234:237], v[4:7]
	v_mfma_i32_16x16x64_i8 v[0:3], v[182:185], v[234:237], v[0:3]
	v_mfma_i32_16x16x64_i8 v[28:31], v[178:181], v[194:197], v[28:31]
	v_mfma_i32_16x16x64_i8 v[24:27], v[186:189], v[194:197], v[24:27]
	v_mfma_i32_16x16x64_i8 v[20:23], v[178:181], v[202:205], v[20:23]
	v_mfma_i32_16x16x64_i8 v[16:19], v[186:189], v[202:205], v[16:19]
	v_mfma_i32_16x16x64_i8 v[12:15], v[178:181], v[210:213], v[12:15]
	v_mfma_i32_16x16x64_i8 v[8:11], v[186:189], v[210:213], v[8:11]
	v_mfma_i32_16x16x64_i8 v[4:7], v[178:181], v[238:241], v[4:7]
	v_mfma_i32_16x16x64_i8 v[0:3], v[186:189], v[238:241], v[0:3]
	s_setprio 0
	s_barrier
	s_add_i32 s90, 0, 0x1c000
	v_add_u32_e32 v140, s0, v225
	v_add_u32_e32 v144, s90, v225
	ds_read_b128 v[128:131], v140
	ds_read_b128 v[132:135], v140 offset:1024
	ds_read_b128 v[136:139], v140 offset:2048
	ds_read_b128 v[140:143], v140 offset:3072
	ds_read_b128 v[174:177], v144
	ds_read_b128 v[178:181], v144 offset:1024
	ds_read_b128 v[182:185], v144 offset:2048
	ds_read_b128 v[186:189], v144 offset:3072
	s_add_u32 s70, s70, 0x20000
	s_addc_u32 s71, s71, 0
	s_mov_b32 m0, s80
	ds_read_b128 v[190:193], v228 offset:32768
	ds_read_b128 v[194:197], v228 offset:33792
	ds_read_b128 v[198:201], v228 offset:34816
	ds_read_b128 v[202:205], v228 offset:35840
	ds_read_b128 v[206:209], v228 offset:36864
	ds_read_b128 v[210:213], v228 offset:37888
	ds_read_b128 v[234:237], v228 offset:38912
	ds_read_b128 v[238:241], v228 offset:39936
	global_load_lds_dwordx4 v152, s[70:71]
	v_lshl_add_u64 v[248:249], s[70:71], 0, v[156:157]
	s_mov_b32 m0, s82
	s_nop 0
	global_load_lds_dwordx4 v[248:249], off
	s_waitcnt vmcnt(8)
	s_waitcnt lgkmcnt(0)
	s_barrier
	s_setprio 1
	s_waitcnt lgkmcnt(0)
	v_mfma_i32_16x16x64_i8 v[124:127], v[128:131], v[190:193], v[124:127]
	v_mfma_i32_16x16x64_i8 v[120:123], v[136:139], v[190:193], v[120:123]
	v_mfma_i32_16x16x64_i8 v[116:119], v[128:131], v[198:201], v[116:119]
	v_mfma_i32_16x16x64_i8 v[112:115], v[136:139], v[198:201], v[112:115]
	v_mfma_i32_16x16x64_i8 v[108:111], v[128:131], v[206:209], v[108:111]
	v_mfma_i32_16x16x64_i8 v[104:107], v[136:139], v[206:209], v[104:107]
	v_mfma_i32_16x16x64_i8 v[100:103], v[128:131], v[234:237], v[100:103]
	v_mfma_i32_16x16x64_i8 v[96:99], v[136:139], v[234:237], v[96:99]
	v_mfma_i32_16x16x64_i8 v[124:127], v[132:135], v[194:197], v[124:127]
	v_mfma_i32_16x16x64_i8 v[120:123], v[140:143], v[194:197], v[120:123]
	v_mfma_i32_16x16x64_i8 v[116:119], v[132:135], v[202:205], v[116:119]
	v_mfma_i32_16x16x64_i8 v[112:115], v[140:143], v[202:205], v[112:115]
	v_mfma_i32_16x16x64_i8 v[108:111], v[132:135], v[210:213], v[108:111]
	v_mfma_i32_16x16x64_i8 v[104:107], v[140:143], v[210:213], v[104:107]
	v_mfma_i32_16x16x64_i8 v[100:103], v[132:135], v[238:241], v[100:103]
	v_mfma_i32_16x16x64_i8 v[96:99], v[140:143], v[238:241], v[96:99]
	s_setprio 0
	s_setprio 1
	v_mfma_i32_16x16x64_i8 v[92:95], v[174:177], v[190:193], v[92:95]
	v_mfma_i32_16x16x64_i8 v[88:91], v[182:185], v[190:193], v[88:91]
	v_mfma_i32_16x16x64_i8 v[84:87], v[174:177], v[198:201], v[84:87]
	v_mfma_i32_16x16x64_i8 v[80:83], v[182:185], v[198:201], v[80:83]
	v_mfma_i32_16x16x64_i8 v[76:79], v[174:177], v[206:209], v[76:79]
	v_mfma_i32_16x16x64_i8 v[72:75], v[182:185], v[206:209], v[72:75]
	v_mfma_i32_16x16x64_i8 v[68:71], v[174:177], v[234:237], v[68:71]
	v_mfma_i32_16x16x64_i8 v[64:67], v[182:185], v[234:237], v[64:67]
	v_mfma_i32_16x16x64_i8 v[92:95], v[178:181], v[194:197], v[92:95]
	v_mfma_i32_16x16x64_i8 v[88:91], v[186:189], v[194:197], v[88:91]
	v_mfma_i32_16x16x64_i8 v[84:87], v[178:181], v[202:205], v[84:87]
	v_mfma_i32_16x16x64_i8 v[80:83], v[186:189], v[202:205], v[80:83]
	v_mfma_i32_16x16x64_i8 v[76:79], v[178:181], v[210:213], v[76:79]
	v_mfma_i32_16x16x64_i8 v[72:75], v[186:189], v[210:213], v[72:75]
	v_mfma_i32_16x16x64_i8 v[68:71], v[178:181], v[238:241], v[68:71]
	v_mfma_i32_16x16x64_i8 v[64:67], v[186:189], v[238:241], v[64:67]
	s_setprio 0
	s_barrier
	s_add_i32 s70, s0, s77
	s_add_u32 s98, s98, s14
	s_addc_u32 s99, s99, s15
	s_mov_b32 m0, s70
	ds_read_b128 v[190:193], v228 offset:49152
	ds_read_b128 v[194:197], v228 offset:50176
	ds_read_b128 v[198:201], v228 offset:51200
	ds_read_b128 v[202:205], v228 offset:52224
	ds_read_b128 v[206:209], v228 offset:53248
	ds_read_b128 v[210:213], v228 offset:54272
	ds_read_b128 v[234:237], v228 offset:55296
	ds_read_b128 v[238:241], v228 offset:56320
	global_load_lds_dwordx4 v154, s[98:99]
	s_add_i32 m0, s70, 0x2000
	s_add_u32 s66, s66, 0x20080
	s_addc_u32 s67, s67, 0
	s_add_i32 s70, s90, s77
	global_load_lds_dwordx4 v158, s[98:99]
	s_mov_b32 m0, s70
	s_nop 0
	global_load_lds_dwordx4 v154, s[66:67]
	s_add_i32 m0, s70, 0x2000
	s_nop 0
	global_load_lds_dwordx4 v158, s[66:67]
	s_add_u32 s100, s100, s14
	s_addc_u32 s101, s101, s15
	s_mov_b32 m0, s84
	s_nop 0
	global_load_lds_dwordx4 v152, s[100:101]
	s_mov_b32 m0, s74
	s_nop 0
	global_load_lds_dwordx4 v156, s[100:101]
	s_waitcnt vmcnt(8)
	s_waitcnt lgkmcnt(0)
	s_barrier
	s_setprio 1
	s_waitcnt lgkmcnt(0)
	v_mfma_i32_16x16x64_i8 v[60:63], v[128:131], v[190:193], v[60:63]
	v_mfma_i32_16x16x64_i8 v[56:59], v[136:139], v[190:193], v[56:59]
	v_mfma_i32_16x16x64_i8 v[52:55], v[128:131], v[198:201], v[52:55]
	v_mfma_i32_16x16x64_i8 v[48:51], v[136:139], v[198:201], v[48:51]
	v_mfma_i32_16x16x64_i8 v[44:47], v[128:131], v[206:209], v[44:47]
	v_mfma_i32_16x16x64_i8 v[40:43], v[136:139], v[206:209], v[40:43]
	v_mfma_i32_16x16x64_i8 v[36:39], v[128:131], v[234:237], v[36:39]
	v_mfma_i32_16x16x64_i8 v[32:35], v[136:139], v[234:237], v[32:35]
	v_mfma_i32_16x16x64_i8 v[60:63], v[132:135], v[194:197], v[60:63]
	v_mfma_i32_16x16x64_i8 v[56:59], v[140:143], v[194:197], v[56:59]
	v_mfma_i32_16x16x64_i8 v[52:55], v[132:135], v[202:205], v[52:55]
	v_mfma_i32_16x16x64_i8 v[48:51], v[140:143], v[202:205], v[48:51]
	v_mfma_i32_16x16x64_i8 v[44:47], v[132:135], v[210:213], v[44:47]
	v_mfma_i32_16x16x64_i8 v[40:43], v[140:143], v[210:213], v[40:43]
	v_mfma_i32_16x16x64_i8 v[36:39], v[132:135], v[238:241], v[36:39]
	v_mfma_i32_16x16x64_i8 v[32:35], v[140:143], v[238:241], v[32:35]
	s_setprio 0
	s_setprio 1
	v_mfma_i32_16x16x64_i8 v[28:31], v[174:177], v[190:193], v[28:31]
	v_mfma_i32_16x16x64_i8 v[24:27], v[182:185], v[190:193], v[24:27]
	v_mfma_i32_16x16x64_i8 v[20:23], v[174:177], v[198:201], v[20:23]
	v_mfma_i32_16x16x64_i8 v[16:19], v[182:185], v[198:201], v[16:19]
	v_mfma_i32_16x16x64_i8 v[12:15], v[174:177], v[206:209], v[12:15]
	v_mfma_i32_16x16x64_i8 v[8:11], v[182:185], v[206:209], v[8:11]
	v_mfma_i32_16x16x64_i8 v[4:7], v[174:177], v[234:237], v[4:7]
	v_mfma_i32_16x16x64_i8 v[0:3], v[182:185], v[234:237], v[0:3]
	v_mfma_i32_16x16x64_i8 v[28:31], v[178:181], v[194:197], v[28:31]
	v_mfma_i32_16x16x64_i8 v[24:27], v[186:189], v[194:197], v[24:27]
	v_mfma_i32_16x16x64_i8 v[20:23], v[178:181], v[202:205], v[20:23]
	v_mfma_i32_16x16x64_i8 v[16:19], v[186:189], v[202:205], v[16:19]
	v_mfma_i32_16x16x64_i8 v[12:15], v[178:181], v[210:213], v[12:15]
	v_mfma_i32_16x16x64_i8 v[8:11], v[186:189], v[210:213], v[8:11]
	v_mfma_i32_16x16x64_i8 v[4:7], v[178:181], v[238:241], v[4:7]
	v_mfma_i32_16x16x64_i8 v[0:3], v[186:189], v[238:241], v[0:3]
	s_setprio 0
	s_barrier
	s_add_i32 vcc_lo, vcc_lo, 2
	s_add_u32 s48, s48, 0x100
	s_addc_u32 s49, s49, 0
	s_add_u32 s73, s73, 0x100
	s_addc_u32 s83, s83, 0
	s_cmp_gt_u32 vcc_lo, 5
	s_cbranch_scc0 .LBB0_479
	s_and_b64 vcc, exec, s[56:57]
	s_cbranch_vccz .LBB0_482
	s_barrier

.LBB0_925:
	s_add_u32 s58, s56, 0xfffe0080
	s_addc_u32 s59, s57, -1
	s_add_i32 s83, 0, 0x10000
	s_cmp_eq_u32 s82, 4
	s_cselect_b32 s61, s51, s59
	s_cselect_b32 s60, s79, s58
	s_cselect_b32 s59, s43, s81
	s_cselect_b32 s58, s45, s80
	s_add_i32 s86, 0, 0x14000
	v_add_u32_e32 v150, s83, v182
	v_add_u32_e32 v154, s86, v182
	ds_read_b128 v[138:141], v150
	ds_read_b128 v[142:145], v150 offset:1024
	ds_read_b128 v[146:149], v150 offset:2048
	ds_read_b128 v[150:153], v150 offset:3072
	ds_read_b128 v[166:169], v154
	ds_read_b128 v[190:193], v154 offset:1024
	ds_read_b128 v[194:197], v154 offset:2048
	ds_read_b128 v[198:201], v154 offset:3072
	s_add_i32 m0, s12, 0xc000
	ds_read_b128 v[202:205], v185
	ds_read_b128 v[206:209], v185 offset:1024
	ds_read_b128 v[210:213], v185 offset:2048
	ds_read_b128 v[214:217], v185 offset:3072
	ds_read_b128 v[218:221], v185 offset:4096
	ds_read_b128 v[222:225], v185 offset:5120
	ds_read_b128 v[226:229], v185 offset:6144
	ds_read_b128 v[234:237], v185 offset:7168
	global_load_lds_dwordx4 v134, s[56:57]
	s_add_i32 m0, s12, 0xe000
	s_nop 0
	global_load_lds_dwordx4 v136, s[56:57]
	s_waitcnt vmcnt(8)
	s_waitcnt lgkmcnt(0)
	s_barrier
	s_setprio 1
	s_waitcnt lgkmcnt(0)
	v_mfma_i32_16x16x64_i8 v[126:129], v[138:141], v[202:205], v[126:129]
	v_mfma_i32_16x16x64_i8 v[122:125], v[146:149], v[202:205], v[122:125]
	v_mfma_i32_16x16x64_i8 v[110:113], v[138:141], v[210:213], v[110:113]
	v_mfma_i32_16x16x64_i8 v[106:109], v[146:149], v[210:213], v[106:109]
	v_mfma_i32_16x16x64_i8 v[94:97], v[138:141], v[218:221], v[94:97]
	v_mfma_i32_16x16x64_i8 v[90:93], v[146:149], v[218:221], v[90:93]
	v_mfma_i32_16x16x64_i8 v[78:81], v[138:141], v[226:229], v[78:81]
	v_mfma_i32_16x16x64_i8 v[74:77], v[146:149], v[226:229], v[74:77]
	v_mfma_i32_16x16x64_i8 v[126:129], v[142:145], v[206:209], v[126:129]
	v_mfma_i32_16x16x64_i8 v[122:125], v[150:153], v[206:209], v[122:125]
	v_mfma_i32_16x16x64_i8 v[110:113], v[142:145], v[214:217], v[110:113]
	v_mfma_i32_16x16x64_i8 v[106:109], v[150:153], v[214:217], v[106:109]
	v_mfma_i32_16x16x64_i8 v[94:97], v[142:145], v[222:225], v[94:97]
	v_mfma_i32_16x16x64_i8 v[90:93], v[150:153], v[222:225], v[90:93]
	v_mfma_i32_16x16x64_i8 v[78:81], v[142:145], v[234:237], v[78:81]
	v_mfma_i32_16x16x64_i8 v[74:77], v[150:153], v[234:237], v[74:77]
	s_setprio 0
	s_setprio 1
	v_mfma_i32_16x16x64_i8 v[118:121], v[166:169], v[202:205], v[118:121]
	v_mfma_i32_16x16x64_i8 v[114:117], v[194:197], v[202:205], v[114:117]
	v_mfma_i32_16x16x64_i8 v[102:105], v[166:169], v[210:213], v[102:105]
	v_mfma_i32_16x16x64_i8 v[98:101], v[194:197], v[210:213], v[98:101]
	v_mfma_i32_16x16x64_i8 v[86:89], v[166:169], v[218:221], v[86:89]
	v_mfma_i32_16x16x64_i8 v[82:85], v[194:197], v[218:221], v[82:85]
	v_mfma_i32_16x16x64_i8 v[70:73], v[166:169], v[226:229], v[70:73]
	v_mfma_i32_16x16x64_i8 v[66:69], v[194:197], v[226:229], v[66:69]
	v_mfma_i32_16x16x64_i8 v[118:121], v[190:193], v[206:209], v[118:121]
	v_mfma_i32_16x16x64_i8 v[114:117], v[198:201], v[206:209], v[114:117]
	v_mfma_i32_16x16x64_i8 v[102:105], v[190:193], v[214:217], v[102:105]
	v_mfma_i32_16x16x64_i8 v[98:101], v[198:201], v[214:217], v[98:101]
	v_mfma_i32_16x16x64_i8 v[86:89], v[190:193], v[222:225], v[86:89]
	v_mfma_i32_16x16x64_i8 v[82:85], v[198:201], v[222:225], v[82:85]
	v_mfma_i32_16x16x64_i8 v[70:73], v[190:193], v[234:237], v[70:73]
	v_mfma_i32_16x16x64_i8 v[66:69], v[198:201], v[234:237], v[66:69]
	s_setprio 0
	s_barrier
	s_add_i32 s83, s83, s69
	s_mov_b64 s[98:99], s[58:59]
	s_mov_b32 m0, s83
	ds_read_b128 v[202:205], v185 offset:16384
	ds_read_b128 v[206:209], v185 offset:17408
	ds_read_b128 v[210:213], v185 offset:18432
	ds_read_b128 v[214:217], v185 offset:19456
	ds_read_b128 v[218:221], v185 offset:20480
	ds_read_b128 v[222:225], v185 offset:21504
	ds_read_b128 v[226:229], v185 offset:22528
	ds_read_b128 v[234:237], v185 offset:23552
	global_load_lds_dwordx4 v0, s[58:59]
	s_add_i32 m0, s83, 0x2000
	s_add_u32 s84, s58, 0x20000
	s_addc_u32 s85, s59, 0
	s_add_i32 s83, s86, s69
	global_load_lds_dwordx4 v164, s[58:59]
	s_mov_b32 m0, s83
	s_mov_b64 s[100:101], s[60:61]
	global_load_lds_dwordx4 v0, s[84:85]
	s_add_i32 m0, s83, 0x2000
	s_nop 0
	global_load_lds_dwordx4 v164, s[84:85]
	s_mov_b32 m0, s12
	s_nop 0
	global_load_lds_dwordx4 v160, s[60:61]
	s_mov_b32 m0, s49
	s_nop 0
	global_load_lds_dwordx4 v162, s[60:61]
	s_waitcnt vmcnt(8)
	s_waitcnt lgkmcnt(0)
	s_barrier
	s_setprio 1
	s_waitcnt lgkmcnt(0)
	v_mfma_i32_16x16x64_i8 v[62:65], v[138:141], v[202:205], v[62:65]
	v_mfma_i32_16x16x64_i8 v[58:61], v[146:149], v[202:205], v[58:61]
	v_mfma_i32_16x16x64_i8 v[46:49], v[138:141], v[210:213], v[46:49]
	v_mfma_i32_16x16x64_i8 v[42:45], v[146:149], v[210:213], v[42:45]
	v_mfma_i32_16x16x64_i8 v[30:33], v[138:141], v[218:221], v[30:33]
	v_mfma_i32_16x16x64_i8 v[26:29], v[146:149], v[218:221], v[26:29]
	v_mfma_i32_16x16x64_i8 v[10:13], v[138:141], v[226:229], v[10:13]
	v_mfma_i32_16x16x64_i8 v[2:5], v[146:149], v[226:229], v[2:5]
	v_mfma_i32_16x16x64_i8 v[62:65], v[142:145], v[206:209], v[62:65]
	v_mfma_i32_16x16x64_i8 v[58:61], v[150:153], v[206:209], v[58:61]
	v_mfma_i32_16x16x64_i8 v[46:49], v[142:145], v[214:217], v[46:49]
	v_mfma_i32_16x16x64_i8 v[42:45], v[150:153], v[214:217], v[42:45]
	v_mfma_i32_16x16x64_i8 v[30:33], v[142:145], v[222:225], v[30:33]
	v_mfma_i32_16x16x64_i8 v[26:29], v[150:153], v[222:225], v[26:29]
	v_mfma_i32_16x16x64_i8 v[10:13], v[142:145], v[234:237], v[10:13]
	v_mfma_i32_16x16x64_i8 v[2:5], v[150:153], v[234:237], v[2:5]
	s_setprio 0
	s_setprio 1
	v_mfma_i32_16x16x64_i8 v[54:57], v[166:169], v[202:205], v[54:57]
	v_mfma_i32_16x16x64_i8 v[50:53], v[194:197], v[202:205], v[50:53]
	v_mfma_i32_16x16x64_i8 v[38:41], v[166:169], v[210:213], v[38:41]
	v_mfma_i32_16x16x64_i8 v[34:37], v[194:197], v[210:213], v[34:37]
	v_mfma_i32_16x16x64_i8 v[22:25], v[166:169], v[218:221], v[22:25]
	v_mfma_i32_16x16x64_i8 v[18:21], v[194:197], v[218:221], v[18:21]
	v_mfma_i32_16x16x64_i8 v[14:17], v[166:169], v[226:229], v[14:17]
	v_mfma_i32_16x16x64_i8 v[6:9], v[194:197], v[226:229], v[6:9]
	v_mfma_i32_16x16x64_i8 v[54:57], v[190:193], v[206:209], v[54:57]
	v_mfma_i32_16x16x64_i8 v[50:53], v[198:201], v[206:209], v[50:53]
	v_mfma_i32_16x16x64_i8 v[38:41], v[190:193], v[214:217], v[38:41]
	v_mfma_i32_16x16x64_i8 v[34:37], v[198:201], v[214:217], v[34:37]
	v_mfma_i32_16x16x64_i8 v[22:25], v[190:193], v[222:225], v[22:25]
	v_mfma_i32_16x16x64_i8 v[18:21], v[198:201], v[222:225], v[18:21]
	v_mfma_i32_16x16x64_i8 v[14:17], v[190:193], v[234:237], v[14:17]
	v_mfma_i32_16x16x64_i8 v[6:9], v[198:201], v[234:237], v[6:9]
	s_setprio 0
	s_barrier
	s_add_i32 s83, 0, 0x18000
	s_add_i32 s84, 0, 0x1c000
	v_add_u32_e32 v150, s83, v182
	v_add_u32_e32 v189, s84, v182
	ds_read_b128 v[138:141], v150
	ds_read_b128 v[142:145], v150 offset:1024
	ds_read_b128 v[146:149], v150 offset:2048
	ds_read_b128 v[150:153], v150 offset:3072
	ds_read_b128 v[166:169], v189
	ds_read_b128 v[190:193], v189 offset:1024
	ds_read_b128 v[194:197], v189 offset:2048
	ds_read_b128 v[198:201], v189 offset:3072
	s_add_u32 s60, s60, 0x20000
	s_addc_u32 s61, s61, 0
	s_mov_b32 m0, s70
	ds_read_b128 v[202:205], v185 offset:32768
	ds_read_b128 v[206:209], v185 offset:33792
	ds_read_b128 v[210:213], v185 offset:34816
	ds_read_b128 v[214:217], v185 offset:35840
	ds_read_b128 v[218:221], v185 offset:36864
	ds_read_b128 v[222:225], v185 offset:37888
	ds_read_b128 v[226:229], v185 offset:38912
	ds_read_b128 v[234:237], v185 offset:39936
	global_load_lds_dwordx4 v160, s[60:61]
	s_mov_b32 m0, s71
	s_nop 0
	global_load_lds_dwordx4 v162, s[60:61]
	s_waitcnt vmcnt(8)
	s_waitcnt lgkmcnt(0)
	s_barrier
	s_setprio 1
	s_waitcnt lgkmcnt(0)
	v_mfma_i32_16x16x64_i8 v[126:129], v[138:141], v[202:205], v[126:129]
	v_mfma_i32_16x16x64_i8 v[122:125], v[146:149], v[202:205], v[122:125]
	v_mfma_i32_16x16x64_i8 v[110:113], v[138:141], v[210:213], v[110:113]
	v_mfma_i32_16x16x64_i8 v[106:109], v[146:149], v[210:213], v[106:109]
	v_mfma_i32_16x16x64_i8 v[94:97], v[138:141], v[218:221], v[94:97]
	v_mfma_i32_16x16x64_i8 v[90:93], v[146:149], v[218:221], v[90:93]
	v_mfma_i32_16x16x64_i8 v[78:81], v[138:141], v[226:229], v[78:81]
	v_mfma_i32_16x16x64_i8 v[74:77], v[146:149], v[226:229], v[74:77]
	v_mfma_i32_16x16x64_i8 v[126:129], v[142:145], v[206:209], v[126:129]
	v_mfma_i32_16x16x64_i8 v[122:125], v[150:153], v[206:209], v[122:125]
	v_mfma_i32_16x16x64_i8 v[110:113], v[142:145], v[214:217], v[110:113]
	v_mfma_i32_16x16x64_i8 v[106:109], v[150:153], v[214:217], v[106:109]
	v_mfma_i32_16x16x64_i8 v[94:97], v[142:145], v[222:225], v[94:97]
	v_mfma_i32_16x16x64_i8 v[90:93], v[150:153], v[222:225], v[90:93]
	v_mfma_i32_16x16x64_i8 v[78:81], v[142:145], v[234:237], v[78:81]
	v_mfma_i32_16x16x64_i8 v[74:77], v[150:153], v[234:237], v[74:77]
	s_setprio 0
	s_setprio 1
	v_mfma_i32_16x16x64_i8 v[118:121], v[166:169], v[202:205], v[118:121]
	v_mfma_i32_16x16x64_i8 v[114:117], v[194:197], v[202:205], v[114:117]
	v_mfma_i32_16x16x64_i8 v[102:105], v[166:169], v[210:213], v[102:105]
	v_mfma_i32_16x16x64_i8 v[98:101], v[194:197], v[210:213], v[98:101]
	v_mfma_i32_16x16x64_i8 v[86:89], v[166:169], v[218:221], v[86:89]
	v_mfma_i32_16x16x64_i8 v[82:85], v[194:197], v[218:221], v[82:85]
	v_mfma_i32_16x16x64_i8 v[70:73], v[166:169], v[226:229], v[70:73]
	v_mfma_i32_16x16x64_i8 v[66:69], v[194:197], v[226:229], v[66:69]
	v_mfma_i32_16x16x64_i8 v[118:121], v[190:193], v[206:209], v[118:121]
	v_mfma_i32_16x16x64_i8 v[114:117], v[198:201], v[206:209], v[114:117]
	v_mfma_i32_16x16x64_i8 v[102:105], v[190:193], v[214:217], v[102:105]
	v_mfma_i32_16x16x64_i8 v[98:101], v[198:201], v[214:217], v[98:101]
	v_mfma_i32_16x16x64_i8 v[86:89], v[190:193], v[222:225], v[86:89]
	v_mfma_i32_16x16x64_i8 v[82:85], v[198:201], v[222:225], v[82:85]
	v_mfma_i32_16x16x64_i8 v[70:73], v[190:193], v[234:237], v[70:73]
	v_mfma_i32_16x16x64_i8 v[66:69], v[198:201], v[234:237], v[66:69]
	s_setprio 0
	s_barrier
	s_add_i32 s60, s83, s69
	s_add_u32 s98, s98, s14
	s_addc_u32 s99, s99, s15
	s_mov_b32 m0, s60
	ds_read_b128 v[202:205], v185 offset:49152
	ds_read_b128 v[206:209], v185 offset:50176
	ds_read_b128 v[210:213], v185 offset:51200
	ds_read_b128 v[214:217], v185 offset:52224
	ds_read_b128 v[218:221], v185 offset:53248
	ds_read_b128 v[222:225], v185 offset:54272
	ds_read_b128 v[226:229], v185 offset:55296
	ds_read_b128 v[234:237], v185 offset:56320
	global_load_lds_dwordx4 v0, s[98:99]
	s_add_i32 m0, s60, 0x2000
	s_add_u32 s58, s58, 0x20080
	s_addc_u32 s59, s59, 0
	s_add_i32 s60, s84, s69
	global_load_lds_dwordx4 v164, s[98:99]
	s_mov_b32 m0, s60
	s_nop 0
	global_load_lds_dwordx4 v0, s[58:59]
	s_add_i32 m0, s60, 0x2000
	s_nop 0
	global_load_lds_dwordx4 v164, s[58:59]
	s_add_u32 s100, s100, s14
	s_addc_u32 s101, s101, s15
	s_mov_b32 m0, s72
	s_nop 0
	global_load_lds_dwordx4 v160, s[100:101]
	s_mov_b32 m0, s73
	s_nop 0
	global_load_lds_dwordx4 v162, s[100:101]
	s_waitcnt vmcnt(8)
	s_waitcnt lgkmcnt(0)
	s_barrier
	s_setprio 1
	s_waitcnt lgkmcnt(0)
	v_mfma_i32_16x16x64_i8 v[62:65], v[138:141], v[202:205], v[62:65]
	v_mfma_i32_16x16x64_i8 v[58:61], v[146:149], v[202:205], v[58:61]
	v_mfma_i32_16x16x64_i8 v[46:49], v[138:141], v[210:213], v[46:49]
	v_mfma_i32_16x16x64_i8 v[42:45], v[146:149], v[210:213], v[42:45]
	v_mfma_i32_16x16x64_i8 v[30:33], v[138:141], v[218:221], v[30:33]
	v_mfma_i32_16x16x64_i8 v[26:29], v[146:149], v[218:221], v[26:29]
	v_mfma_i32_16x16x64_i8 v[10:13], v[138:141], v[226:229], v[10:13]
	v_mfma_i32_16x16x64_i8 v[2:5], v[146:149], v[226:229], v[2:5]
	v_mfma_i32_16x16x64_i8 v[62:65], v[142:145], v[206:209], v[62:65]
	v_mfma_i32_16x16x64_i8 v[58:61], v[150:153], v[206:209], v[58:61]
	v_mfma_i32_16x16x64_i8 v[46:49], v[142:145], v[214:217], v[46:49]
	v_mfma_i32_16x16x64_i8 v[42:45], v[150:153], v[214:217], v[42:45]
	v_mfma_i32_16x16x64_i8 v[30:33], v[142:145], v[222:225], v[30:33]
	v_mfma_i32_16x16x64_i8 v[26:29], v[150:153], v[222:225], v[26:29]
	v_mfma_i32_16x16x64_i8 v[10:13], v[142:145], v[234:237], v[10:13]
	v_mfma_i32_16x16x64_i8 v[2:5], v[150:153], v[234:237], v[2:5]
	s_setprio 0
	s_setprio 1
	v_mfma_i32_16x16x64_i8 v[54:57], v[166:169], v[202:205], v[54:57]
	v_mfma_i32_16x16x64_i8 v[50:53], v[194:197], v[202:205], v[50:53]
	v_mfma_i32_16x16x64_i8 v[38:41], v[166:169], v[210:213], v[38:41]
	v_mfma_i32_16x16x64_i8 v[34:37], v[194:197], v[210:213], v[34:37]
	v_mfma_i32_16x16x64_i8 v[22:25], v[166:169], v[218:221], v[22:25]
	v_mfma_i32_16x16x64_i8 v[18:21], v[194:197], v[218:221], v[18:21]
	v_mfma_i32_16x16x64_i8 v[14:17], v[166:169], v[226:229], v[14:17]
	v_mfma_i32_16x16x64_i8 v[6:9], v[194:197], v[226:229], v[6:9]
	v_mfma_i32_16x16x64_i8 v[54:57], v[190:193], v[206:209], v[54:57]
	v_mfma_i32_16x16x64_i8 v[50:53], v[198:201], v[206:209], v[50:53]
	v_mfma_i32_16x16x64_i8 v[38:41], v[190:193], v[214:217], v[38:41]
	v_mfma_i32_16x16x64_i8 v[34:37], v[198:201], v[214:217], v[34:37]
	v_mfma_i32_16x16x64_i8 v[22:25], v[190:193], v[222:225], v[22:25]
	v_mfma_i32_16x16x64_i8 v[18:21], v[198:201], v[222:225], v[18:21]
	v_mfma_i32_16x16x64_i8 v[14:17], v[190:193], v[234:237], v[14:17]
	v_mfma_i32_16x16x64_i8 v[6:9], v[198:201], v[234:237], v[6:9]
	s_setprio 0
	s_barrier
	s_add_i32 s82, s82, 2
	s_add_u32 s56, s56, 0x100
	s_addc_u32 s57, s57, 0
	s_add_u32 s80, s80, 0x100
	s_addc_u32 s81, s81, 0
	s_cmp_gt_u32 s82, 5
	s_cbranch_scc0 .LBB0_925
	s_and_b64 vcc, exec, s[40:41]
	s_cbranch_vccz .LBB0_928
	s_barrier

.LBB0_955:
	s_add_u32 s8, s6, 0xfffe0080
	s_addc_u32 s9, s7, -1
	s_add_i32 s70, 0, 0x10000
	s_cmp_eq_u32 s69, 4
	s_cselect_b32 s55, s43, s9
	s_cselect_b32 s54, s49, s8
	v_add_u32_e32 v0, s70, v188
	s_cselect_b32 s9, s39, s68
	s_cselect_b32 s8, s41, s67
	s_add_i32 s72, 0, 0x14000
	ds_read_b128 v[132:135], v0
	ds_read_b128 v[136:139], v0 offset:1024
	ds_read_b128 v[140:143], v0 offset:2048
	ds_read_b128 v[144:147], v0 offset:3072
	v_add_u32_e32 v0, s72, v188
	ds_read_b128 v[148:151], v0
	ds_read_b128 v[152:155], v0 offset:1024
	ds_read_b128 v[176:179], v0 offset:2048
	ds_read_b128 v[180:183], v0 offset:3072
	s_add_i32 m0, s45, 0xc000
	ds_read_b128 v[198:201], v196
	ds_read_b128 v[202:205], v196 offset:1024
	ds_read_b128 v[206:209], v196 offset:2048
	ds_read_b128 v[210:213], v196 offset:3072
	ds_read_b128 v[214:217], v196 offset:4096
	ds_read_b128 v[218:221], v196 offset:5120
	ds_read_b128 v[222:225], v196 offset:6144
	ds_read_b128 v[226:229], v196 offset:7168
	global_load_lds_dwordx4 v172, s[6:7]
	s_add_i32 m0, s45, 0xe000
	s_nop 0
	global_load_lds_dwordx4 v174, s[6:7]
	s_waitcnt vmcnt(8)
	s_waitcnt lgkmcnt(0)
	s_barrier
	s_setprio 1
	s_waitcnt lgkmcnt(0)
	v_mfma_f32_16x16x32_bf16 v[128:131], v[132:135], v[198:201], v[128:131]
	v_mfma_f32_16x16x32_bf16 v[124:127], v[140:143], v[198:201], v[124:127]
	v_mfma_f32_16x16x32_bf16 v[120:123], v[132:135], v[206:209], v[120:123]
	v_mfma_f32_16x16x32_bf16 v[116:119], v[140:143], v[206:209], v[116:119]
	v_mfma_f32_16x16x32_bf16 v[112:115], v[132:135], v[214:217], v[112:115]
	v_mfma_f32_16x16x32_bf16 v[108:111], v[140:143], v[214:217], v[108:111]
	v_mfma_f32_16x16x32_bf16 v[104:107], v[132:135], v[222:225], v[104:107]
	v_mfma_f32_16x16x32_bf16 v[100:103], v[140:143], v[222:225], v[100:103]
	v_mfma_f32_16x16x32_bf16 v[128:131], v[136:139], v[202:205], v[128:131]
	v_mfma_f32_16x16x32_bf16 v[124:127], v[144:147], v[202:205], v[124:127]
	v_mfma_f32_16x16x32_bf16 v[120:123], v[136:139], v[210:213], v[120:123]
	v_mfma_f32_16x16x32_bf16 v[116:119], v[144:147], v[210:213], v[116:119]
	v_mfma_f32_16x16x32_bf16 v[112:115], v[136:139], v[218:221], v[112:115]
	v_mfma_f32_16x16x32_bf16 v[108:111], v[144:147], v[218:221], v[108:111]
	v_mfma_f32_16x16x32_bf16 v[104:107], v[136:139], v[226:229], v[104:107]
	v_mfma_f32_16x16x32_bf16 v[100:103], v[144:147], v[226:229], v[100:103]
	s_setprio 0
	s_setprio 1
	v_mfma_f32_16x16x32_bf16 v[96:99], v[148:151], v[198:201], v[96:99]
	v_mfma_f32_16x16x32_bf16 v[92:95], v[176:179], v[198:201], v[92:95]
	v_mfma_f32_16x16x32_bf16 v[88:91], v[148:151], v[206:209], v[88:91]
	v_mfma_f32_16x16x32_bf16 v[84:87], v[176:179], v[206:209], v[84:87]
	v_mfma_f32_16x16x32_bf16 v[80:83], v[148:151], v[214:217], v[80:83]
	v_mfma_f32_16x16x32_bf16 v[76:79], v[176:179], v[214:217], v[76:79]
	v_mfma_f32_16x16x32_bf16 v[72:75], v[148:151], v[222:225], v[72:75]
	v_mfma_f32_16x16x32_bf16 v[68:71], v[176:179], v[222:225], v[68:71]
	v_mfma_f32_16x16x32_bf16 v[96:99], v[152:155], v[202:205], v[96:99]
	v_mfma_f32_16x16x32_bf16 v[92:95], v[180:183], v[202:205], v[92:95]
	v_mfma_f32_16x16x32_bf16 v[88:91], v[152:155], v[210:213], v[88:91]
	v_mfma_f32_16x16x32_bf16 v[84:87], v[180:183], v[210:213], v[84:87]
	v_mfma_f32_16x16x32_bf16 v[80:83], v[152:155], v[218:221], v[80:83]
	v_mfma_f32_16x16x32_bf16 v[76:79], v[180:183], v[218:221], v[76:79]
	v_mfma_f32_16x16x32_bf16 v[72:75], v[152:155], v[226:229], v[72:75]
	v_mfma_f32_16x16x32_bf16 v[68:71], v[180:183], v[226:229], v[68:71]
	s_setprio 0
	s_barrier
	s_add_i32 s70, s70, s58
	s_mov_b64 s[98:99], s[8:9]
	s_mov_b32 m0, s70
	ds_read_b128 v[198:201], v196 offset:16384
	ds_read_b128 v[202:205], v196 offset:17408
	ds_read_b128 v[206:209], v196 offset:18432
	ds_read_b128 v[210:213], v196 offset:19456
	ds_read_b128 v[214:217], v196 offset:20480
	ds_read_b128 v[218:221], v196 offset:21504
	ds_read_b128 v[222:225], v196 offset:22528
	ds_read_b128 v[226:229], v196 offset:23552
	global_load_lds_dwordx4 v166, s[8:9]
	s_add_i32 m0, s70, 0x2000
	s_add_u32 s70, s8, 0x20000
	s_addc_u32 s71, s9, 0
	s_add_i32 s72, s72, s58
	global_load_lds_dwordx4 v164, s[8:9]
	s_mov_b32 m0, s72
	s_mov_b64 s[100:101], s[54:55]
	global_load_lds_dwordx4 v166, s[70:71]
	s_add_i32 m0, s72, 0x2000
	s_nop 0
	global_load_lds_dwordx4 v164, s[70:71]
	s_mov_b32 m0, s45
	s_nop 0
	global_load_lds_dwordx4 v160, s[54:55]
	s_mov_b32 m0, s59
	s_nop 0
	global_load_lds_dwordx4 v162, s[54:55]
	s_waitcnt vmcnt(8)
	s_waitcnt lgkmcnt(0)
	s_barrier
	s_setprio 1
	s_waitcnt lgkmcnt(0)
	v_mfma_f32_16x16x32_bf16 v[64:67], v[132:135], v[198:201], v[64:67]
	v_mfma_f32_16x16x32_bf16 v[60:63], v[140:143], v[198:201], v[60:63]
	v_mfma_f32_16x16x32_bf16 v[56:59], v[132:135], v[206:209], v[56:59]
	v_mfma_f32_16x16x32_bf16 v[52:55], v[140:143], v[206:209], v[52:55]
	v_mfma_f32_16x16x32_bf16 v[48:51], v[132:135], v[214:217], v[48:51]
	v_mfma_f32_16x16x32_bf16 v[44:47], v[140:143], v[214:217], v[44:47]
	v_mfma_f32_16x16x32_bf16 v[40:43], v[132:135], v[222:225], v[40:43]
	v_mfma_f32_16x16x32_bf16 v[36:39], v[140:143], v[222:225], v[36:39]
	v_mfma_f32_16x16x32_bf16 v[64:67], v[136:139], v[202:205], v[64:67]
	v_mfma_f32_16x16x32_bf16 v[60:63], v[144:147], v[202:205], v[60:63]
	v_mfma_f32_16x16x32_bf16 v[56:59], v[136:139], v[210:213], v[56:59]
	v_mfma_f32_16x16x32_bf16 v[52:55], v[144:147], v[210:213], v[52:55]
	v_mfma_f32_16x16x32_bf16 v[48:51], v[136:139], v[218:221], v[48:51]
	v_mfma_f32_16x16x32_bf16 v[44:47], v[144:147], v[218:221], v[44:47]
	v_mfma_f32_16x16x32_bf16 v[40:43], v[136:139], v[226:229], v[40:43]
	v_mfma_f32_16x16x32_bf16 v[36:39], v[144:147], v[226:229], v[36:39]
	s_setprio 0
	s_setprio 1
	v_mfma_f32_16x16x32_bf16 v[32:35], v[148:151], v[198:201], v[32:35]
	v_mfma_f32_16x16x32_bf16 v[28:31], v[176:179], v[198:201], v[28:31]
	v_mfma_f32_16x16x32_bf16 v[24:27], v[148:151], v[206:209], v[24:27]
	v_mfma_f32_16x16x32_bf16 v[20:23], v[176:179], v[206:209], v[20:23]
	v_mfma_f32_16x16x32_bf16 v[16:19], v[148:151], v[214:217], v[16:19]
	v_mfma_f32_16x16x32_bf16 v[12:15], v[176:179], v[214:217], v[12:15]
	v_mfma_f32_16x16x32_bf16 v[8:11], v[148:151], v[222:225], v[8:11]
	v_mfma_f32_16x16x32_bf16 v[2:5], v[176:179], v[222:225], v[4:7]
	v_mfma_f32_16x16x32_bf16 v[32:35], v[152:155], v[202:205], v[32:35]
	v_mfma_f32_16x16x32_bf16 v[28:31], v[180:183], v[202:205], v[28:31]
	v_mfma_f32_16x16x32_bf16 v[24:27], v[152:155], v[210:213], v[24:27]
	v_mfma_f32_16x16x32_bf16 v[20:23], v[180:183], v[210:213], v[20:23]
	v_mfma_f32_16x16x32_bf16 v[16:19], v[152:155], v[218:221], v[16:19]
	v_mfma_f32_16x16x32_bf16 v[12:15], v[180:183], v[218:221], v[12:15]
	v_mfma_f32_16x16x32_bf16 v[8:11], v[152:155], v[226:229], v[8:11]
	v_mfma_f32_16x16x32_bf16 v[2:5], v[180:183], v[226:229], v[2:5]
	s_setprio 0
	s_barrier
	s_add_i32 s70, 0, 0x18000
	v_add_u32_e32 v0, s70, v188
	s_add_i32 s71, 0, 0x1c000
	ds_read_b128 v[132:135], v0
	ds_read_b128 v[136:139], v0 offset:1024
	ds_read_b128 v[140:143], v0 offset:2048
	ds_read_b128 v[144:147], v0 offset:3072
	v_add_u32_e32 v0, s71, v188
	ds_read_b128 v[148:151], v0
	ds_read_b128 v[152:155], v0 offset:1024
	ds_read_b128 v[176:179], v0 offset:2048
	ds_read_b128 v[180:183], v0 offset:3072
	s_add_u32 s54, s54, 0x20000
	s_addc_u32 s55, s55, 0
	s_mov_b32 m0, s60
	ds_read_b128 v[198:201], v196 offset:32768
	ds_read_b128 v[202:205], v196 offset:33792
	ds_read_b128 v[206:209], v196 offset:34816
	ds_read_b128 v[210:213], v196 offset:35840
	ds_read_b128 v[214:217], v196 offset:36864
	ds_read_b128 v[218:221], v196 offset:37888
	ds_read_b128 v[222:225], v196 offset:38912
	ds_read_b128 v[226:229], v196 offset:39936
	global_load_lds_dwordx4 v160, s[54:55]
	s_mov_b32 m0, s61
	s_nop 0
	global_load_lds_dwordx4 v162, s[54:55]
	s_waitcnt vmcnt(8)
	s_waitcnt lgkmcnt(0)
	s_barrier
	s_setprio 1
	s_waitcnt lgkmcnt(0)
	v_mfma_f32_16x16x32_bf16 v[128:131], v[132:135], v[198:201], v[128:131]
	v_mfma_f32_16x16x32_bf16 v[124:127], v[140:143], v[198:201], v[124:127]
	v_mfma_f32_16x16x32_bf16 v[120:123], v[132:135], v[206:209], v[120:123]
	v_mfma_f32_16x16x32_bf16 v[116:119], v[140:143], v[206:209], v[116:119]
	v_mfma_f32_16x16x32_bf16 v[112:115], v[132:135], v[214:217], v[112:115]
	v_mfma_f32_16x16x32_bf16 v[108:111], v[140:143], v[214:217], v[108:111]
	v_mfma_f32_16x16x32_bf16 v[104:107], v[132:135], v[222:225], v[104:107]
	v_mfma_f32_16x16x32_bf16 v[100:103], v[140:143], v[222:225], v[100:103]
	v_mfma_f32_16x16x32_bf16 v[128:131], v[136:139], v[202:205], v[128:131]
	v_mfma_f32_16x16x32_bf16 v[124:127], v[144:147], v[202:205], v[124:127]
	v_mfma_f32_16x16x32_bf16 v[120:123], v[136:139], v[210:213], v[120:123]
	v_mfma_f32_16x16x32_bf16 v[116:119], v[144:147], v[210:213], v[116:119]
	v_mfma_f32_16x16x32_bf16 v[112:115], v[136:139], v[218:221], v[112:115]
	v_mfma_f32_16x16x32_bf16 v[108:111], v[144:147], v[218:221], v[108:111]
	v_mfma_f32_16x16x32_bf16 v[104:107], v[136:139], v[226:229], v[104:107]
	v_mfma_f32_16x16x32_bf16 v[100:103], v[144:147], v[226:229], v[100:103]
	s_setprio 0
	s_setprio 1
	v_mfma_f32_16x16x32_bf16 v[96:99], v[148:151], v[198:201], v[96:99]
	v_mfma_f32_16x16x32_bf16 v[92:95], v[176:179], v[198:201], v[92:95]
	v_mfma_f32_16x16x32_bf16 v[88:91], v[148:151], v[206:209], v[88:91]
	v_mfma_f32_16x16x32_bf16 v[84:87], v[176:179], v[206:209], v[84:87]
	v_mfma_f32_16x16x32_bf16 v[80:83], v[148:151], v[214:217], v[80:83]
	v_mfma_f32_16x16x32_bf16 v[76:79], v[176:179], v[214:217], v[76:79]
	v_mfma_f32_16x16x32_bf16 v[72:75], v[148:151], v[222:225], v[72:75]
	v_mfma_f32_16x16x32_bf16 v[68:71], v[176:179], v[222:225], v[68:71]
	v_mfma_f32_16x16x32_bf16 v[96:99], v[152:155], v[202:205], v[96:99]
	v_mfma_f32_16x16x32_bf16 v[92:95], v[180:183], v[202:205], v[92:95]
	v_mfma_f32_16x16x32_bf16 v[88:91], v[152:155], v[210:213], v[88:91]
	v_mfma_f32_16x16x32_bf16 v[84:87], v[180:183], v[210:213], v[84:87]
	v_mfma_f32_16x16x32_bf16 v[80:83], v[152:155], v[218:221], v[80:83]
	v_mfma_f32_16x16x32_bf16 v[76:79], v[180:183], v[218:221], v[76:79]
	v_mfma_f32_16x16x32_bf16 v[72:75], v[152:155], v[226:229], v[72:75]
	v_mfma_f32_16x16x32_bf16 v[68:71], v[180:183], v[226:229], v[68:71]
	s_setprio 0
	s_barrier
	s_add_i32 s54, s70, s58
	s_add_u32 s98, s98, s14
	s_addc_u32 s99, s99, s15
	s_mov_b32 m0, s54
	ds_read_b128 v[198:201], v196 offset:49152
	ds_read_b128 v[202:205], v196 offset:50176
	ds_read_b128 v[206:209], v196 offset:51200
	ds_read_b128 v[210:213], v196 offset:52224
	ds_read_b128 v[214:217], v196 offset:53248
	ds_read_b128 v[218:221], v196 offset:54272
	ds_read_b128 v[222:225], v196 offset:55296
	ds_read_b128 v[226:229], v196 offset:56320
	global_load_lds_dwordx4 v166, s[98:99]
	s_add_i32 m0, s54, 0x2000
	s_add_u32 s8, s8, 0x20080
	s_addc_u32 s9, s9, 0
	s_add_i32 s54, s71, s58
	global_load_lds_dwordx4 v164, s[98:99]
	s_mov_b32 m0, s54
	s_nop 0
	global_load_lds_dwordx4 v166, s[8:9]
	s_add_i32 m0, s54, 0x2000
	s_nop 0
	global_load_lds_dwordx4 v164, s[8:9]
	s_add_u32 s100, s100, s14
	s_addc_u32 s101, s101, s15
	s_mov_b32 m0, s63
	s_nop 0
	global_load_lds_dwordx4 v160, s[100:101]
	s_mov_b32 m0, s64
	s_nop 0
	global_load_lds_dwordx4 v162, s[100:101]
	s_waitcnt vmcnt(8)
	s_waitcnt lgkmcnt(0)
	s_barrier
	s_setprio 1
	s_waitcnt lgkmcnt(0)
	v_mfma_f32_16x16x32_bf16 v[64:67], v[132:135], v[198:201], v[64:67]
	v_mfma_f32_16x16x32_bf16 v[60:63], v[140:143], v[198:201], v[60:63]
	v_mfma_f32_16x16x32_bf16 v[56:59], v[132:135], v[206:209], v[56:59]
	v_mfma_f32_16x16x32_bf16 v[52:55], v[140:143], v[206:209], v[52:55]
	v_mfma_f32_16x16x32_bf16 v[48:51], v[132:135], v[214:217], v[48:51]
	v_mfma_f32_16x16x32_bf16 v[44:47], v[140:143], v[214:217], v[44:47]
	v_mfma_f32_16x16x32_bf16 v[40:43], v[132:135], v[222:225], v[40:43]
	v_mfma_f32_16x16x32_bf16 v[36:39], v[140:143], v[222:225], v[36:39]
	v_mfma_f32_16x16x32_bf16 v[64:67], v[136:139], v[202:205], v[64:67]
	v_mfma_f32_16x16x32_bf16 v[60:63], v[144:147], v[202:205], v[60:63]
	v_mfma_f32_16x16x32_bf16 v[56:59], v[136:139], v[210:213], v[56:59]
	v_mfma_f32_16x16x32_bf16 v[52:55], v[144:147], v[210:213], v[52:55]
	v_mfma_f32_16x16x32_bf16 v[48:51], v[136:139], v[218:221], v[48:51]
	v_mfma_f32_16x16x32_bf16 v[44:47], v[144:147], v[218:221], v[44:47]
	v_mfma_f32_16x16x32_bf16 v[40:43], v[136:139], v[226:229], v[40:43]
	v_mfma_f32_16x16x32_bf16 v[36:39], v[144:147], v[226:229], v[36:39]
	s_setprio 0
	s_setprio 1
	v_mfma_f32_16x16x32_bf16 v[32:35], v[148:151], v[198:201], v[32:35]
	v_mfma_f32_16x16x32_bf16 v[28:31], v[176:179], v[198:201], v[28:31]
	v_mfma_f32_16x16x32_bf16 v[24:27], v[148:151], v[206:209], v[24:27]
	v_mfma_f32_16x16x32_bf16 v[20:23], v[176:179], v[206:209], v[20:23]
	v_mfma_f32_16x16x32_bf16 v[16:19], v[148:151], v[214:217], v[16:19]
	v_mfma_f32_16x16x32_bf16 v[12:15], v[176:179], v[214:217], v[12:15]
	v_mfma_f32_16x16x32_bf16 v[6:9], v[148:151], v[222:225], v[8:11]
	v_mfma_f32_16x16x32_bf16 v[2:5], v[176:179], v[222:225], v[2:5]
	v_mfma_f32_16x16x32_bf16 v[32:35], v[152:155], v[202:205], v[32:35]
	v_mfma_f32_16x16x32_bf16 v[28:31], v[180:183], v[202:205], v[28:31]
	v_mfma_f32_16x16x32_bf16 v[24:27], v[152:155], v[210:213], v[24:27]
	v_mfma_f32_16x16x32_bf16 v[20:23], v[180:183], v[210:213], v[20:23]
	v_mfma_f32_16x16x32_bf16 v[16:19], v[152:155], v[218:221], v[16:19]
	v_mfma_f32_16x16x32_bf16 v[12:15], v[180:183], v[218:221], v[12:15]
	v_mfma_f32_16x16x32_bf16 v[8:11], v[152:155], v[226:229], v[6:9]
	v_mfma_f32_16x16x32_bf16 v[4:7], v[180:183], v[226:229], v[2:5]
	s_setprio 0
	s_barrier
	s_add_i32 s69, s69, 2
	s_add_u32 s6, s6, 0x100
	s_addc_u32 s7, s7, 0
	s_add_u32 s67, s67, 0x100
	s_addc_u32 s68, s68, 0
	s_cmp_gt_u32 s69, 5
	s_cbranch_scc0 .LBB0_955
	s_and_b64 vcc, exec, s[34:35]
	s_cbranch_vccz .LBB0_958
	s_barrier

.LBB0_1167:
	s_add_u32 s60, s48, 0xfffc0080
	s_addc_u32 s61, s49, -1
	s_add_i32 s66, 0, 0x10000
	s_cmp_eq_u32 s65, 12
	s_cselect_b32 s63, s14, s61
	s_cselect_b32 s62, s51, s60
	v_add_u32_e32 v0, s66, v169
	s_cselect_b32 s61, s45, s64
	s_cselect_b32 s60, s57, s59
	s_add_i32 s68, 0, 0x14000
	ds_read_b128 v[148:151], v0
	ds_read_b128 v[152:155], v0 offset:1024
	ds_read_b128 v[156:159], v0 offset:2048
	ds_read_b128 v[190:193], v0 offset:3072
	v_add_u32_e32 v0, s68, v169
	ds_read_b128 v[194:197], v0
	ds_read_b128 v[198:201], v0 offset:1024
	ds_read_b128 v[202:205], v0 offset:2048
	ds_read_b128 v[206:209], v0 offset:3072
	s_add_i32 m0, s79, 0xc000
	ds_read_b128 v[210:213], v188
	ds_read_b128 v[214:217], v188 offset:1024
	ds_read_b128 v[218:221], v188 offset:2048
	ds_read_b128 v[222:225], v188 offset:3072
	ds_read_b128 v[226:229], v188 offset:4096
	ds_read_b128 v[234:237], v188 offset:5120
	ds_read_b128 v[238:241], v188 offset:6144
	ds_read_b128 v[242:245], v188 offset:7168
	global_load_lds_dwordx4 v144, s[48:49]
	s_add_i32 m0, s79, 0xe000
	s_nop 0
	global_load_lds_dwordx4 v146, s[48:49]
	s_waitcnt vmcnt(8)
	s_waitcnt lgkmcnt(0)
	s_barrier
	s_setprio 1
	s_waitcnt lgkmcnt(0)
	v_mfma_f32_16x16x32_bf16 v[126:129], v[148:151], v[210:213], v[126:129]
	v_mfma_f32_16x16x32_bf16 v[122:125], v[156:159], v[210:213], v[122:125]
	v_mfma_f32_16x16x32_bf16 v[110:113], v[148:151], v[218:221], v[110:113]
	v_mfma_f32_16x16x32_bf16 v[106:109], v[156:159], v[218:221], v[106:109]
	v_mfma_f32_16x16x32_bf16 v[94:97], v[148:151], v[226:229], v[94:97]
	v_mfma_f32_16x16x32_bf16 v[90:93], v[156:159], v[226:229], v[90:93]
	v_mfma_f32_16x16x32_bf16 v[78:81], v[148:151], v[238:241], v[78:81]
	v_mfma_f32_16x16x32_bf16 v[74:77], v[156:159], v[238:241], v[74:77]
	v_mfma_f32_16x16x32_bf16 v[126:129], v[152:155], v[214:217], v[126:129]
	v_mfma_f32_16x16x32_bf16 v[122:125], v[190:193], v[214:217], v[122:125]
	v_mfma_f32_16x16x32_bf16 v[110:113], v[152:155], v[222:225], v[110:113]
	v_mfma_f32_16x16x32_bf16 v[106:109], v[190:193], v[222:225], v[106:109]
	v_mfma_f32_16x16x32_bf16 v[94:97], v[152:155], v[234:237], v[94:97]
	v_mfma_f32_16x16x32_bf16 v[90:93], v[190:193], v[234:237], v[90:93]
	v_mfma_f32_16x16x32_bf16 v[78:81], v[152:155], v[242:245], v[78:81]
	v_mfma_f32_16x16x32_bf16 v[74:77], v[190:193], v[242:245], v[74:77]
	s_setprio 0
	s_setprio 1
	v_mfma_f32_16x16x32_bf16 v[118:121], v[194:197], v[210:213], v[118:121]
	v_mfma_f32_16x16x32_bf16 v[114:117], v[202:205], v[210:213], v[114:117]
	v_mfma_f32_16x16x32_bf16 v[102:105], v[194:197], v[218:221], v[102:105]
	v_mfma_f32_16x16x32_bf16 v[98:101], v[202:205], v[218:221], v[98:101]
	v_mfma_f32_16x16x32_bf16 v[86:89], v[194:197], v[226:229], v[86:89]
	v_mfma_f32_16x16x32_bf16 v[82:85], v[202:205], v[226:229], v[82:85]
	v_mfma_f32_16x16x32_bf16 v[70:73], v[194:197], v[238:241], v[70:73]
	v_mfma_f32_16x16x32_bf16 v[66:69], v[202:205], v[238:241], v[66:69]
	v_mfma_f32_16x16x32_bf16 v[118:121], v[198:201], v[214:217], v[118:121]
	v_mfma_f32_16x16x32_bf16 v[114:117], v[206:209], v[214:217], v[114:117]
	v_mfma_f32_16x16x32_bf16 v[102:105], v[198:201], v[222:225], v[102:105]
	v_mfma_f32_16x16x32_bf16 v[98:101], v[206:209], v[222:225], v[98:101]
	v_mfma_f32_16x16x32_bf16 v[86:89], v[198:201], v[234:237], v[86:89]
	v_mfma_f32_16x16x32_bf16 v[82:85], v[206:209], v[234:237], v[82:85]
	v_mfma_f32_16x16x32_bf16 v[70:73], v[198:201], v[242:245], v[70:73]
	v_mfma_f32_16x16x32_bf16 v[66:69], v[206:209], v[242:245], v[66:69]
	s_setprio 0
	s_barrier
	s_add_i32 s66, s66, s78
	s_mov_b64 s[98:99], s[60:61]
	s_mov_b32 m0, s66
	ds_read_b128 v[210:213], v188 offset:16384
	ds_read_b128 v[214:217], v188 offset:17408
	ds_read_b128 v[218:221], v188 offset:18432
	ds_read_b128 v[222:225], v188 offset:19456
	ds_read_b128 v[226:229], v188 offset:20480
	ds_read_b128 v[234:237], v188 offset:21504
	ds_read_b128 v[238:241], v188 offset:22528
	ds_read_b128 v[242:245], v188 offset:23552
	global_load_lds_dwordx4 v136, s[60:61]
	s_add_i32 m0, s66, 0x2000
	s_add_u32 s66, s60, 0x40000
	s_addc_u32 s67, s61, 0
	s_add_i32 s68, s68, s78
	global_load_lds_dwordx4 v140, s[60:61]
	s_mov_b32 m0, s68
	s_mov_b64 s[100:101], s[62:63]
	global_load_lds_dwordx4 v136, s[66:67]
	s_add_i32 m0, s68, 0x2000
	s_nop 0
	global_load_lds_dwordx4 v140, s[66:67]
	s_mov_b32 m0, s79
	s_nop 0
	global_load_lds_dwordx4 v134, s[62:63]
	s_mov_b32 m0, s80
	s_nop 0
	global_load_lds_dwordx4 v138, s[62:63]
	s_waitcnt vmcnt(8)
	s_waitcnt lgkmcnt(0)
	s_barrier
	s_setprio 1
	s_waitcnt lgkmcnt(0)
	v_mfma_f32_16x16x32_bf16 v[62:65], v[148:151], v[210:213], v[62:65]
	v_mfma_f32_16x16x32_bf16 v[58:61], v[156:159], v[210:213], v[58:61]
	v_mfma_f32_16x16x32_bf16 v[46:49], v[148:151], v[218:221], v[46:49]
	v_mfma_f32_16x16x32_bf16 v[42:45], v[156:159], v[218:221], v[42:45]
	v_mfma_f32_16x16x32_bf16 v[30:33], v[148:151], v[226:229], v[30:33]
	v_mfma_f32_16x16x32_bf16 v[26:29], v[156:159], v[226:229], v[26:29]
	v_mfma_f32_16x16x32_bf16 v[14:17], v[148:151], v[238:241], v[14:17]
	v_mfma_f32_16x16x32_bf16 v[10:13], v[156:159], v[238:241], v[10:13]
	v_mfma_f32_16x16x32_bf16 v[62:65], v[152:155], v[214:217], v[62:65]
	v_mfma_f32_16x16x32_bf16 v[58:61], v[190:193], v[214:217], v[58:61]
	v_mfma_f32_16x16x32_bf16 v[46:49], v[152:155], v[222:225], v[46:49]
	v_mfma_f32_16x16x32_bf16 v[42:45], v[190:193], v[222:225], v[42:45]
	v_mfma_f32_16x16x32_bf16 v[30:33], v[152:155], v[234:237], v[30:33]
	v_mfma_f32_16x16x32_bf16 v[26:29], v[190:193], v[234:237], v[26:29]
	v_mfma_f32_16x16x32_bf16 v[14:17], v[152:155], v[242:245], v[14:17]
	v_mfma_f32_16x16x32_bf16 v[10:13], v[190:193], v[242:245], v[10:13]
	s_setprio 0
	s_setprio 1
	v_mfma_f32_16x16x32_bf16 v[54:57], v[194:197], v[210:213], v[54:57]
	v_mfma_f32_16x16x32_bf16 v[50:53], v[202:205], v[210:213], v[50:53]
	v_mfma_f32_16x16x32_bf16 v[38:41], v[194:197], v[218:221], v[38:41]
	v_mfma_f32_16x16x32_bf16 v[34:37], v[202:205], v[218:221], v[34:37]
	v_mfma_f32_16x16x32_bf16 v[22:25], v[194:197], v[226:229], v[22:25]
	v_mfma_f32_16x16x32_bf16 v[18:21], v[202:205], v[226:229], v[18:21]
	v_mfma_f32_16x16x32_bf16 v[6:9], v[194:197], v[238:241], v[6:9]
	v_mfma_f32_16x16x32_bf16 v[2:5], v[202:205], v[238:241], v[2:5]
	v_mfma_f32_16x16x32_bf16 v[54:57], v[198:201], v[214:217], v[54:57]
	v_mfma_f32_16x16x32_bf16 v[50:53], v[206:209], v[214:217], v[50:53]
	v_mfma_f32_16x16x32_bf16 v[38:41], v[198:201], v[222:225], v[38:41]
	v_mfma_f32_16x16x32_bf16 v[34:37], v[206:209], v[222:225], v[34:37]
	v_mfma_f32_16x16x32_bf16 v[22:25], v[198:201], v[234:237], v[22:25]
	v_mfma_f32_16x16x32_bf16 v[18:21], v[206:209], v[234:237], v[18:21]
	v_mfma_f32_16x16x32_bf16 v[6:9], v[198:201], v[242:245], v[6:9]
	v_mfma_f32_16x16x32_bf16 v[2:5], v[206:209], v[242:245], v[2:5]
	s_setprio 0
	s_barrier
	s_add_i32 s66, 0, 0x18000
	v_add_u32_e32 v0, s66, v169
	s_add_i32 s67, 0, 0x1c000
	ds_read_b128 v[148:151], v0
	ds_read_b128 v[152:155], v0 offset:1024
	ds_read_b128 v[156:159], v0 offset:2048
	ds_read_b128 v[190:193], v0 offset:3072
	v_add_u32_e32 v0, s67, v169
	ds_read_b128 v[194:197], v0
	ds_read_b128 v[198:201], v0 offset:1024
	ds_read_b128 v[202:205], v0 offset:2048
	ds_read_b128 v[206:209], v0 offset:3072
	s_add_u32 s62, s62, 0x40000
	s_addc_u32 s63, s63, 0
	s_mov_b32 m0, s81
	ds_read_b128 v[210:213], v188 offset:32768
	ds_read_b128 v[214:217], v188 offset:33792
	ds_read_b128 v[218:221], v188 offset:34816
	ds_read_b128 v[222:225], v188 offset:35840
	ds_read_b128 v[226:229], v188 offset:36864
	ds_read_b128 v[234:237], v188 offset:37888
	ds_read_b128 v[238:241], v188 offset:38912
	ds_read_b128 v[242:245], v188 offset:39936
	global_load_lds_dwordx4 v134, s[62:63]
	s_mov_b32 m0, s82
	s_nop 0
	global_load_lds_dwordx4 v138, s[62:63]
	s_waitcnt vmcnt(8)
	s_waitcnt lgkmcnt(0)
	s_barrier
	s_setprio 1
	s_waitcnt lgkmcnt(0)
	v_mfma_f32_16x16x32_bf16 v[126:129], v[148:151], v[210:213], v[126:129]
	v_mfma_f32_16x16x32_bf16 v[122:125], v[156:159], v[210:213], v[122:125]
	v_mfma_f32_16x16x32_bf16 v[110:113], v[148:151], v[218:221], v[110:113]
	v_mfma_f32_16x16x32_bf16 v[106:109], v[156:159], v[218:221], v[106:109]
	v_mfma_f32_16x16x32_bf16 v[94:97], v[148:151], v[226:229], v[94:97]
	v_mfma_f32_16x16x32_bf16 v[90:93], v[156:159], v[226:229], v[90:93]
	v_mfma_f32_16x16x32_bf16 v[78:81], v[148:151], v[238:241], v[78:81]
	v_mfma_f32_16x16x32_bf16 v[74:77], v[156:159], v[238:241], v[74:77]
	v_mfma_f32_16x16x32_bf16 v[126:129], v[152:155], v[214:217], v[126:129]
	v_mfma_f32_16x16x32_bf16 v[122:125], v[190:193], v[214:217], v[122:125]
	v_mfma_f32_16x16x32_bf16 v[110:113], v[152:155], v[222:225], v[110:113]
	v_mfma_f32_16x16x32_bf16 v[106:109], v[190:193], v[222:225], v[106:109]
	v_mfma_f32_16x16x32_bf16 v[94:97], v[152:155], v[234:237], v[94:97]
	v_mfma_f32_16x16x32_bf16 v[90:93], v[190:193], v[234:237], v[90:93]
	v_mfma_f32_16x16x32_bf16 v[78:81], v[152:155], v[242:245], v[78:81]
	v_mfma_f32_16x16x32_bf16 v[74:77], v[190:193], v[242:245], v[74:77]
	s_setprio 0
	s_setprio 1
	v_mfma_f32_16x16x32_bf16 v[118:121], v[194:197], v[210:213], v[118:121]
	v_mfma_f32_16x16x32_bf16 v[114:117], v[202:205], v[210:213], v[114:117]
	v_mfma_f32_16x16x32_bf16 v[102:105], v[194:197], v[218:221], v[102:105]
	v_mfma_f32_16x16x32_bf16 v[98:101], v[202:205], v[218:221], v[98:101]
	v_mfma_f32_16x16x32_bf16 v[86:89], v[194:197], v[226:229], v[86:89]
	v_mfma_f32_16x16x32_bf16 v[82:85], v[202:205], v[226:229], v[82:85]
	v_mfma_f32_16x16x32_bf16 v[70:73], v[194:197], v[238:241], v[70:73]
	v_mfma_f32_16x16x32_bf16 v[66:69], v[202:205], v[238:241], v[66:69]
	v_mfma_f32_16x16x32_bf16 v[118:121], v[198:201], v[214:217], v[118:121]
	v_mfma_f32_16x16x32_bf16 v[114:117], v[206:209], v[214:217], v[114:117]
	v_mfma_f32_16x16x32_bf16 v[102:105], v[198:201], v[222:225], v[102:105]
	v_mfma_f32_16x16x32_bf16 v[98:101], v[206:209], v[222:225], v[98:101]
	v_mfma_f32_16x16x32_bf16 v[86:89], v[198:201], v[234:237], v[86:89]
	v_mfma_f32_16x16x32_bf16 v[82:85], v[206:209], v[234:237], v[82:85]
	v_mfma_f32_16x16x32_bf16 v[70:73], v[198:201], v[242:245], v[70:73]
	v_mfma_f32_16x16x32_bf16 v[66:69], v[206:209], v[242:245], v[66:69]
	s_setprio 0
	s_barrier
	s_add_i32 s62, s66, s78
	s_add_u32 s98, s98, s16
	s_addc_u32 s99, s99, s17
	s_mov_b32 m0, s62
	ds_read_b128 v[210:213], v188 offset:49152
	ds_read_b128 v[214:217], v188 offset:50176
	ds_read_b128 v[218:221], v188 offset:51200
	ds_read_b128 v[222:225], v188 offset:52224
	ds_read_b128 v[226:229], v188 offset:53248
	ds_read_b128 v[234:237], v188 offset:54272
	ds_read_b128 v[238:241], v188 offset:55296
	ds_read_b128 v[242:245], v188 offset:56320
	global_load_lds_dwordx4 v136, s[98:99]
	s_add_i32 m0, s62, 0x2000
	s_add_u32 s60, s60, 0x40080
	s_addc_u32 s61, s61, 0
	s_add_i32 s62, s67, s78
	global_load_lds_dwordx4 v140, s[98:99]
	s_mov_b32 m0, s62
	s_nop 0
	global_load_lds_dwordx4 v136, s[60:61]
	s_add_i32 m0, s62, 0x2000
	s_nop 0
	global_load_lds_dwordx4 v140, s[60:61]
	s_add_u32 s100, s100, s16
	s_addc_u32 s101, s101, s17
	s_mov_b32 m0, s85
	s_nop 0
	global_load_lds_dwordx4 v134, s[100:101]
	s_mov_b32 m0, s86
	s_nop 0
	global_load_lds_dwordx4 v138, s[100:101]
	s_waitcnt vmcnt(8)
	s_waitcnt lgkmcnt(0)
	s_barrier
	s_setprio 1
	s_waitcnt lgkmcnt(0)
	v_mfma_f32_16x16x32_bf16 v[62:65], v[148:151], v[210:213], v[62:65]
	v_mfma_f32_16x16x32_bf16 v[58:61], v[156:159], v[210:213], v[58:61]
	v_mfma_f32_16x16x32_bf16 v[46:49], v[148:151], v[218:221], v[46:49]
	v_mfma_f32_16x16x32_bf16 v[42:45], v[156:159], v[218:221], v[42:45]
	v_mfma_f32_16x16x32_bf16 v[30:33], v[148:151], v[226:229], v[30:33]
	v_mfma_f32_16x16x32_bf16 v[26:29], v[156:159], v[226:229], v[26:29]
	v_mfma_f32_16x16x32_bf16 v[14:17], v[148:151], v[238:241], v[14:17]
	v_mfma_f32_16x16x32_bf16 v[10:13], v[156:159], v[238:241], v[10:13]
	v_mfma_f32_16x16x32_bf16 v[62:65], v[152:155], v[214:217], v[62:65]
	v_mfma_f32_16x16x32_bf16 v[58:61], v[190:193], v[214:217], v[58:61]
	v_mfma_f32_16x16x32_bf16 v[46:49], v[152:155], v[222:225], v[46:49]
	v_mfma_f32_16x16x32_bf16 v[42:45], v[190:193], v[222:225], v[42:45]
	v_mfma_f32_16x16x32_bf16 v[30:33], v[152:155], v[234:237], v[30:33]
	v_mfma_f32_16x16x32_bf16 v[26:29], v[190:193], v[234:237], v[26:29]
	v_mfma_f32_16x16x32_bf16 v[14:17], v[152:155], v[242:245], v[14:17]
	v_mfma_f32_16x16x32_bf16 v[10:13], v[190:193], v[242:245], v[10:13]
	s_setprio 0
	s_setprio 1
	v_mfma_f32_16x16x32_bf16 v[54:57], v[194:197], v[210:213], v[54:57]
	v_mfma_f32_16x16x32_bf16 v[50:53], v[202:205], v[210:213], v[50:53]
	v_mfma_f32_16x16x32_bf16 v[38:41], v[194:197], v[218:221], v[38:41]
	v_mfma_f32_16x16x32_bf16 v[34:37], v[202:205], v[218:221], v[34:37]
	v_mfma_f32_16x16x32_bf16 v[22:25], v[194:197], v[226:229], v[22:25]
	v_mfma_f32_16x16x32_bf16 v[18:21], v[202:205], v[226:229], v[18:21]
	v_mfma_f32_16x16x32_bf16 v[6:9], v[194:197], v[238:241], v[6:9]
	v_mfma_f32_16x16x32_bf16 v[2:5], v[202:205], v[238:241], v[2:5]
	v_mfma_f32_16x16x32_bf16 v[54:57], v[198:201], v[214:217], v[54:57]
	v_mfma_f32_16x16x32_bf16 v[50:53], v[206:209], v[214:217], v[50:53]
	v_mfma_f32_16x16x32_bf16 v[38:41], v[198:201], v[222:225], v[38:41]
	v_mfma_f32_16x16x32_bf16 v[34:37], v[206:209], v[222:225], v[34:37]
	v_mfma_f32_16x16x32_bf16 v[22:25], v[198:201], v[234:237], v[22:25]
	v_mfma_f32_16x16x32_bf16 v[18:21], v[206:209], v[234:237], v[18:21]
	v_mfma_f32_16x16x32_bf16 v[6:9], v[198:201], v[242:245], v[6:9]
	v_mfma_f32_16x16x32_bf16 v[2:5], v[206:209], v[242:245], v[2:5]
	s_setprio 0
	s_barrier
	s_add_i32 s65, s65, 2
	s_add_u32 s48, s48, 0x100
	s_addc_u32 s49, s49, 0
	s_add_u32 s59, s59, 0x100
	s_addc_u32 s64, s64, 0
	s_cmp_gt_u32 s65, 13
	s_cbranch_scc0 .LBB0_1167
	s_and_b64 vcc, exec, s[38:39]
	s_cbranch_vccz .LBB0_1171
	s_barrier
	s_andn2_b64 vcc, exec, s[20:21]
	s_cbranch_vccz .LBB0_1172

.LBB0_1482:
	s_add_u32 s62, s60, 0xfffe0080
	s_addc_u32 s63, s61, -1
	s_cmp_eq_u32 s97, 4
	s_cselect_b32 s65, s43, s63
	s_cselect_b32 s64, s93, s62
	s_cselect_b32 s63, s41, s96
	s_cselect_b32 s62, s94, s95
	s_mov_b32 m0, s57
	s_mov_b64 s[98:99], s[62:63]
	s_add_u32 vcc_lo, s62, 0x20000
	global_load_lds_dwordx4 v200, s[62:63]
	s_mov_b32 m0, s73
	s_addc_u32 vcc_hi, s63, 0
	global_load_lds_dwordx4 v204, s[62:63]
	v_lshl_add_u64 v[216:217], vcc, 0, v[200:201]
	s_mov_b32 m0, s74
	s_mov_b64 s[100:101], s[64:65]
	global_load_lds_dwordx4 v[216:217], off
	v_lshl_add_u64 v[216:217], vcc, 0, v[204:205]
	s_mov_b32 m0, s75
	s_and_b64 vcc, exec, s[6:7]
	global_load_lds_dwordx4 v[216:217], off
	s_mov_b32 m0, s55
	s_nop 0
	global_load_lds_dwordx4 v198, s[64:65]
	s_mov_b32 m0, s76
	s_nop 0
	global_load_lds_dwordx4 v202, s[64:65]
	s_waitcnt vmcnt(8)
	s_waitcnt lgkmcnt(0)
	s_barrier
	s_cbranch_vccnz .LBB0_1484
	s_setprio 1
	s_waitcnt lgkmcnt(0)
	v_mfma_i32_16x16x64_i8 v[96:99], v[180:183], v[4:7], v[96:99]
	v_mfma_i32_16x16x64_i8 v[88:91], v[188:191], v[4:7], v[88:91]
	v_mfma_i32_16x16x64_i8 v[80:83], v[180:183], v[12:15], v[80:83]
	v_mfma_i32_16x16x64_i8 v[72:75], v[188:191], v[12:15], v[72:75]
	v_mfma_i32_16x16x64_i8 v[64:67], v[180:183], v[20:23], v[64:67]
	v_mfma_i32_16x16x64_i8 v[56:59], v[188:191], v[20:23], v[56:59]
	v_mfma_i32_16x16x64_i8 v[48:51], v[180:183], v[28:31], v[48:51]
	v_mfma_i32_16x16x64_i8 v[40:43], v[188:191], v[28:31], v[40:43]
	v_mfma_i32_16x16x64_i8 v[96:99], v[184:187], v[8:11], v[96:99]
	v_mfma_i32_16x16x64_i8 v[88:91], v[192:195], v[8:11], v[88:91]
	v_mfma_i32_16x16x64_i8 v[80:83], v[184:187], v[16:19], v[80:83]
	v_mfma_i32_16x16x64_i8 v[72:75], v[192:195], v[16:19], v[72:75]
	v_mfma_i32_16x16x64_i8 v[64:67], v[184:187], v[24:27], v[64:67]
	v_mfma_i32_16x16x64_i8 v[56:59], v[192:195], v[24:27], v[56:59]
	v_mfma_i32_16x16x64_i8 v[48:51], v[184:187], v[32:35], v[48:51]
	v_mfma_i32_16x16x64_i8 v[40:43], v[192:195], v[32:35], v[40:43]
	s_setprio 0
	s_setprio 1
	v_mfma_i32_16x16x64_i8 v[92:95], v[108:111], v[4:7], v[92:95]
	v_mfma_i32_16x16x64_i8 v[84:87], v[124:127], v[4:7], v[84:87]
	v_mfma_i32_16x16x64_i8 v[76:79], v[108:111], v[12:15], v[76:79]
	v_mfma_i32_16x16x64_i8 v[68:71], v[124:127], v[12:15], v[68:71]
	v_mfma_i32_16x16x64_i8 v[60:63], v[108:111], v[20:23], v[60:63]
	v_mfma_i32_16x16x64_i8 v[52:55], v[124:127], v[20:23], v[52:55]
	v_mfma_i32_16x16x64_i8 v[44:47], v[108:111], v[28:31], v[44:47]
	v_mfma_i32_16x16x64_i8 v[36:39], v[124:127], v[28:31], v[36:39]
	v_mfma_i32_16x16x64_i8 v[92:95], v[112:115], v[8:11], v[92:95]
	v_mfma_i32_16x16x64_i8 v[84:87], v[128:131], v[8:11], v[84:87]
	v_mfma_i32_16x16x64_i8 v[76:79], v[112:115], v[16:19], v[76:79]
	v_mfma_i32_16x16x64_i8 v[68:71], v[128:131], v[16:19], v[68:71]
	v_mfma_i32_16x16x64_i8 v[60:63], v[112:115], v[24:27], v[60:63]
	v_mfma_i32_16x16x64_i8 v[52:55], v[128:131], v[24:27], v[52:55]
	v_mfma_i32_16x16x64_i8 v[44:47], v[112:115], v[32:35], v[44:47]
	v_mfma_i32_16x16x64_i8 v[36:39], v[128:131], v[32:35], v[36:39]
	s_setprio 0

.LBB0_1490:
	s_mov_b32 m0, s80
	s_add_u32 s98, s98, s20
	s_addc_u32 s99, s99, s21
	s_add_u32 s8, s62, 0x20080
	global_load_lds_dwordx4 v200, s[98:99]
	s_mov_b32 m0, s81
	s_addc_u32 s9, s63, 0
	global_load_lds_dwordx4 v204, s[98:99]
	s_mov_b32 m0, s84
	s_and_b64 vcc, exec, s[6:7]
	global_load_lds_dwordx4 v200, s[8:9]
	s_mov_b32 m0, s85
	s_nop 0
	global_load_lds_dwordx4 v204, s[8:9]
	s_add_u32 s100, s100, s20
	s_addc_u32 s101, s101, s21
	s_mov_b32 m0, s82
	s_nop 0
	global_load_lds_dwordx4 v198, s[100:101]
	s_mov_b32 m0, s83
	s_nop 0
	global_load_lds_dwordx4 v202, s[100:101]
	s_waitcnt vmcnt(8)
	s_waitcnt lgkmcnt(0)
	s_barrier
	s_cbranch_vccnz .LBB0_1475
	s_setprio 1
	s_waitcnt lgkmcnt(0)
	v_mfma_i32_16x16x64_i8 v[96:99], v[180:183], v[4:7], v[96:99]
	v_mfma_i32_16x16x64_i8 v[88:91], v[188:191], v[4:7], v[88:91]
	v_mfma_i32_16x16x64_i8 v[80:83], v[180:183], v[12:15], v[80:83]
	v_mfma_i32_16x16x64_i8 v[72:75], v[188:191], v[12:15], v[72:75]
	v_mfma_i32_16x16x64_i8 v[64:67], v[180:183], v[20:23], v[64:67]
	v_mfma_i32_16x16x64_i8 v[56:59], v[188:191], v[20:23], v[56:59]
	v_mfma_i32_16x16x64_i8 v[48:51], v[180:183], v[28:31], v[48:51]
	v_mfma_i32_16x16x64_i8 v[40:43], v[188:191], v[28:31], v[40:43]
	v_mfma_i32_16x16x64_i8 v[96:99], v[184:187], v[8:11], v[96:99]
	v_mfma_i32_16x16x64_i8 v[88:91], v[192:195], v[8:11], v[88:91]
	v_mfma_i32_16x16x64_i8 v[80:83], v[184:187], v[16:19], v[80:83]
	v_mfma_i32_16x16x64_i8 v[72:75], v[192:195], v[16:19], v[72:75]
	v_mfma_i32_16x16x64_i8 v[64:67], v[184:187], v[24:27], v[64:67]
	v_mfma_i32_16x16x64_i8 v[56:59], v[192:195], v[24:27], v[56:59]
	v_mfma_i32_16x16x64_i8 v[48:51], v[184:187], v[32:35], v[48:51]
	v_mfma_i32_16x16x64_i8 v[40:43], v[192:195], v[32:35], v[40:43]
	s_setprio 0
	s_setprio 1
	v_mfma_i32_16x16x64_i8 v[92:95], v[108:111], v[4:7], v[92:95]
	v_mfma_i32_16x16x64_i8 v[84:87], v[124:127], v[4:7], v[84:87]
	v_mfma_i32_16x16x64_i8 v[76:79], v[108:111], v[12:15], v[76:79]
	v_mfma_i32_16x16x64_i8 v[68:71], v[124:127], v[12:15], v[68:71]
	v_mfma_i32_16x16x64_i8 v[60:63], v[108:111], v[20:23], v[60:63]
	v_mfma_i32_16x16x64_i8 v[52:55], v[124:127], v[20:23], v[52:55]
	v_mfma_i32_16x16x64_i8 v[44:47], v[108:111], v[28:31], v[44:47]
	v_mfma_i32_16x16x64_i8 v[36:39], v[124:127], v[28:31], v[36:39]
	v_mfma_i32_16x16x64_i8 v[92:95], v[112:115], v[8:11], v[92:95]
	v_mfma_i32_16x16x64_i8 v[84:87], v[128:131], v[8:11], v[84:87]
	v_mfma_i32_16x16x64_i8 v[76:79], v[112:115], v[16:19], v[76:79]
	v_mfma_i32_16x16x64_i8 v[68:71], v[128:131], v[16:19], v[68:71]
	v_mfma_i32_16x16x64_i8 v[60:63], v[112:115], v[24:27], v[60:63]
	v_mfma_i32_16x16x64_i8 v[52:55], v[128:131], v[24:27], v[52:55]
	v_mfma_i32_16x16x64_i8 v[44:47], v[112:115], v[32:35], v[44:47]
	v_mfma_i32_16x16x64_i8 v[36:39], v[128:131], v[32:35], v[36:39]
	s_setprio 0
	s_branch .LBB0_1475

.LBB0_1636:
	s_add_u32 s56, s48, 0x100
	s_addc_u32 s57, s49, 0
	s_add_i32 s64, 0, 0x10000
	s_cmp_eq_u32 s63, 40
	s_cselect_b32 s61, s13, s57
	s_cselect_b32 s60, s12, s56
	v_add_u32_e32 v0, s64, v169
	s_cselect_b32 s59, s53, s55
	s_cselect_b32 s58, s52, s16
	s_add_i32 s65, 0, 0x14000
	ds_read_b128 v[148:151], v0
	ds_read_b128 v[152:155], v0 offset:1024
	ds_read_b128 v[156:159], v0 offset:2048
	ds_read_b128 v[190:193], v0 offset:3072
	v_add_u32_e32 v0, s65, v169
	ds_read_b128 v[194:197], v0
	ds_read_b128 v[198:201], v0 offset:1024
	ds_read_b128 v[202:205], v0 offset:2048
	ds_read_b128 v[206:209], v0 offset:3072
	v_lshl_add_u64 v[230:231], s[48:49], 0, v[144:145]
	s_add_i32 m0, s79, 0xc000
	ds_read_b128 v[210:213], v188
	ds_read_b128 v[214:217], v188 offset:1024
	ds_read_b128 v[218:221], v188 offset:2048
	ds_read_b128 v[222:225], v188 offset:3072
	ds_read_b128 v[226:229], v188 offset:4096
	ds_read_b128 v[234:237], v188 offset:5120
	ds_read_b128 v[238:241], v188 offset:6144
	ds_read_b128 v[242:245], v188 offset:7168
	global_load_lds_dwordx4 v[230:231], off
	v_lshl_add_u64 v[230:231], s[48:49], 0, v[146:147]
	s_add_i32 m0, s79, 0xe000
	s_nop 0
	global_load_lds_dwordx4 v[230:231], off
	s_waitcnt vmcnt(8)
	s_waitcnt lgkmcnt(0)
	s_barrier
	s_setprio 1
	s_waitcnt lgkmcnt(0)
	v_mfma_f32_16x16x32_bf16 v[126:129], v[148:151], v[210:213], v[126:129]
	v_mfma_f32_16x16x32_bf16 v[122:125], v[156:159], v[210:213], v[122:125]
	v_mfma_f32_16x16x32_bf16 v[110:113], v[148:151], v[218:221], v[110:113]
	v_mfma_f32_16x16x32_bf16 v[106:109], v[156:159], v[218:221], v[106:109]
	v_mfma_f32_16x16x32_bf16 v[94:97], v[148:151], v[226:229], v[94:97]
	v_mfma_f32_16x16x32_bf16 v[90:93], v[156:159], v[226:229], v[90:93]
	v_mfma_f32_16x16x32_bf16 v[78:81], v[148:151], v[238:241], v[78:81]
	v_mfma_f32_16x16x32_bf16 v[74:77], v[156:159], v[238:241], v[74:77]
	v_mfma_f32_16x16x32_bf16 v[126:129], v[152:155], v[214:217], v[126:129]
	v_mfma_f32_16x16x32_bf16 v[122:125], v[190:193], v[214:217], v[122:125]
	v_mfma_f32_16x16x32_bf16 v[110:113], v[152:155], v[222:225], v[110:113]
	v_mfma_f32_16x16x32_bf16 v[106:109], v[190:193], v[222:225], v[106:109]
	v_mfma_f32_16x16x32_bf16 v[94:97], v[152:155], v[234:237], v[94:97]
	v_mfma_f32_16x16x32_bf16 v[90:93], v[190:193], v[234:237], v[90:93]
	v_mfma_f32_16x16x32_bf16 v[78:81], v[152:155], v[242:245], v[78:81]
	v_mfma_f32_16x16x32_bf16 v[74:77], v[190:193], v[242:245], v[74:77]
	s_setprio 0
	s_setprio 1
	v_mfma_f32_16x16x32_bf16 v[118:121], v[194:197], v[210:213], v[118:121]
	v_mfma_f32_16x16x32_bf16 v[114:117], v[202:205], v[210:213], v[114:117]
	v_mfma_f32_16x16x32_bf16 v[102:105], v[194:197], v[218:221], v[102:105]
	v_mfma_f32_16x16x32_bf16 v[98:101], v[202:205], v[218:221], v[98:101]
	v_mfma_f32_16x16x32_bf16 v[86:89], v[194:197], v[226:229], v[86:89]
	v_mfma_f32_16x16x32_bf16 v[82:85], v[202:205], v[226:229], v[82:85]
	v_mfma_f32_16x16x32_bf16 v[70:73], v[194:197], v[238:241], v[70:73]
	v_mfma_f32_16x16x32_bf16 v[66:69], v[202:205], v[238:241], v[66:69]
	v_mfma_f32_16x16x32_bf16 v[118:121], v[198:201], v[214:217], v[118:121]
	v_mfma_f32_16x16x32_bf16 v[114:117], v[206:209], v[214:217], v[114:117]
	v_mfma_f32_16x16x32_bf16 v[102:105], v[198:201], v[222:225], v[102:105]
	v_mfma_f32_16x16x32_bf16 v[98:101], v[206:209], v[222:225], v[98:101]
	v_mfma_f32_16x16x32_bf16 v[86:89], v[198:201], v[234:237], v[86:89]
	v_mfma_f32_16x16x32_bf16 v[82:85], v[206:209], v[234:237], v[82:85]
	v_mfma_f32_16x16x32_bf16 v[70:73], v[198:201], v[242:245], v[70:73]
	v_mfma_f32_16x16x32_bf16 v[66:69], v[206:209], v[242:245], v[66:69]
	s_setprio 0
	s_barrier
	s_add_i32 s48, s64, s78
	s_mov_b64 s[98:99], s[58:59]
	s_mov_b32 m0, s48
	ds_read_b128 v[210:213], v188 offset:16384
	ds_read_b128 v[214:217], v188 offset:17408
	ds_read_b128 v[218:221], v188 offset:18432
	ds_read_b128 v[222:225], v188 offset:19456
	ds_read_b128 v[226:229], v188 offset:20480
	ds_read_b128 v[234:237], v188 offset:21504
	ds_read_b128 v[238:241], v188 offset:22528
	ds_read_b128 v[242:245], v188 offset:23552
	global_load_lds_dwordx4 v136, s[58:59]
	s_add_i32 m0, s48, 0x2000
	s_add_u32 s48, s58, 0xb0000
	s_addc_u32 s49, s59, 0
	s_add_i32 s64, s65, s78
	global_load_lds_dwordx4 v140, s[58:59]
	s_mov_b32 m0, s64
	s_mov_b64 s[100:101], s[60:61]
	global_load_lds_dwordx4 v136, s[48:49]
	s_add_i32 m0, s64, 0x2000
	s_nop 0
	global_load_lds_dwordx4 v140, s[48:49]
	s_mov_b32 m0, s79
	s_nop 0
	global_load_lds_dwordx4 v134, s[60:61]
	s_mov_b32 m0, s80
	s_nop 0
	global_load_lds_dwordx4 v138, s[60:61]
	s_waitcnt vmcnt(8)
	s_waitcnt lgkmcnt(0)
	s_barrier
	s_setprio 1
	s_waitcnt lgkmcnt(0)
	v_mfma_f32_16x16x32_bf16 v[62:65], v[148:151], v[210:213], v[62:65]
	v_mfma_f32_16x16x32_bf16 v[58:61], v[156:159], v[210:213], v[58:61]
	v_mfma_f32_16x16x32_bf16 v[46:49], v[148:151], v[218:221], v[46:49]
	v_mfma_f32_16x16x32_bf16 v[42:45], v[156:159], v[218:221], v[42:45]
	v_mfma_f32_16x16x32_bf16 v[30:33], v[148:151], v[226:229], v[30:33]
	v_mfma_f32_16x16x32_bf16 v[26:29], v[156:159], v[226:229], v[26:29]
	v_mfma_f32_16x16x32_bf16 v[14:17], v[148:151], v[238:241], v[14:17]
	v_mfma_f32_16x16x32_bf16 v[10:13], v[156:159], v[238:241], v[10:13]
	v_mfma_f32_16x16x32_bf16 v[62:65], v[152:155], v[214:217], v[62:65]
	v_mfma_f32_16x16x32_bf16 v[58:61], v[190:193], v[214:217], v[58:61]
	v_mfma_f32_16x16x32_bf16 v[46:49], v[152:155], v[222:225], v[46:49]
	v_mfma_f32_16x16x32_bf16 v[42:45], v[190:193], v[222:225], v[42:45]
	v_mfma_f32_16x16x32_bf16 v[30:33], v[152:155], v[234:237], v[30:33]
	v_mfma_f32_16x16x32_bf16 v[26:29], v[190:193], v[234:237], v[26:29]
	v_mfma_f32_16x16x32_bf16 v[14:17], v[152:155], v[242:245], v[14:17]
	v_mfma_f32_16x16x32_bf16 v[10:13], v[190:193], v[242:245], v[10:13]
	s_setprio 0
	s_setprio 1
	v_mfma_f32_16x16x32_bf16 v[54:57], v[194:197], v[210:213], v[54:57]
	v_mfma_f32_16x16x32_bf16 v[50:53], v[202:205], v[210:213], v[50:53]
	v_mfma_f32_16x16x32_bf16 v[38:41], v[194:197], v[218:221], v[38:41]
	v_mfma_f32_16x16x32_bf16 v[34:37], v[202:205], v[218:221], v[34:37]
	v_mfma_f32_16x16x32_bf16 v[22:25], v[194:197], v[226:229], v[22:25]
	v_mfma_f32_16x16x32_bf16 v[18:21], v[202:205], v[226:229], v[18:21]
	v_mfma_f32_16x16x32_bf16 v[6:9], v[194:197], v[238:241], v[6:9]
	v_mfma_f32_16x16x32_bf16 v[2:5], v[202:205], v[238:241], v[2:5]
	v_mfma_f32_16x16x32_bf16 v[54:57], v[198:201], v[214:217], v[54:57]
	v_mfma_f32_16x16x32_bf16 v[50:53], v[206:209], v[214:217], v[50:53]
	v_mfma_f32_16x16x32_bf16 v[38:41], v[198:201], v[222:225], v[38:41]
	v_mfma_f32_16x16x32_bf16 v[34:37], v[206:209], v[222:225], v[34:37]
	v_mfma_f32_16x16x32_bf16 v[22:25], v[198:201], v[234:237], v[22:25]
	v_mfma_f32_16x16x32_bf16 v[18:21], v[206:209], v[234:237], v[18:21]
	v_mfma_f32_16x16x32_bf16 v[6:9], v[198:201], v[242:245], v[6:9]
	v_mfma_f32_16x16x32_bf16 v[2:5], v[206:209], v[242:245], v[2:5]
	s_setprio 0
	s_barrier
	s_add_i32 s64, 0, 0x18000
	v_add_u32_e32 v0, s64, v169
	s_add_i32 s65, 0, 0x1c000
	ds_read_b128 v[148:151], v0
	ds_read_b128 v[152:155], v0 offset:1024
	ds_read_b128 v[156:159], v0 offset:2048
	ds_read_b128 v[190:193], v0 offset:3072
	v_add_u32_e32 v0, s65, v169
	ds_read_b128 v[194:197], v0
	ds_read_b128 v[198:201], v0 offset:1024
	ds_read_b128 v[202:205], v0 offset:2048
	ds_read_b128 v[206:209], v0 offset:3072
	s_add_u32 s48, s60, 0xb0000
	s_addc_u32 s49, s61, 0
	s_mov_b32 m0, s81
	ds_read_b128 v[210:213], v188 offset:32768
	ds_read_b128 v[214:217], v188 offset:33792
	ds_read_b128 v[218:221], v188 offset:34816
	ds_read_b128 v[222:225], v188 offset:35840
	ds_read_b128 v[226:229], v188 offset:36864
	ds_read_b128 v[234:237], v188 offset:37888
	ds_read_b128 v[238:241], v188 offset:38912
	ds_read_b128 v[242:245], v188 offset:39936
	global_load_lds_dwordx4 v134, s[48:49]
	s_mov_b32 m0, s82
	s_nop 0
	global_load_lds_dwordx4 v138, s[48:49]
	s_waitcnt vmcnt(8)
	s_waitcnt lgkmcnt(0)
	s_barrier
	s_setprio 1
	s_waitcnt lgkmcnt(0)
	v_mfma_f32_16x16x32_bf16 v[126:129], v[148:151], v[210:213], v[126:129]
	v_mfma_f32_16x16x32_bf16 v[122:125], v[156:159], v[210:213], v[122:125]
	v_mfma_f32_16x16x32_bf16 v[110:113], v[148:151], v[218:221], v[110:113]
	v_mfma_f32_16x16x32_bf16 v[106:109], v[156:159], v[218:221], v[106:109]
	v_mfma_f32_16x16x32_bf16 v[94:97], v[148:151], v[226:229], v[94:97]
	v_mfma_f32_16x16x32_bf16 v[90:93], v[156:159], v[226:229], v[90:93]
	v_mfma_f32_16x16x32_bf16 v[78:81], v[148:151], v[238:241], v[78:81]
	v_mfma_f32_16x16x32_bf16 v[74:77], v[156:159], v[238:241], v[74:77]
	v_mfma_f32_16x16x32_bf16 v[126:129], v[152:155], v[214:217], v[126:129]
	v_mfma_f32_16x16x32_bf16 v[122:125], v[190:193], v[214:217], v[122:125]
	v_mfma_f32_16x16x32_bf16 v[110:113], v[152:155], v[222:225], v[110:113]
	v_mfma_f32_16x16x32_bf16 v[106:109], v[190:193], v[222:225], v[106:109]
	v_mfma_f32_16x16x32_bf16 v[94:97], v[152:155], v[234:237], v[94:97]
	v_mfma_f32_16x16x32_bf16 v[90:93], v[190:193], v[234:237], v[90:93]
	v_mfma_f32_16x16x32_bf16 v[78:81], v[152:155], v[242:245], v[78:81]
	v_mfma_f32_16x16x32_bf16 v[74:77], v[190:193], v[242:245], v[74:77]
	s_setprio 0
	s_setprio 1
	v_mfma_f32_16x16x32_bf16 v[118:121], v[194:197], v[210:213], v[118:121]
	v_mfma_f32_16x16x32_bf16 v[114:117], v[202:205], v[210:213], v[114:117]
	v_mfma_f32_16x16x32_bf16 v[102:105], v[194:197], v[218:221], v[102:105]
	v_mfma_f32_16x16x32_bf16 v[98:101], v[202:205], v[218:221], v[98:101]
	v_mfma_f32_16x16x32_bf16 v[86:89], v[194:197], v[226:229], v[86:89]
	v_mfma_f32_16x16x32_bf16 v[82:85], v[202:205], v[226:229], v[82:85]
	v_mfma_f32_16x16x32_bf16 v[70:73], v[194:197], v[238:241], v[70:73]
	v_mfma_f32_16x16x32_bf16 v[66:69], v[202:205], v[238:241], v[66:69]
	v_mfma_f32_16x16x32_bf16 v[118:121], v[198:201], v[214:217], v[118:121]
	v_mfma_f32_16x16x32_bf16 v[114:117], v[206:209], v[214:217], v[114:117]
	v_mfma_f32_16x16x32_bf16 v[102:105], v[198:201], v[222:225], v[102:105]
	v_mfma_f32_16x16x32_bf16 v[98:101], v[206:209], v[222:225], v[98:101]
	v_mfma_f32_16x16x32_bf16 v[86:89], v[198:201], v[234:237], v[86:89]
	v_mfma_f32_16x16x32_bf16 v[82:85], v[206:209], v[234:237], v[82:85]
	v_mfma_f32_16x16x32_bf16 v[70:73], v[198:201], v[242:245], v[70:73]
	v_mfma_f32_16x16x32_bf16 v[66:69], v[206:209], v[242:245], v[66:69]
	s_setprio 0
	s_barrier
	s_add_i32 s48, s64, s78
	s_add_u32 s98, s98, s18
	s_addc_u32 s99, s99, s19
	s_mov_b32 m0, s48
	ds_read_b128 v[210:213], v188 offset:49152
	ds_read_b128 v[214:217], v188 offset:50176
	ds_read_b128 v[218:221], v188 offset:51200
	ds_read_b128 v[222:225], v188 offset:52224
	ds_read_b128 v[226:229], v188 offset:53248
	ds_read_b128 v[234:237], v188 offset:54272
	ds_read_b128 v[238:241], v188 offset:55296
	ds_read_b128 v[242:245], v188 offset:56320
	global_load_lds_dwordx4 v136, s[98:99]
	s_add_i32 m0, s48, 0x2000
	s_add_u32 s48, s58, 0xb0080
	s_addc_u32 s49, s59, 0
	s_add_i32 s58, s65, s78
	global_load_lds_dwordx4 v140, s[98:99]
	s_mov_b32 m0, s58
	s_nop 0
	global_load_lds_dwordx4 v136, s[48:49]
	s_add_i32 m0, s58, 0x2000
	s_nop 0
	global_load_lds_dwordx4 v140, s[48:49]
	s_add_u32 s100, s100, s18
	s_addc_u32 s101, s101, s19
	s_mov_b32 m0, s85
	s_nop 0
	global_load_lds_dwordx4 v134, s[100:101]
	s_mov_b32 m0, s86
	s_nop 0
	global_load_lds_dwordx4 v138, s[100:101]
	s_waitcnt vmcnt(8)
	s_waitcnt lgkmcnt(0)
	s_barrier
	s_setprio 1
	s_waitcnt lgkmcnt(0)
	v_mfma_f32_16x16x32_bf16 v[62:65], v[148:151], v[210:213], v[62:65]
	v_mfma_f32_16x16x32_bf16 v[58:61], v[156:159], v[210:213], v[58:61]
	v_mfma_f32_16x16x32_bf16 v[46:49], v[148:151], v[218:221], v[46:49]
	v_mfma_f32_16x16x32_bf16 v[42:45], v[156:159], v[218:221], v[42:45]
	v_mfma_f32_16x16x32_bf16 v[30:33], v[148:151], v[226:229], v[30:33]
	v_mfma_f32_16x16x32_bf16 v[26:29], v[156:159], v[226:229], v[26:29]
	v_mfma_f32_16x16x32_bf16 v[14:17], v[148:151], v[238:241], v[14:17]
	v_mfma_f32_16x16x32_bf16 v[10:13], v[156:159], v[238:241], v[10:13]
	v_mfma_f32_16x16x32_bf16 v[62:65], v[152:155], v[214:217], v[62:65]
	v_mfma_f32_16x16x32_bf16 v[58:61], v[190:193], v[214:217], v[58:61]
	v_mfma_f32_16x16x32_bf16 v[46:49], v[152:155], v[222:225], v[46:49]
	v_mfma_f32_16x16x32_bf16 v[42:45], v[190:193], v[222:225], v[42:45]
	v_mfma_f32_16x16x32_bf16 v[30:33], v[152:155], v[234:237], v[30:33]
	v_mfma_f32_16x16x32_bf16 v[26:29], v[190:193], v[234:237], v[26:29]
	v_mfma_f32_16x16x32_bf16 v[14:17], v[152:155], v[242:245], v[14:17]
	v_mfma_f32_16x16x32_bf16 v[10:13], v[190:193], v[242:245], v[10:13]
	s_setprio 0
	s_setprio 1
	v_mfma_f32_16x16x32_bf16 v[54:57], v[194:197], v[210:213], v[54:57]
	v_mfma_f32_16x16x32_bf16 v[50:53], v[202:205], v[210:213], v[50:53]
	v_mfma_f32_16x16x32_bf16 v[38:41], v[194:197], v[218:221], v[38:41]
	v_mfma_f32_16x16x32_bf16 v[34:37], v[202:205], v[218:221], v[34:37]
	v_mfma_f32_16x16x32_bf16 v[22:25], v[194:197], v[226:229], v[22:25]
	v_mfma_f32_16x16x32_bf16 v[18:21], v[202:205], v[226:229], v[18:21]
	v_mfma_f32_16x16x32_bf16 v[6:9], v[194:197], v[238:241], v[6:9]
	v_mfma_f32_16x16x32_bf16 v[2:5], v[202:205], v[238:241], v[2:5]
	v_mfma_f32_16x16x32_bf16 v[54:57], v[198:201], v[214:217], v[54:57]
	v_mfma_f32_16x16x32_bf16 v[50:53], v[206:209], v[214:217], v[50:53]
	v_mfma_f32_16x16x32_bf16 v[38:41], v[198:201], v[222:225], v[38:41]
	v_mfma_f32_16x16x32_bf16 v[34:37], v[206:209], v[222:225], v[34:37]
	v_mfma_f32_16x16x32_bf16 v[22:25], v[198:201], v[234:237], v[22:25]
	v_mfma_f32_16x16x32_bf16 v[18:21], v[206:209], v[234:237], v[18:21]
	v_mfma_f32_16x16x32_bf16 v[6:9], v[198:201], v[242:245], v[6:9]
	v_mfma_f32_16x16x32_bf16 v[2:5], v[206:209], v[242:245], v[2:5]
	s_setprio 0
	s_barrier
	s_add_i32 s63, s63, 2
	s_add_u32 s16, s16, 0x100
	s_addc_u32 s55, s55, 0
	s_cmp_gt_u32 s63, 41
	s_mov_b64 s[48:49], s[56:57]
	s_cbranch_scc0 .LBB0_1636
	s_and_b64 vcc, exec, s[42:43]
	s_cbranch_vccz .LBB0_1640
	s_barrier
	s_andn2_b64 vcc, exec, s[24:25]
	s_cbranch_vccz .LBB0_1641

.LBB0_2108:
	s_add_u32 s48, s8, 0xfffc0080
	s_addc_u32 s49, s9, -1
	s_add_i32 s85, 0, 0x10000
	s_cmp_eq_u32 s71, 12
	s_cselect_b32 s65, s7, s49
	s_cselect_b32 s64, s57, s48
	v_add_u32_e32 v128, s85, v173
	s_cselect_b32 s49, s59, s70
	s_cselect_b32 s48, s68, s69
	s_add_i32 s87, 0, 0x14000
	ds_read_b128 v[174:177], v128
	ds_read_b128 v[180:183], v128 offset:1024
	ds_read_b128 v[184:187], v128 offset:2048
	ds_read_b128 v[188:191], v128 offset:3072
	v_add_u32_e32 v128, s87, v173
	ds_read_b128 v[192:195], v128
	ds_read_b128 v[196:199], v128 offset:1024
	ds_read_b128 v[202:205], v128 offset:2048
	ds_read_b128 v[206:209], v128 offset:3072
	s_add_i32 m0, s67, 0xc000
	ds_read_b128 v[216:219], v200
	ds_read_b128 v[220:223], v200 offset:1024
	ds_read_b128 v[224:227], v200 offset:2048
	ds_read_b128 v[228:231], v200 offset:3072
	ds_read_b128 v[234:237], v200 offset:4096
	ds_read_b128 v[238:241], v200 offset:5120
	ds_read_b128 v[242:245], v200 offset:6144
	ds_read_b128 v[246:249], v200 offset:7168
	global_load_lds_dwordx4 v148, s[8:9]
	s_add_i32 m0, s67, 0xe000
	s_nop 0
	global_load_lds_dwordx4 v150, s[8:9]
	s_waitcnt vmcnt(8)
	s_waitcnt lgkmcnt(0)
	s_barrier
	s_setprio 1
	s_waitcnt lgkmcnt(0)
	v_mfma_f32_16x16x32_bf16 v[124:127], v[174:177], v[216:219], v[124:127]
	v_mfma_f32_16x16x32_bf16 v[120:123], v[184:187], v[216:219], v[120:123]
	v_mfma_f32_16x16x32_bf16 v[108:111], v[174:177], v[224:227], v[108:111]
	v_mfma_f32_16x16x32_bf16 v[104:107], v[184:187], v[224:227], v[104:107]
	v_mfma_f32_16x16x32_bf16 v[92:95], v[174:177], v[234:237], v[92:95]
	v_mfma_f32_16x16x32_bf16 v[88:91], v[184:187], v[234:237], v[88:91]
	v_mfma_f32_16x16x32_bf16 v[76:79], v[174:177], v[242:245], v[76:79]
	v_mfma_f32_16x16x32_bf16 v[72:75], v[184:187], v[242:245], v[72:75]
	v_mfma_f32_16x16x32_bf16 v[124:127], v[180:183], v[220:223], v[124:127]
	v_mfma_f32_16x16x32_bf16 v[120:123], v[188:191], v[220:223], v[120:123]
	v_mfma_f32_16x16x32_bf16 v[108:111], v[180:183], v[228:231], v[108:111]
	v_mfma_f32_16x16x32_bf16 v[104:107], v[188:191], v[228:231], v[104:107]
	v_mfma_f32_16x16x32_bf16 v[92:95], v[180:183], v[238:241], v[92:95]
	v_mfma_f32_16x16x32_bf16 v[88:91], v[188:191], v[238:241], v[88:91]
	v_mfma_f32_16x16x32_bf16 v[76:79], v[180:183], v[246:249], v[76:79]
	v_mfma_f32_16x16x32_bf16 v[72:75], v[188:191], v[246:249], v[72:75]
	s_setprio 0
	s_setprio 1
	v_mfma_f32_16x16x32_bf16 v[116:119], v[192:195], v[216:219], v[116:119]
	v_mfma_f32_16x16x32_bf16 v[112:115], v[202:205], v[216:219], v[112:115]
	v_mfma_f32_16x16x32_bf16 v[100:103], v[192:195], v[224:227], v[100:103]
	v_mfma_f32_16x16x32_bf16 v[96:99], v[202:205], v[224:227], v[96:99]
	v_mfma_f32_16x16x32_bf16 v[84:87], v[192:195], v[234:237], v[84:87]
	v_mfma_f32_16x16x32_bf16 v[80:83], v[202:205], v[234:237], v[80:83]
	v_mfma_f32_16x16x32_bf16 v[68:71], v[192:195], v[242:245], v[68:71]
	v_mfma_f32_16x16x32_bf16 v[64:67], v[202:205], v[242:245], v[64:67]
	v_mfma_f32_16x16x32_bf16 v[116:119], v[196:199], v[220:223], v[116:119]
	v_mfma_f32_16x16x32_bf16 v[112:115], v[206:209], v[220:223], v[112:115]
	v_mfma_f32_16x16x32_bf16 v[100:103], v[196:199], v[228:231], v[100:103]
	v_mfma_f32_16x16x32_bf16 v[96:99], v[206:209], v[228:231], v[96:99]
	v_mfma_f32_16x16x32_bf16 v[84:87], v[196:199], v[238:241], v[84:87]
	v_mfma_f32_16x16x32_bf16 v[80:83], v[206:209], v[238:241], v[80:83]
	v_mfma_f32_16x16x32_bf16 v[68:71], v[196:199], v[246:249], v[68:71]
	v_mfma_f32_16x16x32_bf16 v[64:67], v[206:209], v[246:249], v[64:67]
	s_setprio 0
	s_barrier
	s_add_i32 s85, s85, s77
	s_mov_b64 s[98:99], s[48:49]
	s_mov_b32 m0, s85
	ds_read_b128 v[216:219], v200 offset:16384
	ds_read_b128 v[220:223], v200 offset:17408
	ds_read_b128 v[224:227], v200 offset:18432
	ds_read_b128 v[228:231], v200 offset:19456
	ds_read_b128 v[234:237], v200 offset:20480
	ds_read_b128 v[238:241], v200 offset:21504
	ds_read_b128 v[242:245], v200 offset:22528
	ds_read_b128 v[246:249], v200 offset:23552
	global_load_lds_dwordx4 v136, s[48:49]
	s_add_i32 m0, s85, 0x2000
	s_add_u32 s88, s48, 0x40000
	s_addc_u32 s89, s49, 0
	s_add_i32 s85, s87, s77
	global_load_lds_dwordx4 v140, s[48:49]
	s_mov_b32 m0, s85
	s_mov_b64 s[100:101], s[64:65]
	global_load_lds_dwordx4 v136, s[88:89]
	s_add_i32 m0, s85, 0x2000
	s_nop 0
	global_load_lds_dwordx4 v140, s[88:89]
	s_mov_b32 m0, s67
	s_nop 0
	global_load_lds_dwordx4 v134, s[64:65]
	s_mov_b32 m0, s78
	s_nop 0
	global_load_lds_dwordx4 v138, s[64:65]
	s_waitcnt vmcnt(8)
	s_waitcnt lgkmcnt(0)
	s_barrier
	s_setprio 1
	s_waitcnt lgkmcnt(0)
	v_mfma_f32_16x16x32_bf16 v[60:63], v[174:177], v[216:219], v[60:63]
	v_mfma_f32_16x16x32_bf16 v[56:59], v[184:187], v[216:219], v[56:59]
	v_mfma_f32_16x16x32_bf16 v[44:47], v[174:177], v[224:227], v[44:47]
	v_mfma_f32_16x16x32_bf16 v[40:43], v[184:187], v[224:227], v[40:43]
	v_mfma_f32_16x16x32_bf16 v[28:31], v[174:177], v[234:237], v[28:31]
	v_mfma_f32_16x16x32_bf16 v[24:27], v[184:187], v[234:237], v[24:27]
	v_mfma_f32_16x16x32_bf16 v[12:15], v[174:177], v[242:245], v[12:15]
	v_mfma_f32_16x16x32_bf16 v[8:11], v[184:187], v[242:245], v[8:11]
	v_mfma_f32_16x16x32_bf16 v[60:63], v[180:183], v[220:223], v[60:63]
	v_mfma_f32_16x16x32_bf16 v[56:59], v[188:191], v[220:223], v[56:59]
	v_mfma_f32_16x16x32_bf16 v[44:47], v[180:183], v[228:231], v[44:47]
	v_mfma_f32_16x16x32_bf16 v[40:43], v[188:191], v[228:231], v[40:43]
	v_mfma_f32_16x16x32_bf16 v[28:31], v[180:183], v[238:241], v[28:31]
	v_mfma_f32_16x16x32_bf16 v[24:27], v[188:191], v[238:241], v[24:27]
	v_mfma_f32_16x16x32_bf16 v[12:15], v[180:183], v[246:249], v[12:15]
	v_mfma_f32_16x16x32_bf16 v[8:11], v[188:191], v[246:249], v[8:11]
	s_setprio 0
	s_setprio 1
	v_mfma_f32_16x16x32_bf16 v[52:55], v[192:195], v[216:219], v[52:55]
	v_mfma_f32_16x16x32_bf16 v[48:51], v[202:205], v[216:219], v[48:51]
	v_mfma_f32_16x16x32_bf16 v[36:39], v[192:195], v[224:227], v[36:39]
	v_mfma_f32_16x16x32_bf16 v[32:35], v[202:205], v[224:227], v[32:35]
	v_mfma_f32_16x16x32_bf16 v[20:23], v[192:195], v[234:237], v[20:23]
	v_mfma_f32_16x16x32_bf16 v[16:19], v[202:205], v[234:237], v[16:19]
	v_mfma_f32_16x16x32_bf16 v[4:7], v[192:195], v[242:245], v[4:7]
	v_mfma_f32_16x16x32_bf16 v[0:3], v[202:205], v[242:245], v[0:3]
	v_mfma_f32_16x16x32_bf16 v[52:55], v[196:199], v[220:223], v[52:55]
	v_mfma_f32_16x16x32_bf16 v[48:51], v[206:209], v[220:223], v[48:51]
	v_mfma_f32_16x16x32_bf16 v[36:39], v[196:199], v[228:231], v[36:39]
	v_mfma_f32_16x16x32_bf16 v[32:35], v[206:209], v[228:231], v[32:35]
	v_mfma_f32_16x16x32_bf16 v[20:23], v[196:199], v[238:241], v[20:23]
	v_mfma_f32_16x16x32_bf16 v[16:19], v[206:209], v[238:241], v[16:19]
	v_mfma_f32_16x16x32_bf16 v[4:7], v[196:199], v[246:249], v[4:7]
	v_mfma_f32_16x16x32_bf16 v[0:3], v[206:209], v[246:249], v[0:3]
	s_setprio 0
	s_barrier
	v_add_u32_e32 v128, s0, v173
	s_add_i32 s85, 0, 0x1c000
	ds_read_b128 v[174:177], v128
	ds_read_b128 v[180:183], v128 offset:1024
	ds_read_b128 v[184:187], v128 offset:2048
	ds_read_b128 v[188:191], v128 offset:3072
	v_add_u32_e32 v128, s85, v173
	ds_read_b128 v[192:195], v128
	ds_read_b128 v[196:199], v128 offset:1024
	ds_read_b128 v[202:205], v128 offset:2048
	ds_read_b128 v[206:209], v128 offset:3072
	s_add_u32 s64, s64, 0x40000
	s_addc_u32 s65, s65, 0
	s_mov_b32 m0, s79
	ds_read_b128 v[216:219], v200 offset:32768
	ds_read_b128 v[220:223], v200 offset:33792
	ds_read_b128 v[224:227], v200 offset:34816
	ds_read_b128 v[228:231], v200 offset:35840
	ds_read_b128 v[234:237], v200 offset:36864
	ds_read_b128 v[238:241], v200 offset:37888
	ds_read_b128 v[242:245], v200 offset:38912
	ds_read_b128 v[246:249], v200 offset:39936
	global_load_lds_dwordx4 v134, s[64:65]
	s_mov_b32 m0, s80
	s_nop 0
	global_load_lds_dwordx4 v138, s[64:65]
	s_waitcnt vmcnt(8)
	s_waitcnt lgkmcnt(0)
	s_barrier
	s_setprio 1
	s_waitcnt lgkmcnt(0)
	v_mfma_f32_16x16x32_bf16 v[124:127], v[174:177], v[216:219], v[124:127]
	v_mfma_f32_16x16x32_bf16 v[120:123], v[184:187], v[216:219], v[120:123]
	v_mfma_f32_16x16x32_bf16 v[108:111], v[174:177], v[224:227], v[108:111]
	v_mfma_f32_16x16x32_bf16 v[104:107], v[184:187], v[224:227], v[104:107]
	v_mfma_f32_16x16x32_bf16 v[92:95], v[174:177], v[234:237], v[92:95]
	v_mfma_f32_16x16x32_bf16 v[88:91], v[184:187], v[234:237], v[88:91]
	v_mfma_f32_16x16x32_bf16 v[76:79], v[174:177], v[242:245], v[76:79]
	v_mfma_f32_16x16x32_bf16 v[72:75], v[184:187], v[242:245], v[72:75]
	v_mfma_f32_16x16x32_bf16 v[124:127], v[180:183], v[220:223], v[124:127]
	v_mfma_f32_16x16x32_bf16 v[120:123], v[188:191], v[220:223], v[120:123]
	v_mfma_f32_16x16x32_bf16 v[108:111], v[180:183], v[228:231], v[108:111]
	v_mfma_f32_16x16x32_bf16 v[104:107], v[188:191], v[228:231], v[104:107]
	v_mfma_f32_16x16x32_bf16 v[92:95], v[180:183], v[238:241], v[92:95]
	v_mfma_f32_16x16x32_bf16 v[88:91], v[188:191], v[238:241], v[88:91]
	v_mfma_f32_16x16x32_bf16 v[76:79], v[180:183], v[246:249], v[76:79]
	v_mfma_f32_16x16x32_bf16 v[72:75], v[188:191], v[246:249], v[72:75]
	s_setprio 0
	s_setprio 1
	v_mfma_f32_16x16x32_bf16 v[116:119], v[192:195], v[216:219], v[116:119]
	v_mfma_f32_16x16x32_bf16 v[112:115], v[202:205], v[216:219], v[112:115]
	v_mfma_f32_16x16x32_bf16 v[100:103], v[192:195], v[224:227], v[100:103]
	v_mfma_f32_16x16x32_bf16 v[96:99], v[202:205], v[224:227], v[96:99]
	v_mfma_f32_16x16x32_bf16 v[84:87], v[192:195], v[234:237], v[84:87]
	v_mfma_f32_16x16x32_bf16 v[80:83], v[202:205], v[234:237], v[80:83]
	v_mfma_f32_16x16x32_bf16 v[68:71], v[192:195], v[242:245], v[68:71]
	v_mfma_f32_16x16x32_bf16 v[64:67], v[202:205], v[242:245], v[64:67]
	v_mfma_f32_16x16x32_bf16 v[116:119], v[196:199], v[220:223], v[116:119]
	v_mfma_f32_16x16x32_bf16 v[112:115], v[206:209], v[220:223], v[112:115]
	v_mfma_f32_16x16x32_bf16 v[100:103], v[196:199], v[228:231], v[100:103]
	v_mfma_f32_16x16x32_bf16 v[96:99], v[206:209], v[228:231], v[96:99]
	v_mfma_f32_16x16x32_bf16 v[84:87], v[196:199], v[238:241], v[84:87]
	v_mfma_f32_16x16x32_bf16 v[80:83], v[206:209], v[238:241], v[80:83]
	v_mfma_f32_16x16x32_bf16 v[68:71], v[196:199], v[246:249], v[68:71]
	v_mfma_f32_16x16x32_bf16 v[64:67], v[206:209], v[246:249], v[64:67]
	s_setprio 0
	s_barrier
	s_add_i32 s64, s0, s77
	s_add_u32 s98, s98, s14
	s_addc_u32 s99, s99, s15
	s_mov_b32 m0, s64
	ds_read_b128 v[216:219], v200 offset:49152
	ds_read_b128 v[220:223], v200 offset:50176
	ds_read_b128 v[224:227], v200 offset:51200
	ds_read_b128 v[228:231], v200 offset:52224
	ds_read_b128 v[234:237], v200 offset:53248
	ds_read_b128 v[238:241], v200 offset:54272
	ds_read_b128 v[242:245], v200 offset:55296
	ds_read_b128 v[246:249], v200 offset:56320
	global_load_lds_dwordx4 v136, s[98:99]
	s_add_i32 m0, s64, 0x2000
	s_add_u32 s48, s48, 0x40080
	s_addc_u32 s49, s49, 0
	s_add_i32 s64, s85, s77
	global_load_lds_dwordx4 v140, s[98:99]
	s_mov_b32 m0, s64
	s_nop 0
	global_load_lds_dwordx4 v136, s[48:49]
	s_add_i32 m0, s64, 0x2000
	s_nop 0
	global_load_lds_dwordx4 v140, s[48:49]
	s_add_u32 s100, s100, s14
	s_addc_u32 s101, s101, s15
	s_mov_b32 m0, s81
	s_nop 0
	global_load_lds_dwordx4 v134, s[100:101]
	s_mov_b32 m0, s82
	s_nop 0
	global_load_lds_dwordx4 v138, s[100:101]
	s_waitcnt vmcnt(8)
	s_waitcnt lgkmcnt(0)
	s_barrier
	s_setprio 1
	s_waitcnt lgkmcnt(0)
	v_mfma_f32_16x16x32_bf16 v[60:63], v[174:177], v[216:219], v[60:63]
	v_mfma_f32_16x16x32_bf16 v[56:59], v[184:187], v[216:219], v[56:59]
	v_mfma_f32_16x16x32_bf16 v[44:47], v[174:177], v[224:227], v[44:47]
	v_mfma_f32_16x16x32_bf16 v[40:43], v[184:187], v[224:227], v[40:43]
	v_mfma_f32_16x16x32_bf16 v[28:31], v[174:177], v[234:237], v[28:31]
	v_mfma_f32_16x16x32_bf16 v[24:27], v[184:187], v[234:237], v[24:27]
	v_mfma_f32_16x16x32_bf16 v[12:15], v[174:177], v[242:245], v[12:15]
	v_mfma_f32_16x16x32_bf16 v[8:11], v[184:187], v[242:245], v[8:11]
	v_mfma_f32_16x16x32_bf16 v[60:63], v[180:183], v[220:223], v[60:63]
	v_mfma_f32_16x16x32_bf16 v[56:59], v[188:191], v[220:223], v[56:59]
	v_mfma_f32_16x16x32_bf16 v[44:47], v[180:183], v[228:231], v[44:47]
	v_mfma_f32_16x16x32_bf16 v[40:43], v[188:191], v[228:231], v[40:43]
	v_mfma_f32_16x16x32_bf16 v[28:31], v[180:183], v[238:241], v[28:31]
	v_mfma_f32_16x16x32_bf16 v[24:27], v[188:191], v[238:241], v[24:27]
	v_mfma_f32_16x16x32_bf16 v[12:15], v[180:183], v[246:249], v[12:15]
	v_mfma_f32_16x16x32_bf16 v[8:11], v[188:191], v[246:249], v[8:11]
	s_setprio 0
	s_setprio 1
	v_mfma_f32_16x16x32_bf16 v[52:55], v[192:195], v[216:219], v[52:55]
	v_mfma_f32_16x16x32_bf16 v[48:51], v[202:205], v[216:219], v[48:51]
	v_mfma_f32_16x16x32_bf16 v[36:39], v[192:195], v[224:227], v[36:39]
	v_mfma_f32_16x16x32_bf16 v[32:35], v[202:205], v[224:227], v[32:35]
	v_mfma_f32_16x16x32_bf16 v[20:23], v[192:195], v[234:237], v[20:23]
	v_mfma_f32_16x16x32_bf16 v[16:19], v[202:205], v[234:237], v[16:19]
	v_mfma_f32_16x16x32_bf16 v[4:7], v[192:195], v[242:245], v[4:7]
	v_mfma_f32_16x16x32_bf16 v[0:3], v[202:205], v[242:245], v[0:3]
	v_mfma_f32_16x16x32_bf16 v[52:55], v[196:199], v[220:223], v[52:55]
	v_mfma_f32_16x16x32_bf16 v[48:51], v[206:209], v[220:223], v[48:51]
	v_mfma_f32_16x16x32_bf16 v[36:39], v[196:199], v[228:231], v[36:39]
	v_mfma_f32_16x16x32_bf16 v[32:35], v[206:209], v[228:231], v[32:35]
	v_mfma_f32_16x16x32_bf16 v[20:23], v[196:199], v[238:241], v[20:23]
	v_mfma_f32_16x16x32_bf16 v[16:19], v[206:209], v[238:241], v[16:19]
	v_mfma_f32_16x16x32_bf16 v[4:7], v[196:199], v[246:249], v[4:7]
	v_mfma_f32_16x16x32_bf16 v[0:3], v[206:209], v[246:249], v[0:3]
	s_setprio 0
	s_barrier
	s_add_i32 s71, s71, 2
	s_add_u32 s8, s8, 0x100
	s_addc_u32 s9, s9, 0
	s_add_u32 s69, s69, 0x100
	s_addc_u32 s70, s70, 0
	s_cmp_gt_u32 s71, 13
	s_cbranch_scc0 .LBB0_2108
	s_and_b64 vcc, exec, s[54:55]
	s_cbranch_vccz .LBB0_2111
	s_barrier

.LBB0_2189:
	s_add_u32 s68, s48, 0xfffe0080
	s_addc_u32 s69, s49, -1
	s_add_i32 s78, 0, 0x10000
	s_cmp_eq_u32 vcc_lo, 4
	s_cselect_b32 s73, s1, s69
	s_cselect_b32 s72, s7, s68
	s_cselect_b32 s69, s61, s75
	s_cselect_b32 s68, s63, s74
	s_add_i32 vcc_hi, 0, 0x14000
	v_add_u32_e32 v140, s78, v225
	v_add_u32_e32 v144, vcc_hi, v225
	ds_read_b128 v[128:131], v140
	ds_read_b128 v[132:135], v140 offset:1024
	ds_read_b128 v[136:139], v140 offset:2048
	ds_read_b128 v[140:143], v140 offset:3072
	ds_read_b128 v[172:175], v144
	ds_read_b128 v[176:179], v144 offset:1024
	ds_read_b128 v[180:183], v144 offset:2048
	ds_read_b128 v[184:187], v144 offset:3072
	s_add_i32 m0, s18, 0xc000
	ds_read_b128 v[188:191], v228
	ds_read_b128 v[192:195], v228 offset:1024
	ds_read_b128 v[196:199], v228 offset:2048
	ds_read_b128 v[200:203], v228 offset:3072
	ds_read_b128 v[204:207], v228 offset:4096
	ds_read_b128 v[208:211], v228 offset:5120
	ds_read_b128 v[234:237], v228 offset:6144
	ds_read_b128 v[238:241], v228 offset:7168
	global_load_lds_dwordx4 v166, s[48:49]
	s_add_i32 m0, s18, 0xe000
	s_nop 0
	global_load_lds_dwordx4 v168, s[48:49]
	s_waitcnt vmcnt(8)
	s_waitcnt lgkmcnt(0)
	s_barrier
	s_setprio 1
	s_waitcnt lgkmcnt(0)
	v_mfma_i32_16x16x64_i8 v[124:127], v[128:131], v[188:191], v[124:127]
	v_mfma_i32_16x16x64_i8 v[120:123], v[136:139], v[188:191], v[120:123]
	v_mfma_i32_16x16x64_i8 v[116:119], v[128:131], v[196:199], v[116:119]
	v_mfma_i32_16x16x64_i8 v[112:115], v[136:139], v[196:199], v[112:115]
	v_mfma_i32_16x16x64_i8 v[108:111], v[128:131], v[204:207], v[108:111]
	v_mfma_i32_16x16x64_i8 v[104:107], v[136:139], v[204:207], v[104:107]
	v_mfma_i32_16x16x64_i8 v[100:103], v[128:131], v[234:237], v[100:103]
	v_mfma_i32_16x16x64_i8 v[96:99], v[136:139], v[234:237], v[96:99]
	v_mfma_i32_16x16x64_i8 v[124:127], v[132:135], v[192:195], v[124:127]
	v_mfma_i32_16x16x64_i8 v[120:123], v[140:143], v[192:195], v[120:123]
	v_mfma_i32_16x16x64_i8 v[116:119], v[132:135], v[200:203], v[116:119]
	v_mfma_i32_16x16x64_i8 v[112:115], v[140:143], v[200:203], v[112:115]
	v_mfma_i32_16x16x64_i8 v[108:111], v[132:135], v[208:211], v[108:111]
	v_mfma_i32_16x16x64_i8 v[104:107], v[140:143], v[208:211], v[104:107]
	v_mfma_i32_16x16x64_i8 v[100:103], v[132:135], v[238:241], v[100:103]
	v_mfma_i32_16x16x64_i8 v[96:99], v[140:143], v[238:241], v[96:99]
	s_setprio 0
	s_setprio 1
	v_mfma_i32_16x16x64_i8 v[92:95], v[172:175], v[188:191], v[92:95]
	v_mfma_i32_16x16x64_i8 v[88:91], v[180:183], v[188:191], v[88:91]
	v_mfma_i32_16x16x64_i8 v[84:87], v[172:175], v[196:199], v[84:87]
	v_mfma_i32_16x16x64_i8 v[80:83], v[180:183], v[196:199], v[80:83]
	v_mfma_i32_16x16x64_i8 v[76:79], v[172:175], v[204:207], v[76:79]
	v_mfma_i32_16x16x64_i8 v[72:75], v[180:183], v[204:207], v[72:75]
	v_mfma_i32_16x16x64_i8 v[68:71], v[172:175], v[234:237], v[68:71]
	v_mfma_i32_16x16x64_i8 v[64:67], v[180:183], v[234:237], v[64:67]
	v_mfma_i32_16x16x64_i8 v[92:95], v[176:179], v[192:195], v[92:95]
	v_mfma_i32_16x16x64_i8 v[88:91], v[184:187], v[192:195], v[88:91]
	v_mfma_i32_16x16x64_i8 v[84:87], v[176:179], v[200:203], v[84:87]
	v_mfma_i32_16x16x64_i8 v[80:83], v[184:187], v[200:203], v[80:83]
	v_mfma_i32_16x16x64_i8 v[76:79], v[176:179], v[208:211], v[76:79]
	v_mfma_i32_16x16x64_i8 v[72:75], v[184:187], v[208:211], v[72:75]
	v_mfma_i32_16x16x64_i8 v[68:71], v[176:179], v[238:241], v[68:71]
	v_mfma_i32_16x16x64_i8 v[64:67], v[184:187], v[238:241], v[64:67]
	s_setprio 0
	s_barrier
	s_add_i32 s78, s78, s11
	s_mov_b64 s[98:99], s[68:69]
	s_mov_b32 m0, s78
	ds_read_b128 v[188:191], v228 offset:16384
	ds_read_b128 v[192:195], v228 offset:17408
	ds_read_b128 v[196:199], v228 offset:18432
	ds_read_b128 v[200:203], v228 offset:19456
	ds_read_b128 v[204:207], v228 offset:20480
	ds_read_b128 v[208:211], v228 offset:21504
	ds_read_b128 v[234:237], v228 offset:22528
	ds_read_b128 v[238:241], v228 offset:23552
	global_load_lds_dwordx4 v152, s[68:69]
	s_add_i32 m0, s78, 0x2000
	s_add_u32 s78, s68, 0x20000
	s_addc_u32 s79, s69, 0
	s_add_i32 vcc_hi, vcc_hi, s11
	global_load_lds_dwordx4 v156, s[68:69]
	s_mov_b32 m0, vcc_hi
	s_mov_b64 s[100:101], s[72:73]
	global_load_lds_dwordx4 v152, s[78:79]
	s_add_i32 m0, vcc_hi, 0x2000
	s_nop 0
	global_load_lds_dwordx4 v156, s[78:79]
	s_mov_b32 m0, s18
	s_nop 0
	global_load_lds_dwordx4 v150, s[72:73]
	s_mov_b32 m0, s19
	s_nop 0
	global_load_lds_dwordx4 v154, s[72:73]
	s_waitcnt vmcnt(8)
	s_waitcnt lgkmcnt(0)
	s_barrier
	s_setprio 1
	s_waitcnt lgkmcnt(0)
	v_mfma_i32_16x16x64_i8 v[60:63], v[128:131], v[188:191], v[60:63]
	v_mfma_i32_16x16x64_i8 v[56:59], v[136:139], v[188:191], v[56:59]
	v_mfma_i32_16x16x64_i8 v[52:55], v[128:131], v[196:199], v[52:55]
	v_mfma_i32_16x16x64_i8 v[48:51], v[136:139], v[196:199], v[48:51]
	v_mfma_i32_16x16x64_i8 v[44:47], v[128:131], v[204:207], v[44:47]
	v_mfma_i32_16x16x64_i8 v[40:43], v[136:139], v[204:207], v[40:43]
	v_mfma_i32_16x16x64_i8 v[36:39], v[128:131], v[234:237], v[36:39]
	v_mfma_i32_16x16x64_i8 v[32:35], v[136:139], v[234:237], v[32:35]
	v_mfma_i32_16x16x64_i8 v[60:63], v[132:135], v[192:195], v[60:63]
	v_mfma_i32_16x16x64_i8 v[56:59], v[140:143], v[192:195], v[56:59]
	v_mfma_i32_16x16x64_i8 v[52:55], v[132:135], v[200:203], v[52:55]
	v_mfma_i32_16x16x64_i8 v[48:51], v[140:143], v[200:203], v[48:51]
	v_mfma_i32_16x16x64_i8 v[44:47], v[132:135], v[208:211], v[44:47]
	v_mfma_i32_16x16x64_i8 v[40:43], v[140:143], v[208:211], v[40:43]
	v_mfma_i32_16x16x64_i8 v[36:39], v[132:135], v[238:241], v[36:39]
	v_mfma_i32_16x16x64_i8 v[32:35], v[140:143], v[238:241], v[32:35]
	s_setprio 0
	s_setprio 1
	v_mfma_i32_16x16x64_i8 v[28:31], v[172:175], v[188:191], v[28:31]
	v_mfma_i32_16x16x64_i8 v[24:27], v[180:183], v[188:191], v[24:27]
	v_mfma_i32_16x16x64_i8 v[20:23], v[172:175], v[196:199], v[20:23]
	v_mfma_i32_16x16x64_i8 v[16:19], v[180:183], v[196:199], v[16:19]
	v_mfma_i32_16x16x64_i8 v[12:15], v[172:175], v[204:207], v[12:15]
	v_mfma_i32_16x16x64_i8 v[8:11], v[180:183], v[204:207], v[8:11]
	v_mfma_i32_16x16x64_i8 v[4:7], v[172:175], v[234:237], v[4:7]
	v_mfma_i32_16x16x64_i8 v[0:3], v[180:183], v[234:237], v[0:3]
	v_mfma_i32_16x16x64_i8 v[28:31], v[176:179], v[192:195], v[28:31]
	v_mfma_i32_16x16x64_i8 v[24:27], v[184:187], v[192:195], v[24:27]
	v_mfma_i32_16x16x64_i8 v[20:23], v[176:179], v[200:203], v[20:23]
	v_mfma_i32_16x16x64_i8 v[16:19], v[184:187], v[200:203], v[16:19]
	v_mfma_i32_16x16x64_i8 v[12:15], v[176:179], v[208:211], v[12:15]
	v_mfma_i32_16x16x64_i8 v[8:11], v[184:187], v[208:211], v[8:11]
	v_mfma_i32_16x16x64_i8 v[4:7], v[176:179], v[238:241], v[4:7]
	v_mfma_i32_16x16x64_i8 v[0:3], v[184:187], v[238:241], v[0:3]
	s_setprio 0
	s_barrier
	s_add_i32 s78, 0, 0x1c000
	v_add_u32_e32 v140, s0, v225
	v_add_u32_e32 v144, s78, v225
	ds_read_b128 v[128:131], v140
	ds_read_b128 v[132:135], v140 offset:1024
	ds_read_b128 v[136:139], v140 offset:2048
	ds_read_b128 v[140:143], v140 offset:3072
	ds_read_b128 v[172:175], v144
	ds_read_b128 v[176:179], v144 offset:1024
	ds_read_b128 v[180:183], v144 offset:2048
	ds_read_b128 v[184:187], v144 offset:3072
	s_add_u32 s72, s72, 0x20000
	s_addc_u32 s73, s73, 0
	s_mov_b32 m0, s20
	ds_read_b128 v[188:191], v228 offset:32768
	ds_read_b128 v[192:195], v228 offset:33792
	ds_read_b128 v[196:199], v228 offset:34816
	ds_read_b128 v[200:203], v228 offset:35840
	ds_read_b128 v[204:207], v228 offset:36864
	ds_read_b128 v[208:211], v228 offset:37888
	ds_read_b128 v[234:237], v228 offset:38912
	ds_read_b128 v[238:241], v228 offset:39936
	global_load_lds_dwordx4 v150, s[72:73]
	s_mov_b32 m0, s21
	s_nop 0
	global_load_lds_dwordx4 v154, s[72:73]
	s_waitcnt vmcnt(8)
	s_waitcnt lgkmcnt(0)
	s_barrier
	s_setprio 1
	s_waitcnt lgkmcnt(0)
	v_mfma_i32_16x16x64_i8 v[124:127], v[128:131], v[188:191], v[124:127]
	v_mfma_i32_16x16x64_i8 v[120:123], v[136:139], v[188:191], v[120:123]
	v_mfma_i32_16x16x64_i8 v[116:119], v[128:131], v[196:199], v[116:119]
	v_mfma_i32_16x16x64_i8 v[112:115], v[136:139], v[196:199], v[112:115]
	v_mfma_i32_16x16x64_i8 v[108:111], v[128:131], v[204:207], v[108:111]
	v_mfma_i32_16x16x64_i8 v[104:107], v[136:139], v[204:207], v[104:107]
	v_mfma_i32_16x16x64_i8 v[100:103], v[128:131], v[234:237], v[100:103]
	v_mfma_i32_16x16x64_i8 v[96:99], v[136:139], v[234:237], v[96:99]
	v_mfma_i32_16x16x64_i8 v[124:127], v[132:135], v[192:195], v[124:127]
	v_mfma_i32_16x16x64_i8 v[120:123], v[140:143], v[192:195], v[120:123]
	v_mfma_i32_16x16x64_i8 v[116:119], v[132:135], v[200:203], v[116:119]
	v_mfma_i32_16x16x64_i8 v[112:115], v[140:143], v[200:203], v[112:115]
	v_mfma_i32_16x16x64_i8 v[108:111], v[132:135], v[208:211], v[108:111]
	v_mfma_i32_16x16x64_i8 v[104:107], v[140:143], v[208:211], v[104:107]
	v_mfma_i32_16x16x64_i8 v[100:103], v[132:135], v[238:241], v[100:103]
	v_mfma_i32_16x16x64_i8 v[96:99], v[140:143], v[238:241], v[96:99]
	s_setprio 0
	s_setprio 1
	v_mfma_i32_16x16x64_i8 v[92:95], v[172:175], v[188:191], v[92:95]
	v_mfma_i32_16x16x64_i8 v[88:91], v[180:183], v[188:191], v[88:91]
	v_mfma_i32_16x16x64_i8 v[84:87], v[172:175], v[196:199], v[84:87]
	v_mfma_i32_16x16x64_i8 v[80:83], v[180:183], v[196:199], v[80:83]
	v_mfma_i32_16x16x64_i8 v[76:79], v[172:175], v[204:207], v[76:79]
	v_mfma_i32_16x16x64_i8 v[72:75], v[180:183], v[204:207], v[72:75]
	v_mfma_i32_16x16x64_i8 v[68:71], v[172:175], v[234:237], v[68:71]
	v_mfma_i32_16x16x64_i8 v[64:67], v[180:183], v[234:237], v[64:67]
	v_mfma_i32_16x16x64_i8 v[92:95], v[176:179], v[192:195], v[92:95]
	v_mfma_i32_16x16x64_i8 v[88:91], v[184:187], v[192:195], v[88:91]
	v_mfma_i32_16x16x64_i8 v[84:87], v[176:179], v[200:203], v[84:87]
	v_mfma_i32_16x16x64_i8 v[80:83], v[184:187], v[200:203], v[80:83]
	v_mfma_i32_16x16x64_i8 v[76:79], v[176:179], v[208:211], v[76:79]
	v_mfma_i32_16x16x64_i8 v[72:75], v[184:187], v[208:211], v[72:75]
	v_mfma_i32_16x16x64_i8 v[68:71], v[176:179], v[238:241], v[68:71]
	v_mfma_i32_16x16x64_i8 v[64:67], v[184:187], v[238:241], v[64:67]
	s_setprio 0
	s_barrier
	s_add_i32 s72, s0, s11
	s_add_u32 s98, s98, s24
	s_addc_u32 s99, s99, s25
	s_mov_b32 m0, s72
	ds_read_b128 v[188:191], v228 offset:49152
	ds_read_b128 v[192:195], v228 offset:50176
	ds_read_b128 v[196:199], v228 offset:51200
	ds_read_b128 v[200:203], v228 offset:52224
	ds_read_b128 v[204:207], v228 offset:53248
	ds_read_b128 v[208:211], v228 offset:54272
	ds_read_b128 v[234:237], v228 offset:55296
	ds_read_b128 v[238:241], v228 offset:56320
	global_load_lds_dwordx4 v152, s[98:99]
	s_add_i32 m0, s72, 0x2000
	s_add_u32 s68, s68, 0x20080
	s_addc_u32 s69, s69, 0
	s_add_i32 s72, s78, s11
	global_load_lds_dwordx4 v156, s[98:99]
	s_mov_b32 m0, s72
	s_nop 0
	global_load_lds_dwordx4 v152, s[68:69]
	s_add_i32 m0, s72, 0x2000
	s_nop 0
	global_load_lds_dwordx4 v156, s[68:69]
	s_add_u32 s100, s100, s24
	s_addc_u32 s101, s101, s25
	s_mov_b32 m0, s77
	s_nop 0
	global_load_lds_dwordx4 v150, s[100:101]
	s_mov_b32 m0, s84
	s_nop 0
	global_load_lds_dwordx4 v154, s[100:101]
	s_waitcnt vmcnt(8)
	s_waitcnt lgkmcnt(0)
	s_barrier
	s_setprio 1
	s_waitcnt lgkmcnt(0)
	v_mfma_i32_16x16x64_i8 v[60:63], v[128:131], v[188:191], v[60:63]
	v_mfma_i32_16x16x64_i8 v[56:59], v[136:139], v[188:191], v[56:59]
	v_mfma_i32_16x16x64_i8 v[52:55], v[128:131], v[196:199], v[52:55]
	v_mfma_i32_16x16x64_i8 v[48:51], v[136:139], v[196:199], v[48:51]
	v_mfma_i32_16x16x64_i8 v[44:47], v[128:131], v[204:207], v[44:47]
	v_mfma_i32_16x16x64_i8 v[40:43], v[136:139], v[204:207], v[40:43]
	v_mfma_i32_16x16x64_i8 v[36:39], v[128:131], v[234:237], v[36:39]
	v_mfma_i32_16x16x64_i8 v[32:35], v[136:139], v[234:237], v[32:35]
	v_mfma_i32_16x16x64_i8 v[60:63], v[132:135], v[192:195], v[60:63]
	v_mfma_i32_16x16x64_i8 v[56:59], v[140:143], v[192:195], v[56:59]
	v_mfma_i32_16x16x64_i8 v[52:55], v[132:135], v[200:203], v[52:55]
	v_mfma_i32_16x16x64_i8 v[48:51], v[140:143], v[200:203], v[48:51]
	v_mfma_i32_16x16x64_i8 v[44:47], v[132:135], v[208:211], v[44:47]
	v_mfma_i32_16x16x64_i8 v[40:43], v[140:143], v[208:211], v[40:43]
	v_mfma_i32_16x16x64_i8 v[36:39], v[132:135], v[238:241], v[36:39]
	v_mfma_i32_16x16x64_i8 v[32:35], v[140:143], v[238:241], v[32:35]
	s_setprio 0
	s_setprio 1
	v_mfma_i32_16x16x64_i8 v[28:31], v[172:175], v[188:191], v[28:31]
	v_mfma_i32_16x16x64_i8 v[24:27], v[180:183], v[188:191], v[24:27]
	v_mfma_i32_16x16x64_i8 v[20:23], v[172:175], v[196:199], v[20:23]
	v_mfma_i32_16x16x64_i8 v[16:19], v[180:183], v[196:199], v[16:19]
	v_mfma_i32_16x16x64_i8 v[12:15], v[172:175], v[204:207], v[12:15]
	v_mfma_i32_16x16x64_i8 v[8:11], v[180:183], v[204:207], v[8:11]
	v_mfma_i32_16x16x64_i8 v[4:7], v[172:175], v[234:237], v[4:7]
	v_mfma_i32_16x16x64_i8 v[0:3], v[180:183], v[234:237], v[0:3]
	v_mfma_i32_16x16x64_i8 v[28:31], v[176:179], v[192:195], v[28:31]
	v_mfma_i32_16x16x64_i8 v[24:27], v[184:187], v[192:195], v[24:27]
	v_mfma_i32_16x16x64_i8 v[20:23], v[176:179], v[200:203], v[20:23]
	v_mfma_i32_16x16x64_i8 v[16:19], v[184:187], v[200:203], v[16:19]
	v_mfma_i32_16x16x64_i8 v[12:15], v[176:179], v[208:211], v[12:15]
	v_mfma_i32_16x16x64_i8 v[8:11], v[184:187], v[208:211], v[8:11]
	v_mfma_i32_16x16x64_i8 v[4:7], v[176:179], v[238:241], v[4:7]
	v_mfma_i32_16x16x64_i8 v[0:3], v[184:187], v[238:241], v[0:3]
	s_setprio 0
	s_barrier
	s_add_i32 vcc_lo, vcc_lo, 2
	s_add_u32 s48, s48, 0x100
	s_addc_u32 s49, s49, 0
	s_add_u32 s74, s74, 0x100
	s_addc_u32 s75, s75, 0
	s_cmp_gt_u32 vcc_lo, 5
	s_cbranch_scc0 .LBB0_2189
	s_and_b64 vcc, exec, s[58:59]
	s_cbranch_vccz .LBB0_2192
	s_barrier

.LBB0_2520:
	s_add_u32 s48, s8, 0xfffc0080
	s_addc_u32 s49, s9, -1
	s_add_i32 s84, 0, 0x10000
	s_cmp_eq_u32 s67, 12
	s_cselect_b32 s61, s7, s49
	s_cselect_b32 s60, s55, s48
	v_add_u32_e32 v128, s84, v173
	s_cselect_b32 s49, s53, s66
	s_cselect_b32 s48, s64, s65
	s_add_i32 s88, 0, 0x14000
	ds_read_b128 v[174:177], v128
	ds_read_b128 v[180:183], v128 offset:1024
	ds_read_b128 v[184:187], v128 offset:2048
	ds_read_b128 v[188:191], v128 offset:3072
	v_add_u32_e32 v128, s88, v173
	ds_read_b128 v[192:195], v128
	ds_read_b128 v[196:199], v128 offset:1024
	ds_read_b128 v[204:207], v128 offset:2048
	ds_read_b128 v[208:211], v128 offset:3072
	s_add_i32 m0, s63, 0xc000
	ds_read_b128 v[212:215], v203
	ds_read_b128 v[216:219], v203 offset:1024
	ds_read_b128 v[220:223], v203 offset:2048
	ds_read_b128 v[224:227], v203 offset:3072
	ds_read_b128 v[228:231], v203 offset:4096
	ds_read_b128 v[234:237], v203 offset:5120
	ds_read_b128 v[238:241], v203 offset:6144
	ds_read_b128 v[242:245], v203 offset:7168
	global_load_lds_dwordx4 v148, s[8:9]
	s_add_i32 m0, s63, 0xe000
	s_nop 0
	global_load_lds_dwordx4 v150, s[8:9]
	s_waitcnt vmcnt(8)
	s_waitcnt lgkmcnt(0)
	s_barrier
	s_setprio 1
	s_waitcnt lgkmcnt(0)
	v_mfma_f32_16x16x32_bf16 v[124:127], v[174:177], v[212:215], v[124:127]
	v_mfma_f32_16x16x32_bf16 v[120:123], v[184:187], v[212:215], v[120:123]
	v_mfma_f32_16x16x32_bf16 v[108:111], v[174:177], v[220:223], v[108:111]
	v_mfma_f32_16x16x32_bf16 v[104:107], v[184:187], v[220:223], v[104:107]
	v_mfma_f32_16x16x32_bf16 v[92:95], v[174:177], v[228:231], v[92:95]
	v_mfma_f32_16x16x32_bf16 v[88:91], v[184:187], v[228:231], v[88:91]
	v_mfma_f32_16x16x32_bf16 v[76:79], v[174:177], v[238:241], v[76:79]
	v_mfma_f32_16x16x32_bf16 v[72:75], v[184:187], v[238:241], v[72:75]
	v_mfma_f32_16x16x32_bf16 v[124:127], v[180:183], v[216:219], v[124:127]
	v_mfma_f32_16x16x32_bf16 v[120:123], v[188:191], v[216:219], v[120:123]
	v_mfma_f32_16x16x32_bf16 v[108:111], v[180:183], v[224:227], v[108:111]
	v_mfma_f32_16x16x32_bf16 v[104:107], v[188:191], v[224:227], v[104:107]
	v_mfma_f32_16x16x32_bf16 v[92:95], v[180:183], v[234:237], v[92:95]
	v_mfma_f32_16x16x32_bf16 v[88:91], v[188:191], v[234:237], v[88:91]
	v_mfma_f32_16x16x32_bf16 v[76:79], v[180:183], v[242:245], v[76:79]
	v_mfma_f32_16x16x32_bf16 v[72:75], v[188:191], v[242:245], v[72:75]
	s_setprio 0
	s_setprio 1
	v_mfma_f32_16x16x32_bf16 v[116:119], v[192:195], v[212:215], v[116:119]
	v_mfma_f32_16x16x32_bf16 v[112:115], v[204:207], v[212:215], v[112:115]
	v_mfma_f32_16x16x32_bf16 v[100:103], v[192:195], v[220:223], v[100:103]
	v_mfma_f32_16x16x32_bf16 v[96:99], v[204:207], v[220:223], v[96:99]
	v_mfma_f32_16x16x32_bf16 v[84:87], v[192:195], v[228:231], v[84:87]
	v_mfma_f32_16x16x32_bf16 v[80:83], v[204:207], v[228:231], v[80:83]
	v_mfma_f32_16x16x32_bf16 v[68:71], v[192:195], v[238:241], v[68:71]
	v_mfma_f32_16x16x32_bf16 v[64:67], v[204:207], v[238:241], v[64:67]
	v_mfma_f32_16x16x32_bf16 v[116:119], v[196:199], v[216:219], v[116:119]
	v_mfma_f32_16x16x32_bf16 v[112:115], v[208:211], v[216:219], v[112:115]
	v_mfma_f32_16x16x32_bf16 v[100:103], v[196:199], v[224:227], v[100:103]
	v_mfma_f32_16x16x32_bf16 v[96:99], v[208:211], v[224:227], v[96:99]
	v_mfma_f32_16x16x32_bf16 v[84:87], v[196:199], v[234:237], v[84:87]
	v_mfma_f32_16x16x32_bf16 v[80:83], v[208:211], v[234:237], v[80:83]
	v_mfma_f32_16x16x32_bf16 v[68:71], v[196:199], v[242:245], v[68:71]
	v_mfma_f32_16x16x32_bf16 v[64:67], v[208:211], v[242:245], v[64:67]
	s_setprio 0
	s_barrier
	s_add_i32 s84, s84, s75
	s_mov_b64 s[98:99], s[48:49]
	s_mov_b32 m0, s84
	ds_read_b128 v[212:215], v203 offset:16384
	ds_read_b128 v[216:219], v203 offset:17408
	ds_read_b128 v[220:223], v203 offset:18432
	ds_read_b128 v[224:227], v203 offset:19456
	ds_read_b128 v[228:231], v203 offset:20480
	ds_read_b128 v[234:237], v203 offset:21504
	ds_read_b128 v[238:241], v203 offset:22528
	ds_read_b128 v[242:245], v203 offset:23552
	global_load_lds_dwordx4 v136, s[48:49]
	s_add_i32 m0, s84, 0x2000
	s_add_u32 s86, s48, 0x40000
	s_addc_u32 s87, s49, 0
	s_add_i32 s84, s88, s75
	global_load_lds_dwordx4 v140, s[48:49]
	s_mov_b32 m0, s84
	s_mov_b64 s[100:101], s[60:61]
	global_load_lds_dwordx4 v136, s[86:87]
	s_add_i32 m0, s84, 0x2000
	s_nop 0
	global_load_lds_dwordx4 v140, s[86:87]
	s_mov_b32 m0, s63
	s_nop 0
	global_load_lds_dwordx4 v134, s[60:61]
	s_mov_b32 m0, s76
	s_nop 0
	global_load_lds_dwordx4 v138, s[60:61]
	s_waitcnt vmcnt(8)
	s_waitcnt lgkmcnt(0)
	s_barrier
	s_setprio 1
	s_waitcnt lgkmcnt(0)
	v_mfma_f32_16x16x32_bf16 v[60:63], v[174:177], v[212:215], v[60:63]
	v_mfma_f32_16x16x32_bf16 v[56:59], v[184:187], v[212:215], v[56:59]
	v_mfma_f32_16x16x32_bf16 v[44:47], v[174:177], v[220:223], v[44:47]
	v_mfma_f32_16x16x32_bf16 v[40:43], v[184:187], v[220:223], v[40:43]
	v_mfma_f32_16x16x32_bf16 v[28:31], v[174:177], v[228:231], v[28:31]
	v_mfma_f32_16x16x32_bf16 v[24:27], v[184:187], v[228:231], v[24:27]
	v_mfma_f32_16x16x32_bf16 v[12:15], v[174:177], v[238:241], v[12:15]
	v_mfma_f32_16x16x32_bf16 v[8:11], v[184:187], v[238:241], v[8:11]
	v_mfma_f32_16x16x32_bf16 v[60:63], v[180:183], v[216:219], v[60:63]
	v_mfma_f32_16x16x32_bf16 v[56:59], v[188:191], v[216:219], v[56:59]
	v_mfma_f32_16x16x32_bf16 v[44:47], v[180:183], v[224:227], v[44:47]
	v_mfma_f32_16x16x32_bf16 v[40:43], v[188:191], v[224:227], v[40:43]
	v_mfma_f32_16x16x32_bf16 v[28:31], v[180:183], v[234:237], v[28:31]
	v_mfma_f32_16x16x32_bf16 v[24:27], v[188:191], v[234:237], v[24:27]
	v_mfma_f32_16x16x32_bf16 v[12:15], v[180:183], v[242:245], v[12:15]
	v_mfma_f32_16x16x32_bf16 v[8:11], v[188:191], v[242:245], v[8:11]
	s_setprio 0
	s_setprio 1
	v_mfma_f32_16x16x32_bf16 v[52:55], v[192:195], v[212:215], v[52:55]
	v_mfma_f32_16x16x32_bf16 v[48:51], v[204:207], v[212:215], v[48:51]
	v_mfma_f32_16x16x32_bf16 v[36:39], v[192:195], v[220:223], v[36:39]
	v_mfma_f32_16x16x32_bf16 v[32:35], v[204:207], v[220:223], v[32:35]
	v_mfma_f32_16x16x32_bf16 v[20:23], v[192:195], v[228:231], v[20:23]
	v_mfma_f32_16x16x32_bf16 v[16:19], v[204:207], v[228:231], v[16:19]
	v_mfma_f32_16x16x32_bf16 v[4:7], v[192:195], v[238:241], v[4:7]
	v_mfma_f32_16x16x32_bf16 v[0:3], v[204:207], v[238:241], v[0:3]
	v_mfma_f32_16x16x32_bf16 v[52:55], v[196:199], v[216:219], v[52:55]
	v_mfma_f32_16x16x32_bf16 v[48:51], v[208:211], v[216:219], v[48:51]
	v_mfma_f32_16x16x32_bf16 v[36:39], v[196:199], v[224:227], v[36:39]
	v_mfma_f32_16x16x32_bf16 v[32:35], v[208:211], v[224:227], v[32:35]
	v_mfma_f32_16x16x32_bf16 v[20:23], v[196:199], v[234:237], v[20:23]
	v_mfma_f32_16x16x32_bf16 v[16:19], v[208:211], v[234:237], v[16:19]
	v_mfma_f32_16x16x32_bf16 v[4:7], v[196:199], v[242:245], v[4:7]
	v_mfma_f32_16x16x32_bf16 v[0:3], v[208:211], v[242:245], v[0:3]
	s_setprio 0
	s_barrier
	v_add_u32_e32 v128, s0, v173
	s_add_i32 s84, 0, 0x1c000
	ds_read_b128 v[174:177], v128
	ds_read_b128 v[180:183], v128 offset:1024
	ds_read_b128 v[184:187], v128 offset:2048
	ds_read_b128 v[188:191], v128 offset:3072
	v_add_u32_e32 v128, s84, v173
	ds_read_b128 v[192:195], v128
	ds_read_b128 v[196:199], v128 offset:1024
	ds_read_b128 v[204:207], v128 offset:2048
	ds_read_b128 v[208:211], v128 offset:3072
	s_add_u32 s60, s60, 0x40000
	s_addc_u32 s61, s61, 0
	s_mov_b32 m0, s77
	ds_read_b128 v[212:215], v203 offset:32768
	ds_read_b128 v[216:219], v203 offset:33792
	ds_read_b128 v[220:223], v203 offset:34816
	ds_read_b128 v[224:227], v203 offset:35840
	ds_read_b128 v[228:231], v203 offset:36864
	ds_read_b128 v[234:237], v203 offset:37888
	ds_read_b128 v[238:241], v203 offset:38912
	ds_read_b128 v[242:245], v203 offset:39936
	global_load_lds_dwordx4 v134, s[60:61]
	s_mov_b32 m0, s78
	s_nop 0
	global_load_lds_dwordx4 v138, s[60:61]
	s_waitcnt vmcnt(8)
	s_waitcnt lgkmcnt(0)
	s_barrier
	s_setprio 1
	s_waitcnt lgkmcnt(0)
	v_mfma_f32_16x16x32_bf16 v[124:127], v[174:177], v[212:215], v[124:127]
	v_mfma_f32_16x16x32_bf16 v[120:123], v[184:187], v[212:215], v[120:123]
	v_mfma_f32_16x16x32_bf16 v[108:111], v[174:177], v[220:223], v[108:111]
	v_mfma_f32_16x16x32_bf16 v[104:107], v[184:187], v[220:223], v[104:107]
	v_mfma_f32_16x16x32_bf16 v[92:95], v[174:177], v[228:231], v[92:95]
	v_mfma_f32_16x16x32_bf16 v[88:91], v[184:187], v[228:231], v[88:91]
	v_mfma_f32_16x16x32_bf16 v[76:79], v[174:177], v[238:241], v[76:79]
	v_mfma_f32_16x16x32_bf16 v[72:75], v[184:187], v[238:241], v[72:75]
	v_mfma_f32_16x16x32_bf16 v[124:127], v[180:183], v[216:219], v[124:127]
	v_mfma_f32_16x16x32_bf16 v[120:123], v[188:191], v[216:219], v[120:123]
	v_mfma_f32_16x16x32_bf16 v[108:111], v[180:183], v[224:227], v[108:111]
	v_mfma_f32_16x16x32_bf16 v[104:107], v[188:191], v[224:227], v[104:107]
	v_mfma_f32_16x16x32_bf16 v[92:95], v[180:183], v[234:237], v[92:95]
	v_mfma_f32_16x16x32_bf16 v[88:91], v[188:191], v[234:237], v[88:91]
	v_mfma_f32_16x16x32_bf16 v[76:79], v[180:183], v[242:245], v[76:79]
	v_mfma_f32_16x16x32_bf16 v[72:75], v[188:191], v[242:245], v[72:75]
	s_setprio 0
	s_setprio 1
	v_mfma_f32_16x16x32_bf16 v[116:119], v[192:195], v[212:215], v[116:119]
	v_mfma_f32_16x16x32_bf16 v[112:115], v[204:207], v[212:215], v[112:115]
	v_mfma_f32_16x16x32_bf16 v[100:103], v[192:195], v[220:223], v[100:103]
	v_mfma_f32_16x16x32_bf16 v[96:99], v[204:207], v[220:223], v[96:99]
	v_mfma_f32_16x16x32_bf16 v[84:87], v[192:195], v[228:231], v[84:87]
	v_mfma_f32_16x16x32_bf16 v[80:83], v[204:207], v[228:231], v[80:83]
	v_mfma_f32_16x16x32_bf16 v[68:71], v[192:195], v[238:241], v[68:71]
	v_mfma_f32_16x16x32_bf16 v[64:67], v[204:207], v[238:241], v[64:67]
	v_mfma_f32_16x16x32_bf16 v[116:119], v[196:199], v[216:219], v[116:119]
	v_mfma_f32_16x16x32_bf16 v[112:115], v[208:211], v[216:219], v[112:115]
	v_mfma_f32_16x16x32_bf16 v[100:103], v[196:199], v[224:227], v[100:103]
	v_mfma_f32_16x16x32_bf16 v[96:99], v[208:211], v[224:227], v[96:99]
	v_mfma_f32_16x16x32_bf16 v[84:87], v[196:199], v[234:237], v[84:87]
	v_mfma_f32_16x16x32_bf16 v[80:83], v[208:211], v[234:237], v[80:83]
	v_mfma_f32_16x16x32_bf16 v[68:71], v[196:199], v[242:245], v[68:71]
	v_mfma_f32_16x16x32_bf16 v[64:67], v[208:211], v[242:245], v[64:67]
	s_setprio 0
	s_barrier
	s_add_i32 s60, s0, s75
	s_add_u32 s98, s98, s12
	s_addc_u32 s99, s99, s13
	s_mov_b32 m0, s60
	ds_read_b128 v[212:215], v203 offset:49152
	ds_read_b128 v[216:219], v203 offset:50176
	ds_read_b128 v[220:223], v203 offset:51200
	ds_read_b128 v[224:227], v203 offset:52224
	ds_read_b128 v[228:231], v203 offset:53248
	ds_read_b128 v[234:237], v203 offset:54272
	ds_read_b128 v[238:241], v203 offset:55296
	ds_read_b128 v[242:245], v203 offset:56320
	global_load_lds_dwordx4 v136, s[98:99]
	s_add_i32 m0, s60, 0x2000
	s_add_u32 s48, s48, 0x40080
	s_addc_u32 s49, s49, 0
	s_add_i32 s60, s84, s75
	global_load_lds_dwordx4 v140, s[98:99]
	s_mov_b32 m0, s60
	s_nop 0
	global_load_lds_dwordx4 v136, s[48:49]
	s_add_i32 m0, s60, 0x2000
	s_nop 0
	global_load_lds_dwordx4 v140, s[48:49]
	s_add_u32 s100, s100, s12
	s_addc_u32 s101, s101, s13
	s_mov_b32 m0, s79
	s_nop 0
	global_load_lds_dwordx4 v134, s[100:101]
	s_mov_b32 m0, s80
	s_nop 0
	global_load_lds_dwordx4 v138, s[100:101]
	s_waitcnt vmcnt(8)
	s_waitcnt lgkmcnt(0)
	s_barrier
	s_setprio 1
	s_waitcnt lgkmcnt(0)
	v_mfma_f32_16x16x32_bf16 v[60:63], v[174:177], v[212:215], v[60:63]
	v_mfma_f32_16x16x32_bf16 v[56:59], v[184:187], v[212:215], v[56:59]
	v_mfma_f32_16x16x32_bf16 v[44:47], v[174:177], v[220:223], v[44:47]
	v_mfma_f32_16x16x32_bf16 v[40:43], v[184:187], v[220:223], v[40:43]
	v_mfma_f32_16x16x32_bf16 v[28:31], v[174:177], v[228:231], v[28:31]
	v_mfma_f32_16x16x32_bf16 v[24:27], v[184:187], v[228:231], v[24:27]
	v_mfma_f32_16x16x32_bf16 v[12:15], v[174:177], v[238:241], v[12:15]
	v_mfma_f32_16x16x32_bf16 v[8:11], v[184:187], v[238:241], v[8:11]
	v_mfma_f32_16x16x32_bf16 v[60:63], v[180:183], v[216:219], v[60:63]
	v_mfma_f32_16x16x32_bf16 v[56:59], v[188:191], v[216:219], v[56:59]
	v_mfma_f32_16x16x32_bf16 v[44:47], v[180:183], v[224:227], v[44:47]
	v_mfma_f32_16x16x32_bf16 v[40:43], v[188:191], v[224:227], v[40:43]
	v_mfma_f32_16x16x32_bf16 v[28:31], v[180:183], v[234:237], v[28:31]
	v_mfma_f32_16x16x32_bf16 v[24:27], v[188:191], v[234:237], v[24:27]
	v_mfma_f32_16x16x32_bf16 v[12:15], v[180:183], v[242:245], v[12:15]
	v_mfma_f32_16x16x32_bf16 v[8:11], v[188:191], v[242:245], v[8:11]
	s_setprio 0
	s_setprio 1
	v_mfma_f32_16x16x32_bf16 v[52:55], v[192:195], v[212:215], v[52:55]
	v_mfma_f32_16x16x32_bf16 v[48:51], v[204:207], v[212:215], v[48:51]
	v_mfma_f32_16x16x32_bf16 v[36:39], v[192:195], v[220:223], v[36:39]
	v_mfma_f32_16x16x32_bf16 v[32:35], v[204:207], v[220:223], v[32:35]
	v_mfma_f32_16x16x32_bf16 v[20:23], v[192:195], v[228:231], v[20:23]
	v_mfma_f32_16x16x32_bf16 v[16:19], v[204:207], v[228:231], v[16:19]
	v_mfma_f32_16x16x32_bf16 v[4:7], v[192:195], v[238:241], v[4:7]
	v_mfma_f32_16x16x32_bf16 v[0:3], v[204:207], v[238:241], v[0:3]
	v_mfma_f32_16x16x32_bf16 v[52:55], v[196:199], v[216:219], v[52:55]
	v_mfma_f32_16x16x32_bf16 v[48:51], v[208:211], v[216:219], v[48:51]
	v_mfma_f32_16x16x32_bf16 v[36:39], v[196:199], v[224:227], v[36:39]
	v_mfma_f32_16x16x32_bf16 v[32:35], v[208:211], v[224:227], v[32:35]
	v_mfma_f32_16x16x32_bf16 v[20:23], v[196:199], v[234:237], v[20:23]
	v_mfma_f32_16x16x32_bf16 v[16:19], v[208:211], v[234:237], v[16:19]
	v_mfma_f32_16x16x32_bf16 v[4:7], v[196:199], v[242:245], v[4:7]
	v_mfma_f32_16x16x32_bf16 v[0:3], v[208:211], v[242:245], v[0:3]
	s_setprio 0
	s_barrier
	s_add_i32 s67, s67, 2
	s_add_u32 s8, s8, 0x100
	s_addc_u32 s9, s9, 0
	s_add_u32 s65, s65, 0x100
	s_addc_u32 s66, s66, 0
	s_cmp_gt_u32 s67, 13
	s_cbranch_scc0 .LBB0_2520
	s_and_b64 vcc, exec, s[50:51]
	s_cbranch_vccz .LBB0_2523
	s_barrier

.LBB0_2602:
	s_add_u32 s56, s48, 0xfffe0080
	s_addc_u32 s57, s49, -1
	s_add_i32 s87, 0, 0x10000
	s_cmp_eq_u32 s86, 4
	s_cselect_b32 s61, s7, s57
	s_cselect_b32 s60, s51, s56
	s_cselect_b32 s57, s45, s85
	s_cselect_b32 s56, s62, s63
	s_add_i32 s90, 0, 0x14000
	v_add_u32_e32 v140, s87, v203
	v_add_u32_e32 v144, s90, v203
	ds_read_b128 v[128:131], v140
	ds_read_b128 v[132:135], v140 offset:1024
	ds_read_b128 v[136:139], v140 offset:2048
	ds_read_b128 v[140:143], v140 offset:3072
	ds_read_b128 v[172:175], v144
	ds_read_b128 v[176:179], v144 offset:1024
	ds_read_b128 v[180:183], v144 offset:2048
	ds_read_b128 v[184:187], v144 offset:3072
	s_add_i32 m0, s76, 0xc000
	ds_read_b128 v[188:191], v206
	ds_read_b128 v[208:211], v206 offset:1024
	ds_read_b128 v[212:215], v206 offset:2048
	ds_read_b128 v[216:219], v206 offset:3072
	ds_read_b128 v[220:223], v206 offset:4096
	ds_read_b128 v[224:227], v206 offset:5120
	ds_read_b128 v[228:231], v206 offset:6144
	ds_read_b128 v[234:237], v206 offset:7168
	global_load_lds_dwordx4 v166, s[48:49]
	s_add_i32 m0, s76, 0xe000
	s_nop 0
	global_load_lds_dwordx4 v168, s[48:49]
	s_waitcnt vmcnt(8)
	s_waitcnt lgkmcnt(0)
	s_barrier
	s_setprio 1
	s_waitcnt lgkmcnt(0)
	v_mfma_i32_16x16x64_i8 v[124:127], v[128:131], v[188:191], v[124:127]
	v_mfma_i32_16x16x64_i8 v[120:123], v[136:139], v[188:191], v[120:123]
	v_mfma_i32_16x16x64_i8 v[116:119], v[128:131], v[212:215], v[116:119]
	v_mfma_i32_16x16x64_i8 v[112:115], v[136:139], v[212:215], v[112:115]
	v_mfma_i32_16x16x64_i8 v[108:111], v[128:131], v[220:223], v[108:111]
	v_mfma_i32_16x16x64_i8 v[104:107], v[136:139], v[220:223], v[104:107]
	v_mfma_i32_16x16x64_i8 v[100:103], v[128:131], v[228:231], v[100:103]
	v_mfma_i32_16x16x64_i8 v[96:99], v[136:139], v[228:231], v[96:99]
	v_mfma_i32_16x16x64_i8 v[124:127], v[132:135], v[208:211], v[124:127]
	v_mfma_i32_16x16x64_i8 v[120:123], v[140:143], v[208:211], v[120:123]
	v_mfma_i32_16x16x64_i8 v[116:119], v[132:135], v[216:219], v[116:119]
	v_mfma_i32_16x16x64_i8 v[112:115], v[140:143], v[216:219], v[112:115]
	v_mfma_i32_16x16x64_i8 v[108:111], v[132:135], v[224:227], v[108:111]
	v_mfma_i32_16x16x64_i8 v[104:107], v[140:143], v[224:227], v[104:107]
	v_mfma_i32_16x16x64_i8 v[100:103], v[132:135], v[234:237], v[100:103]
	v_mfma_i32_16x16x64_i8 v[96:99], v[140:143], v[234:237], v[96:99]
	s_setprio 0
	s_setprio 1
	v_mfma_i32_16x16x64_i8 v[92:95], v[172:175], v[188:191], v[92:95]
	v_mfma_i32_16x16x64_i8 v[88:91], v[180:183], v[188:191], v[88:91]
	v_mfma_i32_16x16x64_i8 v[84:87], v[172:175], v[212:215], v[84:87]
	v_mfma_i32_16x16x64_i8 v[80:83], v[180:183], v[212:215], v[80:83]
	v_mfma_i32_16x16x64_i8 v[76:79], v[172:175], v[220:223], v[76:79]
	v_mfma_i32_16x16x64_i8 v[72:75], v[180:183], v[220:223], v[72:75]
	v_mfma_i32_16x16x64_i8 v[68:71], v[172:175], v[228:231], v[68:71]
	v_mfma_i32_16x16x64_i8 v[64:67], v[180:183], v[228:231], v[64:67]
	v_mfma_i32_16x16x64_i8 v[92:95], v[176:179], v[208:211], v[92:95]
	v_mfma_i32_16x16x64_i8 v[88:91], v[184:187], v[208:211], v[88:91]
	v_mfma_i32_16x16x64_i8 v[84:87], v[176:179], v[216:219], v[84:87]
	v_mfma_i32_16x16x64_i8 v[80:83], v[184:187], v[216:219], v[80:83]
	v_mfma_i32_16x16x64_i8 v[76:79], v[176:179], v[224:227], v[76:79]
	v_mfma_i32_16x16x64_i8 v[72:75], v[184:187], v[224:227], v[72:75]
	v_mfma_i32_16x16x64_i8 v[68:71], v[176:179], v[234:237], v[68:71]
	v_mfma_i32_16x16x64_i8 v[64:67], v[184:187], v[234:237], v[64:67]
	s_setprio 0
	s_barrier
	s_add_i32 s87, s87, s75
	s_mov_b64 s[98:99], s[56:57]
	s_mov_b32 m0, s87
	ds_read_b128 v[188:191], v206 offset:16384
	ds_read_b128 v[208:211], v206 offset:17408
	ds_read_b128 v[212:215], v206 offset:18432
	ds_read_b128 v[216:219], v206 offset:19456
	ds_read_b128 v[220:223], v206 offset:20480
	ds_read_b128 v[224:227], v206 offset:21504
	ds_read_b128 v[228:231], v206 offset:22528
	ds_read_b128 v[234:237], v206 offset:23552
	global_load_lds_dwordx4 v152, s[56:57]
	s_add_i32 m0, s87, 0x2000
	s_add_u32 s88, s56, 0x20000
	s_addc_u32 s89, s57, 0
	s_add_i32 s87, s90, s75
	global_load_lds_dwordx4 v156, s[56:57]
	s_mov_b32 m0, s87
	s_mov_b64 s[100:101], s[60:61]
	global_load_lds_dwordx4 v152, s[88:89]
	s_add_i32 m0, s87, 0x2000
	s_nop 0
	global_load_lds_dwordx4 v156, s[88:89]
	s_mov_b32 m0, s76
	s_nop 0
	global_load_lds_dwordx4 v150, s[60:61]
	s_mov_b32 m0, s77
	s_nop 0
	global_load_lds_dwordx4 v154, s[60:61]
	s_waitcnt vmcnt(8)
	s_waitcnt lgkmcnt(0)
	s_barrier
	s_setprio 1
	s_waitcnt lgkmcnt(0)
	v_mfma_i32_16x16x64_i8 v[60:63], v[128:131], v[188:191], v[60:63]
	v_mfma_i32_16x16x64_i8 v[56:59], v[136:139], v[188:191], v[56:59]
	v_mfma_i32_16x16x64_i8 v[52:55], v[128:131], v[212:215], v[52:55]
	v_mfma_i32_16x16x64_i8 v[48:51], v[136:139], v[212:215], v[48:51]
	v_mfma_i32_16x16x64_i8 v[44:47], v[128:131], v[220:223], v[44:47]
	v_mfma_i32_16x16x64_i8 v[40:43], v[136:139], v[220:223], v[40:43]
	v_mfma_i32_16x16x64_i8 v[36:39], v[128:131], v[228:231], v[36:39]
	v_mfma_i32_16x16x64_i8 v[32:35], v[136:139], v[228:231], v[32:35]
	v_mfma_i32_16x16x64_i8 v[60:63], v[132:135], v[208:211], v[60:63]
	v_mfma_i32_16x16x64_i8 v[56:59], v[140:143], v[208:211], v[56:59]
	v_mfma_i32_16x16x64_i8 v[52:55], v[132:135], v[216:219], v[52:55]
	v_mfma_i32_16x16x64_i8 v[48:51], v[140:143], v[216:219], v[48:51]
	v_mfma_i32_16x16x64_i8 v[44:47], v[132:135], v[224:227], v[44:47]
	v_mfma_i32_16x16x64_i8 v[40:43], v[140:143], v[224:227], v[40:43]
	v_mfma_i32_16x16x64_i8 v[36:39], v[132:135], v[234:237], v[36:39]
	v_mfma_i32_16x16x64_i8 v[32:35], v[140:143], v[234:237], v[32:35]
	s_setprio 0
	s_setprio 1
	v_mfma_i32_16x16x64_i8 v[28:31], v[172:175], v[188:191], v[28:31]
	v_mfma_i32_16x16x64_i8 v[24:27], v[180:183], v[188:191], v[24:27]
	v_mfma_i32_16x16x64_i8 v[20:23], v[172:175], v[212:215], v[20:23]
	v_mfma_i32_16x16x64_i8 v[16:19], v[180:183], v[212:215], v[16:19]
	v_mfma_i32_16x16x64_i8 v[12:15], v[172:175], v[220:223], v[12:15]
	v_mfma_i32_16x16x64_i8 v[8:11], v[180:183], v[220:223], v[8:11]
	v_mfma_i32_16x16x64_i8 v[4:7], v[172:175], v[228:231], v[4:7]
	v_mfma_i32_16x16x64_i8 v[0:3], v[180:183], v[228:231], v[0:3]
	v_mfma_i32_16x16x64_i8 v[28:31], v[176:179], v[208:211], v[28:31]
	v_mfma_i32_16x16x64_i8 v[24:27], v[184:187], v[208:211], v[24:27]
	v_mfma_i32_16x16x64_i8 v[20:23], v[176:179], v[216:219], v[20:23]
	v_mfma_i32_16x16x64_i8 v[16:19], v[184:187], v[216:219], v[16:19]
	v_mfma_i32_16x16x64_i8 v[12:15], v[176:179], v[224:227], v[12:15]
	v_mfma_i32_16x16x64_i8 v[8:11], v[184:187], v[224:227], v[8:11]
	v_mfma_i32_16x16x64_i8 v[4:7], v[176:179], v[234:237], v[4:7]
	v_mfma_i32_16x16x64_i8 v[0:3], v[184:187], v[234:237], v[0:3]
	s_setprio 0
	s_barrier
	s_add_i32 s87, 0, 0x1c000
	v_add_u32_e32 v140, s0, v203
	v_add_u32_e32 v144, s87, v203
	ds_read_b128 v[128:131], v140
	ds_read_b128 v[132:135], v140 offset:1024
	ds_read_b128 v[136:139], v140 offset:2048
	ds_read_b128 v[140:143], v140 offset:3072
	ds_read_b128 v[172:175], v144
	ds_read_b128 v[176:179], v144 offset:1024
	ds_read_b128 v[180:183], v144 offset:2048
	ds_read_b128 v[184:187], v144 offset:3072
	s_add_u32 s60, s60, 0x20000
	s_addc_u32 s61, s61, 0
	s_mov_b32 m0, s78
	ds_read_b128 v[188:191], v206 offset:32768
	ds_read_b128 v[208:211], v206 offset:33792
	ds_read_b128 v[212:215], v206 offset:34816
	ds_read_b128 v[216:219], v206 offset:35840
	ds_read_b128 v[220:223], v206 offset:36864
	ds_read_b128 v[224:227], v206 offset:37888
	ds_read_b128 v[228:231], v206 offset:38912
	ds_read_b128 v[234:237], v206 offset:39936
	global_load_lds_dwordx4 v150, s[60:61]
	s_mov_b32 m0, s79
	s_nop 0
	global_load_lds_dwordx4 v154, s[60:61]
	s_waitcnt vmcnt(8)
	s_waitcnt lgkmcnt(0)
	s_barrier
	s_setprio 1
	s_waitcnt lgkmcnt(0)
	v_mfma_i32_16x16x64_i8 v[124:127], v[128:131], v[188:191], v[124:127]
	v_mfma_i32_16x16x64_i8 v[120:123], v[136:139], v[188:191], v[120:123]
	v_mfma_i32_16x16x64_i8 v[116:119], v[128:131], v[212:215], v[116:119]
	v_mfma_i32_16x16x64_i8 v[112:115], v[136:139], v[212:215], v[112:115]
	v_mfma_i32_16x16x64_i8 v[108:111], v[128:131], v[220:223], v[108:111]
	v_mfma_i32_16x16x64_i8 v[104:107], v[136:139], v[220:223], v[104:107]
	v_mfma_i32_16x16x64_i8 v[100:103], v[128:131], v[228:231], v[100:103]
	v_mfma_i32_16x16x64_i8 v[96:99], v[136:139], v[228:231], v[96:99]
	v_mfma_i32_16x16x64_i8 v[124:127], v[132:135], v[208:211], v[124:127]
	v_mfma_i32_16x16x64_i8 v[120:123], v[140:143], v[208:211], v[120:123]
	v_mfma_i32_16x16x64_i8 v[116:119], v[132:135], v[216:219], v[116:119]
	v_mfma_i32_16x16x64_i8 v[112:115], v[140:143], v[216:219], v[112:115]
	v_mfma_i32_16x16x64_i8 v[108:111], v[132:135], v[224:227], v[108:111]
	v_mfma_i32_16x16x64_i8 v[104:107], v[140:143], v[224:227], v[104:107]
	v_mfma_i32_16x16x64_i8 v[100:103], v[132:135], v[234:237], v[100:103]
	v_mfma_i32_16x16x64_i8 v[96:99], v[140:143], v[234:237], v[96:99]
	s_setprio 0
	s_setprio 1
	v_mfma_i32_16x16x64_i8 v[92:95], v[172:175], v[188:191], v[92:95]
	v_mfma_i32_16x16x64_i8 v[88:91], v[180:183], v[188:191], v[88:91]
	v_mfma_i32_16x16x64_i8 v[84:87], v[172:175], v[212:215], v[84:87]
	v_mfma_i32_16x16x64_i8 v[80:83], v[180:183], v[212:215], v[80:83]
	v_mfma_i32_16x16x64_i8 v[76:79], v[172:175], v[220:223], v[76:79]
	v_mfma_i32_16x16x64_i8 v[72:75], v[180:183], v[220:223], v[72:75]
	v_mfma_i32_16x16x64_i8 v[68:71], v[172:175], v[228:231], v[68:71]
	v_mfma_i32_16x16x64_i8 v[64:67], v[180:183], v[228:231], v[64:67]
	v_mfma_i32_16x16x64_i8 v[92:95], v[176:179], v[208:211], v[92:95]
	v_mfma_i32_16x16x64_i8 v[88:91], v[184:187], v[208:211], v[88:91]
	v_mfma_i32_16x16x64_i8 v[84:87], v[176:179], v[216:219], v[84:87]
	v_mfma_i32_16x16x64_i8 v[80:83], v[184:187], v[216:219], v[80:83]
	v_mfma_i32_16x16x64_i8 v[76:79], v[176:179], v[224:227], v[76:79]
	v_mfma_i32_16x16x64_i8 v[72:75], v[184:187], v[224:227], v[72:75]
	v_mfma_i32_16x16x64_i8 v[68:71], v[176:179], v[234:237], v[68:71]
	v_mfma_i32_16x16x64_i8 v[64:67], v[184:187], v[234:237], v[64:67]
	s_setprio 0
	s_barrier
	s_add_i32 s60, s0, s75
	s_add_u32 s98, s98, s10
	s_addc_u32 s99, s99, s11
	s_mov_b32 m0, s60
	ds_read_b128 v[188:191], v206 offset:49152
	ds_read_b128 v[208:211], v206 offset:50176
	ds_read_b128 v[212:215], v206 offset:51200
	ds_read_b128 v[216:219], v206 offset:52224
	ds_read_b128 v[220:223], v206 offset:53248
	ds_read_b128 v[224:227], v206 offset:54272
	ds_read_b128 v[228:231], v206 offset:55296
	ds_read_b128 v[234:237], v206 offset:56320
	global_load_lds_dwordx4 v152, s[98:99]
	s_add_i32 m0, s60, 0x2000
	s_add_u32 s56, s56, 0x20080
	s_addc_u32 s57, s57, 0
	s_add_i32 s60, s87, s75
	global_load_lds_dwordx4 v156, s[98:99]
	s_mov_b32 m0, s60
	s_nop 0
	global_load_lds_dwordx4 v152, s[56:57]
	s_add_i32 m0, s60, 0x2000
	s_nop 0
	global_load_lds_dwordx4 v156, s[56:57]
	s_add_u32 s100, s100, s10
	s_addc_u32 s101, s101, s11
	s_mov_b32 m0, s80
	s_nop 0
	global_load_lds_dwordx4 v150, s[100:101]
	s_mov_b32 m0, s81
	s_nop 0
	global_load_lds_dwordx4 v154, s[100:101]
	s_waitcnt vmcnt(8)
	s_waitcnt lgkmcnt(0)
	s_barrier
	s_setprio 1
	s_waitcnt lgkmcnt(0)
	v_mfma_i32_16x16x64_i8 v[60:63], v[128:131], v[188:191], v[60:63]
	v_mfma_i32_16x16x64_i8 v[56:59], v[136:139], v[188:191], v[56:59]
	v_mfma_i32_16x16x64_i8 v[52:55], v[128:131], v[212:215], v[52:55]
	v_mfma_i32_16x16x64_i8 v[48:51], v[136:139], v[212:215], v[48:51]
	v_mfma_i32_16x16x64_i8 v[44:47], v[128:131], v[220:223], v[44:47]
	v_mfma_i32_16x16x64_i8 v[40:43], v[136:139], v[220:223], v[40:43]
	v_mfma_i32_16x16x64_i8 v[36:39], v[128:131], v[228:231], v[36:39]
	v_mfma_i32_16x16x64_i8 v[32:35], v[136:139], v[228:231], v[32:35]
	v_mfma_i32_16x16x64_i8 v[60:63], v[132:135], v[208:211], v[60:63]
	v_mfma_i32_16x16x64_i8 v[56:59], v[140:143], v[208:211], v[56:59]
	v_mfma_i32_16x16x64_i8 v[52:55], v[132:135], v[216:219], v[52:55]
	v_mfma_i32_16x16x64_i8 v[48:51], v[140:143], v[216:219], v[48:51]
	v_mfma_i32_16x16x64_i8 v[44:47], v[132:135], v[224:227], v[44:47]
	v_mfma_i32_16x16x64_i8 v[40:43], v[140:143], v[224:227], v[40:43]
	v_mfma_i32_16x16x64_i8 v[36:39], v[132:135], v[234:237], v[36:39]
	v_mfma_i32_16x16x64_i8 v[32:35], v[140:143], v[234:237], v[32:35]
	s_setprio 0
	s_setprio 1
	v_mfma_i32_16x16x64_i8 v[28:31], v[172:175], v[188:191], v[28:31]
	v_mfma_i32_16x16x64_i8 v[24:27], v[180:183], v[188:191], v[24:27]
	v_mfma_i32_16x16x64_i8 v[20:23], v[172:175], v[212:215], v[20:23]
	v_mfma_i32_16x16x64_i8 v[16:19], v[180:183], v[212:215], v[16:19]
	v_mfma_i32_16x16x64_i8 v[12:15], v[172:175], v[220:223], v[12:15]
	v_mfma_i32_16x16x64_i8 v[8:11], v[180:183], v[220:223], v[8:11]
	v_mfma_i32_16x16x64_i8 v[4:7], v[172:175], v[228:231], v[4:7]
	v_mfma_i32_16x16x64_i8 v[0:3], v[180:183], v[228:231], v[0:3]
	v_mfma_i32_16x16x64_i8 v[28:31], v[176:179], v[208:211], v[28:31]
	v_mfma_i32_16x16x64_i8 v[24:27], v[184:187], v[208:211], v[24:27]
	v_mfma_i32_16x16x64_i8 v[20:23], v[176:179], v[216:219], v[20:23]
	v_mfma_i32_16x16x64_i8 v[16:19], v[184:187], v[216:219], v[16:19]
	v_mfma_i32_16x16x64_i8 v[12:15], v[176:179], v[224:227], v[12:15]
	v_mfma_i32_16x16x64_i8 v[8:11], v[184:187], v[224:227], v[8:11]
	v_mfma_i32_16x16x64_i8 v[4:7], v[176:179], v[234:237], v[4:7]
	v_mfma_i32_16x16x64_i8 v[0:3], v[184:187], v[234:237], v[0:3]
	s_setprio 0
	s_barrier
	s_add_i32 s86, s86, 2
	s_add_u32 s48, s48, 0x100
	s_addc_u32 s49, s49, 0
	s_add_u32 s63, s63, 0x100
	s_addc_u32 s85, s85, 0
	s_cmp_gt_u32 s86, 5
	s_cbranch_scc0 .LBB0_2602
	s_and_b64 vcc, exec, s[42:43]
	s_cbranch_vccz .LBB0_2605
	s_barrier

.LBB0_2985:
	s_add_u32 s58, s56, 0xfffe0080
	s_addc_u32 s59, s57, -1
	s_add_i32 s85, 0, 0x10000
	s_cmp_eq_u32 s84, 4
	s_cselect_b32 s61, s51, s59
	s_cselect_b32 s60, s81, s58
	s_cselect_b32 s59, s43, s83
	s_cselect_b32 s58, s45, s82
	s_add_i32 s88, 0, 0x14000
	v_add_u32_e32 v150, s85, v182
	v_add_u32_e32 v154, s88, v182
	ds_read_b128 v[138:141], v150
	ds_read_b128 v[142:145], v150 offset:1024
	ds_read_b128 v[146:149], v150 offset:2048
	ds_read_b128 v[150:153], v150 offset:3072
	ds_read_b128 v[166:169], v154
	ds_read_b128 v[190:193], v154 offset:1024
	ds_read_b128 v[194:197], v154 offset:2048
	ds_read_b128 v[198:201], v154 offset:3072
	s_add_i32 m0, s12, 0xc000
	ds_read_b128 v[202:205], v185
	ds_read_b128 v[206:209], v185 offset:1024
	ds_read_b128 v[210:213], v185 offset:2048
	ds_read_b128 v[214:217], v185 offset:3072
	ds_read_b128 v[218:221], v185 offset:4096
	ds_read_b128 v[222:225], v185 offset:5120
	ds_read_b128 v[226:229], v185 offset:6144
	ds_read_b128 v[234:237], v185 offset:7168
	global_load_lds_dwordx4 v134, s[56:57]
	s_add_i32 m0, s12, 0xe000
	s_nop 0
	global_load_lds_dwordx4 v136, s[56:57]
	s_waitcnt vmcnt(8)
	s_waitcnt lgkmcnt(0)
	s_barrier
	s_setprio 1
	s_waitcnt lgkmcnt(0)
	v_mfma_i32_16x16x64_i8 v[126:129], v[138:141], v[202:205], v[126:129]
	v_mfma_i32_16x16x64_i8 v[122:125], v[146:149], v[202:205], v[122:125]
	v_mfma_i32_16x16x64_i8 v[110:113], v[138:141], v[210:213], v[110:113]
	v_mfma_i32_16x16x64_i8 v[106:109], v[146:149], v[210:213], v[106:109]
	v_mfma_i32_16x16x64_i8 v[94:97], v[138:141], v[218:221], v[94:97]
	v_mfma_i32_16x16x64_i8 v[90:93], v[146:149], v[218:221], v[90:93]
	v_mfma_i32_16x16x64_i8 v[78:81], v[138:141], v[226:229], v[78:81]
	v_mfma_i32_16x16x64_i8 v[74:77], v[146:149], v[226:229], v[74:77]
	v_mfma_i32_16x16x64_i8 v[126:129], v[142:145], v[206:209], v[126:129]
	v_mfma_i32_16x16x64_i8 v[122:125], v[150:153], v[206:209], v[122:125]
	v_mfma_i32_16x16x64_i8 v[110:113], v[142:145], v[214:217], v[110:113]
	v_mfma_i32_16x16x64_i8 v[106:109], v[150:153], v[214:217], v[106:109]
	v_mfma_i32_16x16x64_i8 v[94:97], v[142:145], v[222:225], v[94:97]
	v_mfma_i32_16x16x64_i8 v[90:93], v[150:153], v[222:225], v[90:93]
	v_mfma_i32_16x16x64_i8 v[78:81], v[142:145], v[234:237], v[78:81]
	v_mfma_i32_16x16x64_i8 v[74:77], v[150:153], v[234:237], v[74:77]
	s_setprio 0
	s_setprio 1
	v_mfma_i32_16x16x64_i8 v[118:121], v[166:169], v[202:205], v[118:121]
	v_mfma_i32_16x16x64_i8 v[114:117], v[194:197], v[202:205], v[114:117]
	v_mfma_i32_16x16x64_i8 v[102:105], v[166:169], v[210:213], v[102:105]
	v_mfma_i32_16x16x64_i8 v[98:101], v[194:197], v[210:213], v[98:101]
	v_mfma_i32_16x16x64_i8 v[86:89], v[166:169], v[218:221], v[86:89]
	v_mfma_i32_16x16x64_i8 v[82:85], v[194:197], v[218:221], v[82:85]
	v_mfma_i32_16x16x64_i8 v[70:73], v[166:169], v[226:229], v[70:73]
	v_mfma_i32_16x16x64_i8 v[66:69], v[194:197], v[226:229], v[66:69]
	v_mfma_i32_16x16x64_i8 v[118:121], v[190:193], v[206:209], v[118:121]
	v_mfma_i32_16x16x64_i8 v[114:117], v[198:201], v[206:209], v[114:117]
	v_mfma_i32_16x16x64_i8 v[102:105], v[190:193], v[214:217], v[102:105]
	v_mfma_i32_16x16x64_i8 v[98:101], v[198:201], v[214:217], v[98:101]
	v_mfma_i32_16x16x64_i8 v[86:89], v[190:193], v[222:225], v[86:89]
	v_mfma_i32_16x16x64_i8 v[82:85], v[198:201], v[222:225], v[82:85]
	v_mfma_i32_16x16x64_i8 v[70:73], v[190:193], v[234:237], v[70:73]
	v_mfma_i32_16x16x64_i8 v[66:69], v[198:201], v[234:237], v[66:69]
	s_setprio 0
	s_barrier
	s_add_i32 s85, s85, s71
	s_mov_b64 s[98:99], s[58:59]
	s_mov_b32 m0, s85
	ds_read_b128 v[202:205], v185 offset:16384
	ds_read_b128 v[206:209], v185 offset:17408
	ds_read_b128 v[210:213], v185 offset:18432
	ds_read_b128 v[214:217], v185 offset:19456
	ds_read_b128 v[218:221], v185 offset:20480
	ds_read_b128 v[222:225], v185 offset:21504
	ds_read_b128 v[226:229], v185 offset:22528
	ds_read_b128 v[234:237], v185 offset:23552
	global_load_lds_dwordx4 v0, s[58:59]
	s_add_i32 m0, s85, 0x2000
	s_add_u32 s86, s58, 0x20000
	s_addc_u32 s87, s59, 0
	s_add_i32 s85, s88, s71
	global_load_lds_dwordx4 v164, s[58:59]
	s_mov_b32 m0, s85
	s_mov_b64 s[100:101], s[60:61]
	global_load_lds_dwordx4 v0, s[86:87]
	s_add_i32 m0, s85, 0x2000
	s_nop 0
	global_load_lds_dwordx4 v164, s[86:87]
	s_mov_b32 m0, s12
	s_nop 0
	global_load_lds_dwordx4 v160, s[60:61]
	s_mov_b32 m0, s49
	s_nop 0
	global_load_lds_dwordx4 v162, s[60:61]
	s_waitcnt vmcnt(8)
	s_waitcnt lgkmcnt(0)
	s_barrier
	s_setprio 1
	s_waitcnt lgkmcnt(0)
	v_mfma_i32_16x16x64_i8 v[62:65], v[138:141], v[202:205], v[62:65]
	v_mfma_i32_16x16x64_i8 v[58:61], v[146:149], v[202:205], v[58:61]
	v_mfma_i32_16x16x64_i8 v[46:49], v[138:141], v[210:213], v[46:49]
	v_mfma_i32_16x16x64_i8 v[42:45], v[146:149], v[210:213], v[42:45]
	v_mfma_i32_16x16x64_i8 v[30:33], v[138:141], v[218:221], v[30:33]
	v_mfma_i32_16x16x64_i8 v[26:29], v[146:149], v[218:221], v[26:29]
	v_mfma_i32_16x16x64_i8 v[10:13], v[138:141], v[226:229], v[10:13]
	v_mfma_i32_16x16x64_i8 v[2:5], v[146:149], v[226:229], v[2:5]
	v_mfma_i32_16x16x64_i8 v[62:65], v[142:145], v[206:209], v[62:65]
	v_mfma_i32_16x16x64_i8 v[58:61], v[150:153], v[206:209], v[58:61]
	v_mfma_i32_16x16x64_i8 v[46:49], v[142:145], v[214:217], v[46:49]
	v_mfma_i32_16x16x64_i8 v[42:45], v[150:153], v[214:217], v[42:45]
	v_mfma_i32_16x16x64_i8 v[30:33], v[142:145], v[222:225], v[30:33]
	v_mfma_i32_16x16x64_i8 v[26:29], v[150:153], v[222:225], v[26:29]
	v_mfma_i32_16x16x64_i8 v[10:13], v[142:145], v[234:237], v[10:13]
	v_mfma_i32_16x16x64_i8 v[2:5], v[150:153], v[234:237], v[2:5]
	s_setprio 0
	s_setprio 1
	v_mfma_i32_16x16x64_i8 v[54:57], v[166:169], v[202:205], v[54:57]
	v_mfma_i32_16x16x64_i8 v[50:53], v[194:197], v[202:205], v[50:53]
	v_mfma_i32_16x16x64_i8 v[38:41], v[166:169], v[210:213], v[38:41]
	v_mfma_i32_16x16x64_i8 v[34:37], v[194:197], v[210:213], v[34:37]
	v_mfma_i32_16x16x64_i8 v[22:25], v[166:169], v[218:221], v[22:25]
	v_mfma_i32_16x16x64_i8 v[18:21], v[194:197], v[218:221], v[18:21]
	v_mfma_i32_16x16x64_i8 v[14:17], v[166:169], v[226:229], v[14:17]
	v_mfma_i32_16x16x64_i8 v[6:9], v[194:197], v[226:229], v[6:9]
	v_mfma_i32_16x16x64_i8 v[54:57], v[190:193], v[206:209], v[54:57]
	v_mfma_i32_16x16x64_i8 v[50:53], v[198:201], v[206:209], v[50:53]
	v_mfma_i32_16x16x64_i8 v[38:41], v[190:193], v[214:217], v[38:41]
	v_mfma_i32_16x16x64_i8 v[34:37], v[198:201], v[214:217], v[34:37]
	v_mfma_i32_16x16x64_i8 v[22:25], v[190:193], v[222:225], v[22:25]
	v_mfma_i32_16x16x64_i8 v[18:21], v[198:201], v[222:225], v[18:21]
	v_mfma_i32_16x16x64_i8 v[14:17], v[190:193], v[234:237], v[14:17]
	v_mfma_i32_16x16x64_i8 v[6:9], v[198:201], v[234:237], v[6:9]
	s_setprio 0
	s_barrier
	s_add_i32 s85, 0, 0x18000
	s_add_i32 s86, 0, 0x1c000
	v_add_u32_e32 v150, s85, v182
	v_add_u32_e32 v189, s86, v182
	ds_read_b128 v[138:141], v150
	ds_read_b128 v[142:145], v150 offset:1024
	ds_read_b128 v[146:149], v150 offset:2048
	ds_read_b128 v[150:153], v150 offset:3072
	ds_read_b128 v[166:169], v189
	ds_read_b128 v[190:193], v189 offset:1024
	ds_read_b128 v[194:197], v189 offset:2048
	ds_read_b128 v[198:201], v189 offset:3072
	s_add_u32 s60, s60, 0x20000
	s_addc_u32 s61, s61, 0
	s_mov_b32 m0, s72
	ds_read_b128 v[202:205], v185 offset:32768
	ds_read_b128 v[206:209], v185 offset:33792
	ds_read_b128 v[210:213], v185 offset:34816
	ds_read_b128 v[214:217], v185 offset:35840
	ds_read_b128 v[218:221], v185 offset:36864
	ds_read_b128 v[222:225], v185 offset:37888
	ds_read_b128 v[226:229], v185 offset:38912
	ds_read_b128 v[234:237], v185 offset:39936
	global_load_lds_dwordx4 v160, s[60:61]
	s_mov_b32 m0, s73
	s_nop 0
	global_load_lds_dwordx4 v162, s[60:61]
	s_waitcnt vmcnt(8)
	s_waitcnt lgkmcnt(0)
	s_barrier
	s_setprio 1
	s_waitcnt lgkmcnt(0)
	v_mfma_i32_16x16x64_i8 v[126:129], v[138:141], v[202:205], v[126:129]
	v_mfma_i32_16x16x64_i8 v[122:125], v[146:149], v[202:205], v[122:125]
	v_mfma_i32_16x16x64_i8 v[110:113], v[138:141], v[210:213], v[110:113]
	v_mfma_i32_16x16x64_i8 v[106:109], v[146:149], v[210:213], v[106:109]
	v_mfma_i32_16x16x64_i8 v[94:97], v[138:141], v[218:221], v[94:97]
	v_mfma_i32_16x16x64_i8 v[90:93], v[146:149], v[218:221], v[90:93]
	v_mfma_i32_16x16x64_i8 v[78:81], v[138:141], v[226:229], v[78:81]
	v_mfma_i32_16x16x64_i8 v[74:77], v[146:149], v[226:229], v[74:77]
	v_mfma_i32_16x16x64_i8 v[126:129], v[142:145], v[206:209], v[126:129]
	v_mfma_i32_16x16x64_i8 v[122:125], v[150:153], v[206:209], v[122:125]
	v_mfma_i32_16x16x64_i8 v[110:113], v[142:145], v[214:217], v[110:113]
	v_mfma_i32_16x16x64_i8 v[106:109], v[150:153], v[214:217], v[106:109]
	v_mfma_i32_16x16x64_i8 v[94:97], v[142:145], v[222:225], v[94:97]
	v_mfma_i32_16x16x64_i8 v[90:93], v[150:153], v[222:225], v[90:93]
	v_mfma_i32_16x16x64_i8 v[78:81], v[142:145], v[234:237], v[78:81]
	v_mfma_i32_16x16x64_i8 v[74:77], v[150:153], v[234:237], v[74:77]
	s_setprio 0
	s_setprio 1
	v_mfma_i32_16x16x64_i8 v[118:121], v[166:169], v[202:205], v[118:121]
	v_mfma_i32_16x16x64_i8 v[114:117], v[194:197], v[202:205], v[114:117]
	v_mfma_i32_16x16x64_i8 v[102:105], v[166:169], v[210:213], v[102:105]
	v_mfma_i32_16x16x64_i8 v[98:101], v[194:197], v[210:213], v[98:101]
	v_mfma_i32_16x16x64_i8 v[86:89], v[166:169], v[218:221], v[86:89]
	v_mfma_i32_16x16x64_i8 v[82:85], v[194:197], v[218:221], v[82:85]
	v_mfma_i32_16x16x64_i8 v[70:73], v[166:169], v[226:229], v[70:73]
	v_mfma_i32_16x16x64_i8 v[66:69], v[194:197], v[226:229], v[66:69]
	v_mfma_i32_16x16x64_i8 v[118:121], v[190:193], v[206:209], v[118:121]
	v_mfma_i32_16x16x64_i8 v[114:117], v[198:201], v[206:209], v[114:117]
	v_mfma_i32_16x16x64_i8 v[102:105], v[190:193], v[214:217], v[102:105]
	v_mfma_i32_16x16x64_i8 v[98:101], v[198:201], v[214:217], v[98:101]
	v_mfma_i32_16x16x64_i8 v[86:89], v[190:193], v[222:225], v[86:89]
	v_mfma_i32_16x16x64_i8 v[82:85], v[198:201], v[222:225], v[82:85]
	v_mfma_i32_16x16x64_i8 v[70:73], v[190:193], v[234:237], v[70:73]
	v_mfma_i32_16x16x64_i8 v[66:69], v[198:201], v[234:237], v[66:69]
	s_setprio 0
	s_barrier
	s_add_i32 s60, s85, s71
	s_add_u32 s98, s98, s14
	s_addc_u32 s99, s99, s15
	s_mov_b32 m0, s60
	ds_read_b128 v[202:205], v185 offset:49152
	ds_read_b128 v[206:209], v185 offset:50176
	ds_read_b128 v[210:213], v185 offset:51200
	ds_read_b128 v[214:217], v185 offset:52224
	ds_read_b128 v[218:221], v185 offset:53248
	ds_read_b128 v[222:225], v185 offset:54272
	ds_read_b128 v[226:229], v185 offset:55296
	ds_read_b128 v[234:237], v185 offset:56320
	global_load_lds_dwordx4 v0, s[98:99]
	s_add_i32 m0, s60, 0x2000
	s_add_u32 s58, s58, 0x20080
	s_addc_u32 s59, s59, 0
	s_add_i32 s60, s86, s71
	global_load_lds_dwordx4 v164, s[98:99]
	s_mov_b32 m0, s60
	s_nop 0
	global_load_lds_dwordx4 v0, s[58:59]
	s_add_i32 m0, s60, 0x2000
	s_nop 0
	global_load_lds_dwordx4 v164, s[58:59]
	s_add_u32 s100, s100, s14
	s_addc_u32 s101, s101, s15
	s_mov_b32 m0, s74
	s_nop 0
	global_load_lds_dwordx4 v160, s[100:101]
	s_mov_b32 m0, s75
	s_nop 0
	global_load_lds_dwordx4 v162, s[100:101]
	s_waitcnt vmcnt(8)
	s_waitcnt lgkmcnt(0)
	s_barrier
	s_setprio 1
	s_waitcnt lgkmcnt(0)
	v_mfma_i32_16x16x64_i8 v[62:65], v[138:141], v[202:205], v[62:65]
	v_mfma_i32_16x16x64_i8 v[58:61], v[146:149], v[202:205], v[58:61]
	v_mfma_i32_16x16x64_i8 v[46:49], v[138:141], v[210:213], v[46:49]
	v_mfma_i32_16x16x64_i8 v[42:45], v[146:149], v[210:213], v[42:45]
	v_mfma_i32_16x16x64_i8 v[30:33], v[138:141], v[218:221], v[30:33]
	v_mfma_i32_16x16x64_i8 v[26:29], v[146:149], v[218:221], v[26:29]
	v_mfma_i32_16x16x64_i8 v[10:13], v[138:141], v[226:229], v[10:13]
	v_mfma_i32_16x16x64_i8 v[2:5], v[146:149], v[226:229], v[2:5]
	v_mfma_i32_16x16x64_i8 v[62:65], v[142:145], v[206:209], v[62:65]
	v_mfma_i32_16x16x64_i8 v[58:61], v[150:153], v[206:209], v[58:61]
	v_mfma_i32_16x16x64_i8 v[46:49], v[142:145], v[214:217], v[46:49]
	v_mfma_i32_16x16x64_i8 v[42:45], v[150:153], v[214:217], v[42:45]
	v_mfma_i32_16x16x64_i8 v[30:33], v[142:145], v[222:225], v[30:33]
	v_mfma_i32_16x16x64_i8 v[26:29], v[150:153], v[222:225], v[26:29]
	v_mfma_i32_16x16x64_i8 v[10:13], v[142:145], v[234:237], v[10:13]
	v_mfma_i32_16x16x64_i8 v[2:5], v[150:153], v[234:237], v[2:5]
	s_setprio 0
	s_setprio 1
	v_mfma_i32_16x16x64_i8 v[54:57], v[166:169], v[202:205], v[54:57]
	v_mfma_i32_16x16x64_i8 v[50:53], v[194:197], v[202:205], v[50:53]
	v_mfma_i32_16x16x64_i8 v[38:41], v[166:169], v[210:213], v[38:41]
	v_mfma_i32_16x16x64_i8 v[34:37], v[194:197], v[210:213], v[34:37]
	v_mfma_i32_16x16x64_i8 v[22:25], v[166:169], v[218:221], v[22:25]
	v_mfma_i32_16x16x64_i8 v[18:21], v[194:197], v[218:221], v[18:21]
	v_mfma_i32_16x16x64_i8 v[14:17], v[166:169], v[226:229], v[14:17]
	v_mfma_i32_16x16x64_i8 v[6:9], v[194:197], v[226:229], v[6:9]
	v_mfma_i32_16x16x64_i8 v[54:57], v[190:193], v[206:209], v[54:57]
	v_mfma_i32_16x16x64_i8 v[50:53], v[198:201], v[206:209], v[50:53]
	v_mfma_i32_16x16x64_i8 v[38:41], v[190:193], v[214:217], v[38:41]
	v_mfma_i32_16x16x64_i8 v[34:37], v[198:201], v[214:217], v[34:37]
	v_mfma_i32_16x16x64_i8 v[22:25], v[190:193], v[222:225], v[22:25]
	v_mfma_i32_16x16x64_i8 v[18:21], v[198:201], v[222:225], v[18:21]
	v_mfma_i32_16x16x64_i8 v[14:17], v[190:193], v[234:237], v[14:17]
	v_mfma_i32_16x16x64_i8 v[6:9], v[198:201], v[234:237], v[6:9]
	s_setprio 0
	s_barrier
	s_add_i32 s84, s84, 2
	s_add_u32 s56, s56, 0x100
	s_addc_u32 s57, s57, 0
	s_add_u32 s82, s82, 0x100
	s_addc_u32 s83, s83, 0
	s_cmp_gt_u32 s84, 5
	s_cbranch_scc0 .LBB0_2985
	s_and_b64 vcc, exec, s[40:41]
	s_cbranch_vccz .LBB0_2988
	s_barrier

.LBB0_3015:
	s_add_u32 s8, s6, 0xfffe0080
	s_addc_u32 s9, s7, -1
	s_add_i32 s72, 0, 0x10000
	s_cmp_eq_u32 s71, 4
	s_cselect_b32 s55, s43, s9
	s_cselect_b32 s54, s49, s8
	v_add_u32_e32 v0, s72, v188
	s_cselect_b32 s9, s39, s70
	s_cselect_b32 s8, s41, s69
	s_add_i32 s74, 0, 0x14000
	ds_read_b128 v[132:135], v0
	ds_read_b128 v[136:139], v0 offset:1024
	ds_read_b128 v[140:143], v0 offset:2048
	ds_read_b128 v[144:147], v0 offset:3072
	v_add_u32_e32 v0, s74, v188
	ds_read_b128 v[148:151], v0
	ds_read_b128 v[152:155], v0 offset:1024
	ds_read_b128 v[176:179], v0 offset:2048
	ds_read_b128 v[180:183], v0 offset:3072
	s_add_i32 m0, s45, 0xc000
	ds_read_b128 v[198:201], v196
	ds_read_b128 v[202:205], v196 offset:1024
	ds_read_b128 v[206:209], v196 offset:2048
	ds_read_b128 v[210:213], v196 offset:3072
	ds_read_b128 v[214:217], v196 offset:4096
	ds_read_b128 v[218:221], v196 offset:5120
	ds_read_b128 v[222:225], v196 offset:6144
	ds_read_b128 v[226:229], v196 offset:7168
	global_load_lds_dwordx4 v172, s[6:7]
	s_add_i32 m0, s45, 0xe000
	s_nop 0
	global_load_lds_dwordx4 v174, s[6:7]
	s_waitcnt vmcnt(8)
	s_waitcnt lgkmcnt(0)
	s_barrier
	s_setprio 1
	s_waitcnt lgkmcnt(0)
	v_mfma_f32_16x16x32_bf16 v[128:131], v[132:135], v[198:201], v[128:131]
	v_mfma_f32_16x16x32_bf16 v[124:127], v[140:143], v[198:201], v[124:127]
	v_mfma_f32_16x16x32_bf16 v[120:123], v[132:135], v[206:209], v[120:123]
	v_mfma_f32_16x16x32_bf16 v[116:119], v[140:143], v[206:209], v[116:119]
	v_mfma_f32_16x16x32_bf16 v[112:115], v[132:135], v[214:217], v[112:115]
	v_mfma_f32_16x16x32_bf16 v[108:111], v[140:143], v[214:217], v[108:111]
	v_mfma_f32_16x16x32_bf16 v[104:107], v[132:135], v[222:225], v[104:107]
	v_mfma_f32_16x16x32_bf16 v[100:103], v[140:143], v[222:225], v[100:103]
	v_mfma_f32_16x16x32_bf16 v[128:131], v[136:139], v[202:205], v[128:131]
	v_mfma_f32_16x16x32_bf16 v[124:127], v[144:147], v[202:205], v[124:127]
	v_mfma_f32_16x16x32_bf16 v[120:123], v[136:139], v[210:213], v[120:123]
	v_mfma_f32_16x16x32_bf16 v[116:119], v[144:147], v[210:213], v[116:119]
	v_mfma_f32_16x16x32_bf16 v[112:115], v[136:139], v[218:221], v[112:115]
	v_mfma_f32_16x16x32_bf16 v[108:111], v[144:147], v[218:221], v[108:111]
	v_mfma_f32_16x16x32_bf16 v[104:107], v[136:139], v[226:229], v[104:107]
	v_mfma_f32_16x16x32_bf16 v[100:103], v[144:147], v[226:229], v[100:103]
	s_setprio 0
	s_setprio 1
	v_mfma_f32_16x16x32_bf16 v[96:99], v[148:151], v[198:201], v[96:99]
	v_mfma_f32_16x16x32_bf16 v[92:95], v[176:179], v[198:201], v[92:95]
	v_mfma_f32_16x16x32_bf16 v[88:91], v[148:151], v[206:209], v[88:91]
	v_mfma_f32_16x16x32_bf16 v[84:87], v[176:179], v[206:209], v[84:87]
	v_mfma_f32_16x16x32_bf16 v[80:83], v[148:151], v[214:217], v[80:83]
	v_mfma_f32_16x16x32_bf16 v[76:79], v[176:179], v[214:217], v[76:79]
	v_mfma_f32_16x16x32_bf16 v[72:75], v[148:151], v[222:225], v[72:75]
	v_mfma_f32_16x16x32_bf16 v[68:71], v[176:179], v[222:225], v[68:71]
	v_mfma_f32_16x16x32_bf16 v[96:99], v[152:155], v[202:205], v[96:99]
	v_mfma_f32_16x16x32_bf16 v[92:95], v[180:183], v[202:205], v[92:95]
	v_mfma_f32_16x16x32_bf16 v[88:91], v[152:155], v[210:213], v[88:91]
	v_mfma_f32_16x16x32_bf16 v[84:87], v[180:183], v[210:213], v[84:87]
	v_mfma_f32_16x16x32_bf16 v[80:83], v[152:155], v[218:221], v[80:83]
	v_mfma_f32_16x16x32_bf16 v[76:79], v[180:183], v[218:221], v[76:79]
	v_mfma_f32_16x16x32_bf16 v[72:75], v[152:155], v[226:229], v[72:75]
	v_mfma_f32_16x16x32_bf16 v[68:71], v[180:183], v[226:229], v[68:71]
	s_setprio 0
	s_barrier
	s_add_i32 s72, s72, s60
	s_mov_b64 s[98:99], s[8:9]
	s_mov_b32 m0, s72
	ds_read_b128 v[198:201], v196 offset:16384
	ds_read_b128 v[202:205], v196 offset:17408
	ds_read_b128 v[206:209], v196 offset:18432
	ds_read_b128 v[210:213], v196 offset:19456
	ds_read_b128 v[214:217], v196 offset:20480
	ds_read_b128 v[218:221], v196 offset:21504
	ds_read_b128 v[222:225], v196 offset:22528
	ds_read_b128 v[226:229], v196 offset:23552
	global_load_lds_dwordx4 v166, s[8:9]
	s_add_i32 m0, s72, 0x2000
	s_add_u32 s72, s8, 0x20000
	s_addc_u32 s73, s9, 0
	s_add_i32 s74, s74, s60
	global_load_lds_dwordx4 v164, s[8:9]
	s_mov_b32 m0, s74
	s_mov_b64 s[100:101], s[54:55]
	global_load_lds_dwordx4 v166, s[72:73]
	s_add_i32 m0, s74, 0x2000
	s_nop 0
	global_load_lds_dwordx4 v164, s[72:73]
	s_mov_b32 m0, s45
	s_nop 0
	global_load_lds_dwordx4 v160, s[54:55]
	s_mov_b32 m0, s61
	s_nop 0
	global_load_lds_dwordx4 v162, s[54:55]
	s_waitcnt vmcnt(8)
	s_waitcnt lgkmcnt(0)
	s_barrier
	s_setprio 1
	s_waitcnt lgkmcnt(0)
	v_mfma_f32_16x16x32_bf16 v[64:67], v[132:135], v[198:201], v[64:67]
	v_mfma_f32_16x16x32_bf16 v[60:63], v[140:143], v[198:201], v[60:63]
	v_mfma_f32_16x16x32_bf16 v[56:59], v[132:135], v[206:209], v[56:59]
	v_mfma_f32_16x16x32_bf16 v[52:55], v[140:143], v[206:209], v[52:55]
	v_mfma_f32_16x16x32_bf16 v[48:51], v[132:135], v[214:217], v[48:51]
	v_mfma_f32_16x16x32_bf16 v[44:47], v[140:143], v[214:217], v[44:47]
	v_mfma_f32_16x16x32_bf16 v[40:43], v[132:135], v[222:225], v[40:43]
	v_mfma_f32_16x16x32_bf16 v[36:39], v[140:143], v[222:225], v[36:39]
	v_mfma_f32_16x16x32_bf16 v[64:67], v[136:139], v[202:205], v[64:67]
	v_mfma_f32_16x16x32_bf16 v[60:63], v[144:147], v[202:205], v[60:63]
	v_mfma_f32_16x16x32_bf16 v[56:59], v[136:139], v[210:213], v[56:59]
	v_mfma_f32_16x16x32_bf16 v[52:55], v[144:147], v[210:213], v[52:55]
	v_mfma_f32_16x16x32_bf16 v[48:51], v[136:139], v[218:221], v[48:51]
	v_mfma_f32_16x16x32_bf16 v[44:47], v[144:147], v[218:221], v[44:47]
	v_mfma_f32_16x16x32_bf16 v[40:43], v[136:139], v[226:229], v[40:43]
	v_mfma_f32_16x16x32_bf16 v[36:39], v[144:147], v[226:229], v[36:39]
	s_setprio 0
	s_setprio 1
	v_mfma_f32_16x16x32_bf16 v[32:35], v[148:151], v[198:201], v[32:35]
	v_mfma_f32_16x16x32_bf16 v[28:31], v[176:179], v[198:201], v[28:31]
	v_mfma_f32_16x16x32_bf16 v[24:27], v[148:151], v[206:209], v[24:27]
	v_mfma_f32_16x16x32_bf16 v[20:23], v[176:179], v[206:209], v[20:23]
	v_mfma_f32_16x16x32_bf16 v[16:19], v[148:151], v[214:217], v[16:19]
	v_mfma_f32_16x16x32_bf16 v[12:15], v[176:179], v[214:217], v[12:15]
	v_mfma_f32_16x16x32_bf16 v[8:11], v[148:151], v[222:225], v[8:11]
	v_mfma_f32_16x16x32_bf16 v[2:5], v[176:179], v[222:225], v[4:7]
	v_mfma_f32_16x16x32_bf16 v[32:35], v[152:155], v[202:205], v[32:35]
	v_mfma_f32_16x16x32_bf16 v[28:31], v[180:183], v[202:205], v[28:31]
	v_mfma_f32_16x16x32_bf16 v[24:27], v[152:155], v[210:213], v[24:27]
	v_mfma_f32_16x16x32_bf16 v[20:23], v[180:183], v[210:213], v[20:23]
	v_mfma_f32_16x16x32_bf16 v[16:19], v[152:155], v[218:221], v[16:19]
	v_mfma_f32_16x16x32_bf16 v[12:15], v[180:183], v[218:221], v[12:15]
	v_mfma_f32_16x16x32_bf16 v[8:11], v[152:155], v[226:229], v[8:11]
	v_mfma_f32_16x16x32_bf16 v[2:5], v[180:183], v[226:229], v[2:5]
	s_setprio 0
	s_barrier
	s_add_i32 s72, 0, 0x18000
	v_add_u32_e32 v0, s72, v188
	s_add_i32 s73, 0, 0x1c000
	ds_read_b128 v[132:135], v0
	ds_read_b128 v[136:139], v0 offset:1024
	ds_read_b128 v[140:143], v0 offset:2048
	ds_read_b128 v[144:147], v0 offset:3072
	v_add_u32_e32 v0, s73, v188
	ds_read_b128 v[148:151], v0
	ds_read_b128 v[152:155], v0 offset:1024
	ds_read_b128 v[176:179], v0 offset:2048
	ds_read_b128 v[180:183], v0 offset:3072
	s_add_u32 s54, s54, 0x20000
	s_addc_u32 s55, s55, 0
	s_mov_b32 m0, s62
	ds_read_b128 v[198:201], v196 offset:32768
	ds_read_b128 v[202:205], v196 offset:33792
	ds_read_b128 v[206:209], v196 offset:34816
	ds_read_b128 v[210:213], v196 offset:35840
	ds_read_b128 v[214:217], v196 offset:36864
	ds_read_b128 v[218:221], v196 offset:37888
	ds_read_b128 v[222:225], v196 offset:38912
	ds_read_b128 v[226:229], v196 offset:39936
	global_load_lds_dwordx4 v160, s[54:55]
	s_mov_b32 m0, s63
	s_nop 0
	global_load_lds_dwordx4 v162, s[54:55]
	s_waitcnt vmcnt(8)
	s_waitcnt lgkmcnt(0)
	s_barrier
	s_setprio 1
	s_waitcnt lgkmcnt(0)
	v_mfma_f32_16x16x32_bf16 v[128:131], v[132:135], v[198:201], v[128:131]
	v_mfma_f32_16x16x32_bf16 v[124:127], v[140:143], v[198:201], v[124:127]
	v_mfma_f32_16x16x32_bf16 v[120:123], v[132:135], v[206:209], v[120:123]
	v_mfma_f32_16x16x32_bf16 v[116:119], v[140:143], v[206:209], v[116:119]
	v_mfma_f32_16x16x32_bf16 v[112:115], v[132:135], v[214:217], v[112:115]
	v_mfma_f32_16x16x32_bf16 v[108:111], v[140:143], v[214:217], v[108:111]
	v_mfma_f32_16x16x32_bf16 v[104:107], v[132:135], v[222:225], v[104:107]
	v_mfma_f32_16x16x32_bf16 v[100:103], v[140:143], v[222:225], v[100:103]
	v_mfma_f32_16x16x32_bf16 v[128:131], v[136:139], v[202:205], v[128:131]
	v_mfma_f32_16x16x32_bf16 v[124:127], v[144:147], v[202:205], v[124:127]
	v_mfma_f32_16x16x32_bf16 v[120:123], v[136:139], v[210:213], v[120:123]
	v_mfma_f32_16x16x32_bf16 v[116:119], v[144:147], v[210:213], v[116:119]
	v_mfma_f32_16x16x32_bf16 v[112:115], v[136:139], v[218:221], v[112:115]
	v_mfma_f32_16x16x32_bf16 v[108:111], v[144:147], v[218:221], v[108:111]
	v_mfma_f32_16x16x32_bf16 v[104:107], v[136:139], v[226:229], v[104:107]
	v_mfma_f32_16x16x32_bf16 v[100:103], v[144:147], v[226:229], v[100:103]
	s_setprio 0
	s_setprio 1
	v_mfma_f32_16x16x32_bf16 v[96:99], v[148:151], v[198:201], v[96:99]
	v_mfma_f32_16x16x32_bf16 v[92:95], v[176:179], v[198:201], v[92:95]
	v_mfma_f32_16x16x32_bf16 v[88:91], v[148:151], v[206:209], v[88:91]
	v_mfma_f32_16x16x32_bf16 v[84:87], v[176:179], v[206:209], v[84:87]
	v_mfma_f32_16x16x32_bf16 v[80:83], v[148:151], v[214:217], v[80:83]
	v_mfma_f32_16x16x32_bf16 v[76:79], v[176:179], v[214:217], v[76:79]
	v_mfma_f32_16x16x32_bf16 v[72:75], v[148:151], v[222:225], v[72:75]
	v_mfma_f32_16x16x32_bf16 v[68:71], v[176:179], v[222:225], v[68:71]
	v_mfma_f32_16x16x32_bf16 v[96:99], v[152:155], v[202:205], v[96:99]
	v_mfma_f32_16x16x32_bf16 v[92:95], v[180:183], v[202:205], v[92:95]
	v_mfma_f32_16x16x32_bf16 v[88:91], v[152:155], v[210:213], v[88:91]
	v_mfma_f32_16x16x32_bf16 v[84:87], v[180:183], v[210:213], v[84:87]
	v_mfma_f32_16x16x32_bf16 v[80:83], v[152:155], v[218:221], v[80:83]
	v_mfma_f32_16x16x32_bf16 v[76:79], v[180:183], v[218:221], v[76:79]
	v_mfma_f32_16x16x32_bf16 v[72:75], v[152:155], v[226:229], v[72:75]
	v_mfma_f32_16x16x32_bf16 v[68:71], v[180:183], v[226:229], v[68:71]
	s_setprio 0
	s_barrier
	s_add_i32 s54, s72, s60
	s_add_u32 s98, s98, s14
	s_addc_u32 s99, s99, s15
	s_mov_b32 m0, s54
	ds_read_b128 v[198:201], v196 offset:49152
	ds_read_b128 v[202:205], v196 offset:50176
	ds_read_b128 v[206:209], v196 offset:51200
	ds_read_b128 v[210:213], v196 offset:52224
	ds_read_b128 v[214:217], v196 offset:53248
	ds_read_b128 v[218:221], v196 offset:54272
	ds_read_b128 v[222:225], v196 offset:55296
	ds_read_b128 v[226:229], v196 offset:56320
	global_load_lds_dwordx4 v166, s[98:99]
	s_add_i32 m0, s54, 0x2000
	s_add_u32 s8, s8, 0x20080
	s_addc_u32 s9, s9, 0
	s_add_i32 s54, s73, s60
	global_load_lds_dwordx4 v164, s[98:99]
	s_mov_b32 m0, s54
	s_nop 0
	global_load_lds_dwordx4 v166, s[8:9]
	s_add_i32 m0, s54, 0x2000
	s_nop 0
	global_load_lds_dwordx4 v164, s[8:9]
	s_add_u32 s100, s100, s14
	s_addc_u32 s101, s101, s15
	s_mov_b32 m0, s65
	s_nop 0
	global_load_lds_dwordx4 v160, s[100:101]
	s_mov_b32 m0, s66
	s_nop 0
	global_load_lds_dwordx4 v162, s[100:101]
	s_waitcnt vmcnt(8)
	s_waitcnt lgkmcnt(0)
	s_barrier
	s_setprio 1
	s_waitcnt lgkmcnt(0)
	v_mfma_f32_16x16x32_bf16 v[64:67], v[132:135], v[198:201], v[64:67]
	v_mfma_f32_16x16x32_bf16 v[60:63], v[140:143], v[198:201], v[60:63]
	v_mfma_f32_16x16x32_bf16 v[56:59], v[132:135], v[206:209], v[56:59]
	v_mfma_f32_16x16x32_bf16 v[52:55], v[140:143], v[206:209], v[52:55]
	v_mfma_f32_16x16x32_bf16 v[48:51], v[132:135], v[214:217], v[48:51]
	v_mfma_f32_16x16x32_bf16 v[44:47], v[140:143], v[214:217], v[44:47]
	v_mfma_f32_16x16x32_bf16 v[40:43], v[132:135], v[222:225], v[40:43]
	v_mfma_f32_16x16x32_bf16 v[36:39], v[140:143], v[222:225], v[36:39]
	v_mfma_f32_16x16x32_bf16 v[64:67], v[136:139], v[202:205], v[64:67]
	v_mfma_f32_16x16x32_bf16 v[60:63], v[144:147], v[202:205], v[60:63]
	v_mfma_f32_16x16x32_bf16 v[56:59], v[136:139], v[210:213], v[56:59]
	v_mfma_f32_16x16x32_bf16 v[52:55], v[144:147], v[210:213], v[52:55]
	v_mfma_f32_16x16x32_bf16 v[48:51], v[136:139], v[218:221], v[48:51]
	v_mfma_f32_16x16x32_bf16 v[44:47], v[144:147], v[218:221], v[44:47]
	v_mfma_f32_16x16x32_bf16 v[40:43], v[136:139], v[226:229], v[40:43]
	v_mfma_f32_16x16x32_bf16 v[36:39], v[144:147], v[226:229], v[36:39]
	s_setprio 0
	s_setprio 1
	v_mfma_f32_16x16x32_bf16 v[32:35], v[148:151], v[198:201], v[32:35]
	v_mfma_f32_16x16x32_bf16 v[28:31], v[176:179], v[198:201], v[28:31]
	v_mfma_f32_16x16x32_bf16 v[24:27], v[148:151], v[206:209], v[24:27]
	v_mfma_f32_16x16x32_bf16 v[20:23], v[176:179], v[206:209], v[20:23]
	v_mfma_f32_16x16x32_bf16 v[16:19], v[148:151], v[214:217], v[16:19]
	v_mfma_f32_16x16x32_bf16 v[12:15], v[176:179], v[214:217], v[12:15]
	v_mfma_f32_16x16x32_bf16 v[6:9], v[148:151], v[222:225], v[8:11]
	v_mfma_f32_16x16x32_bf16 v[2:5], v[176:179], v[222:225], v[2:5]
	v_mfma_f32_16x16x32_bf16 v[32:35], v[152:155], v[202:205], v[32:35]
	v_mfma_f32_16x16x32_bf16 v[28:31], v[180:183], v[202:205], v[28:31]
	v_mfma_f32_16x16x32_bf16 v[24:27], v[152:155], v[210:213], v[24:27]
	v_mfma_f32_16x16x32_bf16 v[20:23], v[180:183], v[210:213], v[20:23]
	v_mfma_f32_16x16x32_bf16 v[16:19], v[152:155], v[218:221], v[16:19]
	v_mfma_f32_16x16x32_bf16 v[12:15], v[180:183], v[218:221], v[12:15]
	v_mfma_f32_16x16x32_bf16 v[8:11], v[152:155], v[226:229], v[6:9]
	v_mfma_f32_16x16x32_bf16 v[4:7], v[180:183], v[226:229], v[2:5]
	s_setprio 0
	s_barrier
	s_add_i32 s71, s71, 2
	s_add_u32 s6, s6, 0x100
	s_addc_u32 s7, s7, 0
	s_add_u32 s69, s69, 0x100
	s_addc_u32 s70, s70, 0
	s_cmp_gt_u32 s71, 5
	s_cbranch_scc0 .LBB0_3015
	s_and_b64 vcc, exec, s[36:37]
	s_cbranch_vccz .LBB0_3018
	s_barrier

.LBB0_3227:
	s_add_u32 s58, s48, 0xfffc0080
	s_addc_u32 s59, s49, -1
	s_add_i32 s64, 0, 0x10000
	s_cmp_eq_u32 s63, 12
	s_cselect_b32 s61, s14, s59
	s_cselect_b32 s60, s45, s58
	v_add_u32_e32 v0, s64, v169
	s_cselect_b32 s59, s43, s62
	s_cselect_b32 s58, s55, s57
	s_add_i32 s66, 0, 0x14000
	ds_read_b128 v[148:151], v0
	ds_read_b128 v[152:155], v0 offset:1024
	ds_read_b128 v[156:159], v0 offset:2048
	ds_read_b128 v[190:193], v0 offset:3072
	v_add_u32_e32 v0, s66, v169
	ds_read_b128 v[194:197], v0
	ds_read_b128 v[198:201], v0 offset:1024
	ds_read_b128 v[202:205], v0 offset:2048
	ds_read_b128 v[206:209], v0 offset:3072
	s_add_i32 m0, s80, 0xc000
	ds_read_b128 v[210:213], v188
	ds_read_b128 v[214:217], v188 offset:1024
	ds_read_b128 v[218:221], v188 offset:2048
	ds_read_b128 v[222:225], v188 offset:3072
	ds_read_b128 v[226:229], v188 offset:4096
	ds_read_b128 v[234:237], v188 offset:5120
	ds_read_b128 v[238:241], v188 offset:6144
	ds_read_b128 v[242:245], v188 offset:7168
	global_load_lds_dwordx4 v144, s[48:49]
	s_add_i32 m0, s80, 0xe000
	s_nop 0
	global_load_lds_dwordx4 v146, s[48:49]
	s_waitcnt vmcnt(8)
	s_waitcnt lgkmcnt(0)
	s_barrier
	s_setprio 1
	s_waitcnt lgkmcnt(0)
	v_mfma_f32_16x16x32_bf16 v[126:129], v[148:151], v[210:213], v[126:129]
	v_mfma_f32_16x16x32_bf16 v[122:125], v[156:159], v[210:213], v[122:125]
	v_mfma_f32_16x16x32_bf16 v[110:113], v[148:151], v[218:221], v[110:113]
	v_mfma_f32_16x16x32_bf16 v[106:109], v[156:159], v[218:221], v[106:109]
	v_mfma_f32_16x16x32_bf16 v[94:97], v[148:151], v[226:229], v[94:97]
	v_mfma_f32_16x16x32_bf16 v[90:93], v[156:159], v[226:229], v[90:93]
	v_mfma_f32_16x16x32_bf16 v[78:81], v[148:151], v[238:241], v[78:81]
	v_mfma_f32_16x16x32_bf16 v[74:77], v[156:159], v[238:241], v[74:77]
	v_mfma_f32_16x16x32_bf16 v[126:129], v[152:155], v[214:217], v[126:129]
	v_mfma_f32_16x16x32_bf16 v[122:125], v[190:193], v[214:217], v[122:125]
	v_mfma_f32_16x16x32_bf16 v[110:113], v[152:155], v[222:225], v[110:113]
	v_mfma_f32_16x16x32_bf16 v[106:109], v[190:193], v[222:225], v[106:109]
	v_mfma_f32_16x16x32_bf16 v[94:97], v[152:155], v[234:237], v[94:97]
	v_mfma_f32_16x16x32_bf16 v[90:93], v[190:193], v[234:237], v[90:93]
	v_mfma_f32_16x16x32_bf16 v[78:81], v[152:155], v[242:245], v[78:81]
	v_mfma_f32_16x16x32_bf16 v[74:77], v[190:193], v[242:245], v[74:77]
	s_setprio 0
	s_setprio 1
	v_mfma_f32_16x16x32_bf16 v[118:121], v[194:197], v[210:213], v[118:121]
	v_mfma_f32_16x16x32_bf16 v[114:117], v[202:205], v[210:213], v[114:117]
	v_mfma_f32_16x16x32_bf16 v[102:105], v[194:197], v[218:221], v[102:105]
	v_mfma_f32_16x16x32_bf16 v[98:101], v[202:205], v[218:221], v[98:101]
	v_mfma_f32_16x16x32_bf16 v[86:89], v[194:197], v[226:229], v[86:89]
	v_mfma_f32_16x16x32_bf16 v[82:85], v[202:205], v[226:229], v[82:85]
	v_mfma_f32_16x16x32_bf16 v[70:73], v[194:197], v[238:241], v[70:73]
	v_mfma_f32_16x16x32_bf16 v[66:69], v[202:205], v[238:241], v[66:69]
	v_mfma_f32_16x16x32_bf16 v[118:121], v[198:201], v[214:217], v[118:121]
	v_mfma_f32_16x16x32_bf16 v[114:117], v[206:209], v[214:217], v[114:117]
	v_mfma_f32_16x16x32_bf16 v[102:105], v[198:201], v[222:225], v[102:105]
	v_mfma_f32_16x16x32_bf16 v[98:101], v[206:209], v[222:225], v[98:101]
	v_mfma_f32_16x16x32_bf16 v[86:89], v[198:201], v[234:237], v[86:89]
	v_mfma_f32_16x16x32_bf16 v[82:85], v[206:209], v[234:237], v[82:85]
	v_mfma_f32_16x16x32_bf16 v[70:73], v[198:201], v[242:245], v[70:73]
	v_mfma_f32_16x16x32_bf16 v[66:69], v[206:209], v[242:245], v[66:69]
	s_setprio 0
	s_barrier
	s_add_i32 s64, s64, s79
	s_mov_b64 s[98:99], s[58:59]
	s_mov_b32 m0, s64
	ds_read_b128 v[210:213], v188 offset:16384
	ds_read_b128 v[214:217], v188 offset:17408
	ds_read_b128 v[218:221], v188 offset:18432
	ds_read_b128 v[222:225], v188 offset:19456
	ds_read_b128 v[226:229], v188 offset:20480
	ds_read_b128 v[234:237], v188 offset:21504
	ds_read_b128 v[238:241], v188 offset:22528
	ds_read_b128 v[242:245], v188 offset:23552
	global_load_lds_dwordx4 v136, s[58:59]
	s_add_i32 m0, s64, 0x2000
	s_add_u32 s64, s58, 0x40000
	s_addc_u32 s65, s59, 0
	s_add_i32 s66, s66, s79
	global_load_lds_dwordx4 v140, s[58:59]
	s_mov_b32 m0, s66
	s_mov_b64 s[100:101], s[60:61]
	global_load_lds_dwordx4 v136, s[64:65]
	s_add_i32 m0, s66, 0x2000
	s_nop 0
	global_load_lds_dwordx4 v140, s[64:65]
	s_mov_b32 m0, s80
	s_nop 0
	global_load_lds_dwordx4 v134, s[60:61]
	s_mov_b32 m0, s81
	s_nop 0
	global_load_lds_dwordx4 v138, s[60:61]
	s_waitcnt vmcnt(8)
	s_waitcnt lgkmcnt(0)
	s_barrier
	s_setprio 1
	s_waitcnt lgkmcnt(0)
	v_mfma_f32_16x16x32_bf16 v[62:65], v[148:151], v[210:213], v[62:65]
	v_mfma_f32_16x16x32_bf16 v[58:61], v[156:159], v[210:213], v[58:61]
	v_mfma_f32_16x16x32_bf16 v[46:49], v[148:151], v[218:221], v[46:49]
	v_mfma_f32_16x16x32_bf16 v[42:45], v[156:159], v[218:221], v[42:45]
	v_mfma_f32_16x16x32_bf16 v[30:33], v[148:151], v[226:229], v[30:33]
	v_mfma_f32_16x16x32_bf16 v[26:29], v[156:159], v[226:229], v[26:29]
	v_mfma_f32_16x16x32_bf16 v[14:17], v[148:151], v[238:241], v[14:17]
	v_mfma_f32_16x16x32_bf16 v[10:13], v[156:159], v[238:241], v[10:13]
	v_mfma_f32_16x16x32_bf16 v[62:65], v[152:155], v[214:217], v[62:65]
	v_mfma_f32_16x16x32_bf16 v[58:61], v[190:193], v[214:217], v[58:61]
	v_mfma_f32_16x16x32_bf16 v[46:49], v[152:155], v[222:225], v[46:49]
	v_mfma_f32_16x16x32_bf16 v[42:45], v[190:193], v[222:225], v[42:45]
	v_mfma_f32_16x16x32_bf16 v[30:33], v[152:155], v[234:237], v[30:33]
	v_mfma_f32_16x16x32_bf16 v[26:29], v[190:193], v[234:237], v[26:29]
	v_mfma_f32_16x16x32_bf16 v[14:17], v[152:155], v[242:245], v[14:17]
	v_mfma_f32_16x16x32_bf16 v[10:13], v[190:193], v[242:245], v[10:13]
	s_setprio 0
	s_setprio 1
	v_mfma_f32_16x16x32_bf16 v[54:57], v[194:197], v[210:213], v[54:57]
	v_mfma_f32_16x16x32_bf16 v[50:53], v[202:205], v[210:213], v[50:53]
	v_mfma_f32_16x16x32_bf16 v[38:41], v[194:197], v[218:221], v[38:41]
	v_mfma_f32_16x16x32_bf16 v[34:37], v[202:205], v[218:221], v[34:37]
	v_mfma_f32_16x16x32_bf16 v[22:25], v[194:197], v[226:229], v[22:25]
	v_mfma_f32_16x16x32_bf16 v[18:21], v[202:205], v[226:229], v[18:21]
	v_mfma_f32_16x16x32_bf16 v[6:9], v[194:197], v[238:241], v[6:9]
	v_mfma_f32_16x16x32_bf16 v[2:5], v[202:205], v[238:241], v[2:5]
	v_mfma_f32_16x16x32_bf16 v[54:57], v[198:201], v[214:217], v[54:57]
	v_mfma_f32_16x16x32_bf16 v[50:53], v[206:209], v[214:217], v[50:53]
	v_mfma_f32_16x16x32_bf16 v[38:41], v[198:201], v[222:225], v[38:41]
	v_mfma_f32_16x16x32_bf16 v[34:37], v[206:209], v[222:225], v[34:37]
	v_mfma_f32_16x16x32_bf16 v[22:25], v[198:201], v[234:237], v[22:25]
	v_mfma_f32_16x16x32_bf16 v[18:21], v[206:209], v[234:237], v[18:21]
	v_mfma_f32_16x16x32_bf16 v[6:9], v[198:201], v[242:245], v[6:9]
	v_mfma_f32_16x16x32_bf16 v[2:5], v[206:209], v[242:245], v[2:5]
	s_setprio 0
	s_barrier
	s_add_i32 s64, 0, 0x18000
	v_add_u32_e32 v0, s64, v169
	s_add_i32 s65, 0, 0x1c000
	ds_read_b128 v[148:151], v0
	ds_read_b128 v[152:155], v0 offset:1024
	ds_read_b128 v[156:159], v0 offset:2048
	ds_read_b128 v[190:193], v0 offset:3072
	v_add_u32_e32 v0, s65, v169
	ds_read_b128 v[194:197], v0
	ds_read_b128 v[198:201], v0 offset:1024
	ds_read_b128 v[202:205], v0 offset:2048
	ds_read_b128 v[206:209], v0 offset:3072
	s_add_u32 s60, s60, 0x40000
	s_addc_u32 s61, s61, 0
	s_mov_b32 m0, s82
	ds_read_b128 v[210:213], v188 offset:32768
	ds_read_b128 v[214:217], v188 offset:33792
	ds_read_b128 v[218:221], v188 offset:34816
	ds_read_b128 v[222:225], v188 offset:35840
	ds_read_b128 v[226:229], v188 offset:36864
	ds_read_b128 v[234:237], v188 offset:37888
	ds_read_b128 v[238:241], v188 offset:38912
	ds_read_b128 v[242:245], v188 offset:39936
	global_load_lds_dwordx4 v134, s[60:61]
	s_mov_b32 m0, s83
	s_nop 0
	global_load_lds_dwordx4 v138, s[60:61]
	s_waitcnt vmcnt(8)
	s_waitcnt lgkmcnt(0)
	s_barrier
	s_setprio 1
	s_waitcnt lgkmcnt(0)
	v_mfma_f32_16x16x32_bf16 v[126:129], v[148:151], v[210:213], v[126:129]
	v_mfma_f32_16x16x32_bf16 v[122:125], v[156:159], v[210:213], v[122:125]
	v_mfma_f32_16x16x32_bf16 v[110:113], v[148:151], v[218:221], v[110:113]
	v_mfma_f32_16x16x32_bf16 v[106:109], v[156:159], v[218:221], v[106:109]
	v_mfma_f32_16x16x32_bf16 v[94:97], v[148:151], v[226:229], v[94:97]
	v_mfma_f32_16x16x32_bf16 v[90:93], v[156:159], v[226:229], v[90:93]
	v_mfma_f32_16x16x32_bf16 v[78:81], v[148:151], v[238:241], v[78:81]
	v_mfma_f32_16x16x32_bf16 v[74:77], v[156:159], v[238:241], v[74:77]
	v_mfma_f32_16x16x32_bf16 v[126:129], v[152:155], v[214:217], v[126:129]
	v_mfma_f32_16x16x32_bf16 v[122:125], v[190:193], v[214:217], v[122:125]
	v_mfma_f32_16x16x32_bf16 v[110:113], v[152:155], v[222:225], v[110:113]
	v_mfma_f32_16x16x32_bf16 v[106:109], v[190:193], v[222:225], v[106:109]
	v_mfma_f32_16x16x32_bf16 v[94:97], v[152:155], v[234:237], v[94:97]
	v_mfma_f32_16x16x32_bf16 v[90:93], v[190:193], v[234:237], v[90:93]
	v_mfma_f32_16x16x32_bf16 v[78:81], v[152:155], v[242:245], v[78:81]
	v_mfma_f32_16x16x32_bf16 v[74:77], v[190:193], v[242:245], v[74:77]
	s_setprio 0
	s_setprio 1
	v_mfma_f32_16x16x32_bf16 v[118:121], v[194:197], v[210:213], v[118:121]
	v_mfma_f32_16x16x32_bf16 v[114:117], v[202:205], v[210:213], v[114:117]
	v_mfma_f32_16x16x32_bf16 v[102:105], v[194:197], v[218:221], v[102:105]
	v_mfma_f32_16x16x32_bf16 v[98:101], v[202:205], v[218:221], v[98:101]
	v_mfma_f32_16x16x32_bf16 v[86:89], v[194:197], v[226:229], v[86:89]
	v_mfma_f32_16x16x32_bf16 v[82:85], v[202:205], v[226:229], v[82:85]
	v_mfma_f32_16x16x32_bf16 v[70:73], v[194:197], v[238:241], v[70:73]
	v_mfma_f32_16x16x32_bf16 v[66:69], v[202:205], v[238:241], v[66:69]
	v_mfma_f32_16x16x32_bf16 v[118:121], v[198:201], v[214:217], v[118:121]
	v_mfma_f32_16x16x32_bf16 v[114:117], v[206:209], v[214:217], v[114:117]
	v_mfma_f32_16x16x32_bf16 v[102:105], v[198:201], v[222:225], v[102:105]
	v_mfma_f32_16x16x32_bf16 v[98:101], v[206:209], v[222:225], v[98:101]
	v_mfma_f32_16x16x32_bf16 v[86:89], v[198:201], v[234:237], v[86:89]
	v_mfma_f32_16x16x32_bf16 v[82:85], v[206:209], v[234:237], v[82:85]
	v_mfma_f32_16x16x32_bf16 v[70:73], v[198:201], v[242:245], v[70:73]
	v_mfma_f32_16x16x32_bf16 v[66:69], v[206:209], v[242:245], v[66:69]
	s_setprio 0
	s_barrier
	s_add_i32 s60, s64, s79
	s_add_u32 s98, s98, s16
	s_addc_u32 s99, s99, s17
	s_mov_b32 m0, s60
	ds_read_b128 v[210:213], v188 offset:49152
	ds_read_b128 v[214:217], v188 offset:50176
	ds_read_b128 v[218:221], v188 offset:51200
	ds_read_b128 v[222:225], v188 offset:52224
	ds_read_b128 v[226:229], v188 offset:53248
	ds_read_b128 v[234:237], v188 offset:54272
	ds_read_b128 v[238:241], v188 offset:55296
	ds_read_b128 v[242:245], v188 offset:56320
	global_load_lds_dwordx4 v136, s[98:99]
	s_add_i32 m0, s60, 0x2000
	s_add_u32 s58, s58, 0x40080
	s_addc_u32 s59, s59, 0
	s_add_i32 s60, s65, s79
	global_load_lds_dwordx4 v140, s[98:99]
	s_mov_b32 m0, s60
	s_nop 0
	global_load_lds_dwordx4 v136, s[58:59]
	s_add_i32 m0, s60, 0x2000
	s_nop 0
	global_load_lds_dwordx4 v140, s[58:59]
	s_add_u32 s100, s100, s16
	s_addc_u32 s101, s101, s17
	s_mov_b32 m0, s86
	s_nop 0
	global_load_lds_dwordx4 v134, s[100:101]
	s_mov_b32 m0, s87
	s_nop 0
	global_load_lds_dwordx4 v138, s[100:101]
	s_waitcnt vmcnt(8)
	s_waitcnt lgkmcnt(0)
	s_barrier
	s_setprio 1
	s_waitcnt lgkmcnt(0)
	v_mfma_f32_16x16x32_bf16 v[62:65], v[148:151], v[210:213], v[62:65]
	v_mfma_f32_16x16x32_bf16 v[58:61], v[156:159], v[210:213], v[58:61]
	v_mfma_f32_16x16x32_bf16 v[46:49], v[148:151], v[218:221], v[46:49]
	v_mfma_f32_16x16x32_bf16 v[42:45], v[156:159], v[218:221], v[42:45]
	v_mfma_f32_16x16x32_bf16 v[30:33], v[148:151], v[226:229], v[30:33]
	v_mfma_f32_16x16x32_bf16 v[26:29], v[156:159], v[226:229], v[26:29]
	v_mfma_f32_16x16x32_bf16 v[14:17], v[148:151], v[238:241], v[14:17]
	v_mfma_f32_16x16x32_bf16 v[10:13], v[156:159], v[238:241], v[10:13]
	v_mfma_f32_16x16x32_bf16 v[62:65], v[152:155], v[214:217], v[62:65]
	v_mfma_f32_16x16x32_bf16 v[58:61], v[190:193], v[214:217], v[58:61]
	v_mfma_f32_16x16x32_bf16 v[46:49], v[152:155], v[222:225], v[46:49]
	v_mfma_f32_16x16x32_bf16 v[42:45], v[190:193], v[222:225], v[42:45]
	v_mfma_f32_16x16x32_bf16 v[30:33], v[152:155], v[234:237], v[30:33]
	v_mfma_f32_16x16x32_bf16 v[26:29], v[190:193], v[234:237], v[26:29]
	v_mfma_f32_16x16x32_bf16 v[14:17], v[152:155], v[242:245], v[14:17]
	v_mfma_f32_16x16x32_bf16 v[10:13], v[190:193], v[242:245], v[10:13]
	s_setprio 0
	s_setprio 1
	v_mfma_f32_16x16x32_bf16 v[54:57], v[194:197], v[210:213], v[54:57]
	v_mfma_f32_16x16x32_bf16 v[50:53], v[202:205], v[210:213], v[50:53]
	v_mfma_f32_16x16x32_bf16 v[38:41], v[194:197], v[218:221], v[38:41]
	v_mfma_f32_16x16x32_bf16 v[34:37], v[202:205], v[218:221], v[34:37]
	v_mfma_f32_16x16x32_bf16 v[22:25], v[194:197], v[226:229], v[22:25]
	v_mfma_f32_16x16x32_bf16 v[18:21], v[202:205], v[226:229], v[18:21]
	v_mfma_f32_16x16x32_bf16 v[6:9], v[194:197], v[238:241], v[6:9]
	v_mfma_f32_16x16x32_bf16 v[2:5], v[202:205], v[238:241], v[2:5]
	v_mfma_f32_16x16x32_bf16 v[54:57], v[198:201], v[214:217], v[54:57]
	v_mfma_f32_16x16x32_bf16 v[50:53], v[206:209], v[214:217], v[50:53]
	v_mfma_f32_16x16x32_bf16 v[38:41], v[198:201], v[222:225], v[38:41]
	v_mfma_f32_16x16x32_bf16 v[34:37], v[206:209], v[222:225], v[34:37]
	v_mfma_f32_16x16x32_bf16 v[22:25], v[198:201], v[234:237], v[22:25]
	v_mfma_f32_16x16x32_bf16 v[18:21], v[206:209], v[234:237], v[18:21]
	v_mfma_f32_16x16x32_bf16 v[6:9], v[198:201], v[242:245], v[6:9]
	v_mfma_f32_16x16x32_bf16 v[2:5], v[206:209], v[242:245], v[2:5]
	s_setprio 0
	s_barrier
	s_add_i32 s63, s63, 2
	s_add_u32 s48, s48, 0x100
	s_addc_u32 s49, s49, 0
	s_add_u32 s57, s57, 0x100
	s_addc_u32 s62, s62, 0
	s_cmp_gt_u32 s63, 13
	s_cbranch_scc0 .LBB0_3227
	s_and_b64 vcc, exec, s[36:37]
	s_cbranch_vccz .LBB0_3231
	s_barrier
	s_andn2_b64 vcc, exec, s[20:21]
	s_cbranch_vccz .LBB0_3232

.LBB0_3542:
	s_add_u32 s56, s54, 0xfffe0080
	s_addc_u32 s57, s55, -1
	s_cmp_eq_u32 s97, 4
	s_cselect_b32 s59, s39, s57
	s_cselect_b32 s58, s93, s56
	s_cselect_b32 s57, s37, s96
	s_cselect_b32 s56, s94, s95
	s_mov_b32 m0, s51
	s_mov_b64 s[98:99], s[56:57]
	s_add_u32 vcc_lo, s56, 0x20000
	global_load_lds_dwordx4 v200, s[56:57]
	s_mov_b32 m0, s73
	s_addc_u32 vcc_hi, s57, 0
	global_load_lds_dwordx4 v204, s[56:57]
	v_lshl_add_u64 v[216:217], vcc, 0, v[200:201]
	s_mov_b32 m0, s74
	s_mov_b64 s[100:101], s[58:59]
	global_load_lds_dwordx4 v[216:217], off
	v_lshl_add_u64 v[216:217], vcc, 0, v[204:205]
	s_mov_b32 m0, s75
	s_and_b64 vcc, exec, s[4:5]
	global_load_lds_dwordx4 v[216:217], off
	s_mov_b32 m0, s49
	s_nop 0
	global_load_lds_dwordx4 v198, s[58:59]
	s_mov_b32 m0, s76
	s_nop 0
	global_load_lds_dwordx4 v202, s[58:59]
	s_waitcnt vmcnt(8)
	s_waitcnt lgkmcnt(0)
	s_barrier
	s_cbranch_vccnz .LBB0_3544
	s_setprio 1
	s_waitcnt lgkmcnt(0)
	v_mfma_i32_16x16x64_i8 v[96:99], v[180:183], v[4:7], v[96:99]
	v_mfma_i32_16x16x64_i8 v[88:91], v[188:191], v[4:7], v[88:91]
	v_mfma_i32_16x16x64_i8 v[80:83], v[180:183], v[12:15], v[80:83]
	v_mfma_i32_16x16x64_i8 v[72:75], v[188:191], v[12:15], v[72:75]
	v_mfma_i32_16x16x64_i8 v[64:67], v[180:183], v[20:23], v[64:67]
	v_mfma_i32_16x16x64_i8 v[56:59], v[188:191], v[20:23], v[56:59]
	v_mfma_i32_16x16x64_i8 v[48:51], v[180:183], v[28:31], v[48:51]
	v_mfma_i32_16x16x64_i8 v[40:43], v[188:191], v[28:31], v[40:43]
	v_mfma_i32_16x16x64_i8 v[96:99], v[184:187], v[8:11], v[96:99]
	v_mfma_i32_16x16x64_i8 v[88:91], v[192:195], v[8:11], v[88:91]
	v_mfma_i32_16x16x64_i8 v[80:83], v[184:187], v[16:19], v[80:83]
	v_mfma_i32_16x16x64_i8 v[72:75], v[192:195], v[16:19], v[72:75]
	v_mfma_i32_16x16x64_i8 v[64:67], v[184:187], v[24:27], v[64:67]
	v_mfma_i32_16x16x64_i8 v[56:59], v[192:195], v[24:27], v[56:59]
	v_mfma_i32_16x16x64_i8 v[48:51], v[184:187], v[32:35], v[48:51]
	v_mfma_i32_16x16x64_i8 v[40:43], v[192:195], v[32:35], v[40:43]
	s_setprio 0
	s_setprio 1
	v_mfma_i32_16x16x64_i8 v[92:95], v[108:111], v[4:7], v[92:95]
	v_mfma_i32_16x16x64_i8 v[84:87], v[124:127], v[4:7], v[84:87]
	v_mfma_i32_16x16x64_i8 v[76:79], v[108:111], v[12:15], v[76:79]
	v_mfma_i32_16x16x64_i8 v[68:71], v[124:127], v[12:15], v[68:71]
	v_mfma_i32_16x16x64_i8 v[60:63], v[108:111], v[20:23], v[60:63]
	v_mfma_i32_16x16x64_i8 v[52:55], v[124:127], v[20:23], v[52:55]
	v_mfma_i32_16x16x64_i8 v[44:47], v[108:111], v[28:31], v[44:47]
	v_mfma_i32_16x16x64_i8 v[36:39], v[124:127], v[28:31], v[36:39]
	v_mfma_i32_16x16x64_i8 v[92:95], v[112:115], v[8:11], v[92:95]
	v_mfma_i32_16x16x64_i8 v[84:87], v[128:131], v[8:11], v[84:87]
	v_mfma_i32_16x16x64_i8 v[76:79], v[112:115], v[16:19], v[76:79]
	v_mfma_i32_16x16x64_i8 v[68:71], v[128:131], v[16:19], v[68:71]
	v_mfma_i32_16x16x64_i8 v[60:63], v[112:115], v[24:27], v[60:63]
	v_mfma_i32_16x16x64_i8 v[52:55], v[128:131], v[24:27], v[52:55]
	v_mfma_i32_16x16x64_i8 v[44:47], v[112:115], v[32:35], v[44:47]
	v_mfma_i32_16x16x64_i8 v[36:39], v[128:131], v[32:35], v[36:39]
	s_setprio 0

.LBB0_3550:
	s_mov_b32 m0, s80
	s_add_u32 s98, s98, s18
	s_addc_u32 s99, s99, s19
	s_add_u32 s6, s56, 0x20080
	global_load_lds_dwordx4 v200, s[98:99]
	s_mov_b32 m0, s81
	s_addc_u32 s7, s57, 0
	global_load_lds_dwordx4 v204, s[98:99]
	s_mov_b32 m0, s84
	s_and_b64 vcc, exec, s[4:5]
	global_load_lds_dwordx4 v200, s[6:7]
	s_mov_b32 m0, s85
	s_nop 0
	global_load_lds_dwordx4 v204, s[6:7]
	s_add_u32 s100, s100, s18
	s_addc_u32 s101, s101, s19
	s_mov_b32 m0, s82
	s_nop 0
	global_load_lds_dwordx4 v198, s[100:101]
	s_mov_b32 m0, s83
	s_nop 0
	global_load_lds_dwordx4 v202, s[100:101]
	s_waitcnt vmcnt(8)
	s_waitcnt lgkmcnt(0)
	s_barrier
	s_cbranch_vccnz .LBB0_3535
	s_setprio 1
	s_waitcnt lgkmcnt(0)
	v_mfma_i32_16x16x64_i8 v[96:99], v[180:183], v[4:7], v[96:99]
	v_mfma_i32_16x16x64_i8 v[88:91], v[188:191], v[4:7], v[88:91]
	v_mfma_i32_16x16x64_i8 v[80:83], v[180:183], v[12:15], v[80:83]
	v_mfma_i32_16x16x64_i8 v[72:75], v[188:191], v[12:15], v[72:75]
	v_mfma_i32_16x16x64_i8 v[64:67], v[180:183], v[20:23], v[64:67]
	v_mfma_i32_16x16x64_i8 v[56:59], v[188:191], v[20:23], v[56:59]
	v_mfma_i32_16x16x64_i8 v[48:51], v[180:183], v[28:31], v[48:51]
	v_mfma_i32_16x16x64_i8 v[40:43], v[188:191], v[28:31], v[40:43]
	v_mfma_i32_16x16x64_i8 v[96:99], v[184:187], v[8:11], v[96:99]
	v_mfma_i32_16x16x64_i8 v[88:91], v[192:195], v[8:11], v[88:91]
	v_mfma_i32_16x16x64_i8 v[80:83], v[184:187], v[16:19], v[80:83]
	v_mfma_i32_16x16x64_i8 v[72:75], v[192:195], v[16:19], v[72:75]
	v_mfma_i32_16x16x64_i8 v[64:67], v[184:187], v[24:27], v[64:67]
	v_mfma_i32_16x16x64_i8 v[56:59], v[192:195], v[24:27], v[56:59]
	v_mfma_i32_16x16x64_i8 v[48:51], v[184:187], v[32:35], v[48:51]
	v_mfma_i32_16x16x64_i8 v[40:43], v[192:195], v[32:35], v[40:43]
	s_setprio 0
	s_setprio 1
	v_mfma_i32_16x16x64_i8 v[92:95], v[108:111], v[4:7], v[92:95]
	v_mfma_i32_16x16x64_i8 v[84:87], v[124:127], v[4:7], v[84:87]
	v_mfma_i32_16x16x64_i8 v[76:79], v[108:111], v[12:15], v[76:79]
	v_mfma_i32_16x16x64_i8 v[68:71], v[124:127], v[12:15], v[68:71]
	v_mfma_i32_16x16x64_i8 v[60:63], v[108:111], v[20:23], v[60:63]
	v_mfma_i32_16x16x64_i8 v[52:55], v[124:127], v[20:23], v[52:55]
	v_mfma_i32_16x16x64_i8 v[44:47], v[108:111], v[28:31], v[44:47]
	v_mfma_i32_16x16x64_i8 v[36:39], v[124:127], v[28:31], v[36:39]
	v_mfma_i32_16x16x64_i8 v[92:95], v[112:115], v[8:11], v[92:95]
	v_mfma_i32_16x16x64_i8 v[84:87], v[128:131], v[8:11], v[84:87]
	v_mfma_i32_16x16x64_i8 v[76:79], v[112:115], v[16:19], v[76:79]
	v_mfma_i32_16x16x64_i8 v[68:71], v[128:131], v[16:19], v[68:71]
	v_mfma_i32_16x16x64_i8 v[60:63], v[112:115], v[24:27], v[60:63]
	v_mfma_i32_16x16x64_i8 v[52:55], v[128:131], v[24:27], v[52:55]
	v_mfma_i32_16x16x64_i8 v[44:47], v[112:115], v[32:35], v[44:47]
	v_mfma_i32_16x16x64_i8 v[36:39], v[128:131], v[32:35], v[36:39]
	s_setprio 0
	s_branch .LBB0_3535

.LBB0_3694:
	s_add_u32 s22, s20, 0xfff50080
	s_addc_u32 s23, s21, -1
	s_add_i32 s57, 0, 0x10000
	s_cmp_eq_u32 s56, 40
	s_cselect_b32 s25, s5, s23
	s_cselect_b32 s24, s4, s22
	v_add_u32_e32 v153, s57, v151
	s_cselect_b32 s23, s19, s55
	s_cselect_b32 s22, s18, s54
	s_add_i32 s60, 0, 0x14000
	ds_read_b128 v[146:149], v153
	ds_read_b128 v[154:157], v153 offset:1024
	ds_read_b128 v[158:161], v153 offset:2048
	ds_read_b128 v[162:165], v153 offset:3072
	v_add_u32_e32 v153, s60, v151
	ds_read_b128 v[166:169], v153
	ds_read_b128 v[170:173], v153 offset:1024
	ds_read_b128 v[174:177], v153 offset:2048
	ds_read_b128 v[178:181], v153 offset:3072
	s_add_i32 m0, s41, 0xc000
	ds_read_b128 v[182:185], v152
	ds_read_b128 v[186:189], v152 offset:1024
	ds_read_b128 v[190:193], v152 offset:2048
	ds_read_b128 v[194:197], v152 offset:3072
	ds_read_b128 v[198:201], v152 offset:4096
	ds_read_b128 v[202:205], v152 offset:5120
	ds_read_b128 v[206:209], v152 offset:6144
	ds_read_b128 v[210:213], v152 offset:7168
	global_load_lds_dwordx4 v142, s[20:21]
	s_add_i32 m0, s41, 0xe000
	s_nop 0
	global_load_lds_dwordx4 v144, s[20:21]
	s_waitcnt vmcnt(8)
	s_waitcnt lgkmcnt(0)
	s_barrier
	s_setprio 1
	s_waitcnt lgkmcnt(0)
	v_mfma_f32_16x16x32_bf16 v[124:127], v[146:149], v[182:185], v[124:127]
	v_mfma_f32_16x16x32_bf16 v[120:123], v[158:161], v[182:185], v[120:123]
	v_mfma_f32_16x16x32_bf16 v[108:111], v[146:149], v[190:193], v[108:111]
	v_mfma_f32_16x16x32_bf16 v[104:107], v[158:161], v[190:193], v[104:107]
	v_mfma_f32_16x16x32_bf16 v[92:95], v[146:149], v[198:201], v[92:95]
	v_mfma_f32_16x16x32_bf16 v[88:91], v[158:161], v[198:201], v[88:91]
	v_mfma_f32_16x16x32_bf16 v[76:79], v[146:149], v[206:209], v[76:79]
	v_mfma_f32_16x16x32_bf16 v[72:75], v[158:161], v[206:209], v[72:75]
	v_mfma_f32_16x16x32_bf16 v[124:127], v[154:157], v[186:189], v[124:127]
	v_mfma_f32_16x16x32_bf16 v[120:123], v[162:165], v[186:189], v[120:123]
	v_mfma_f32_16x16x32_bf16 v[108:111], v[154:157], v[194:197], v[108:111]
	v_mfma_f32_16x16x32_bf16 v[104:107], v[162:165], v[194:197], v[104:107]
	v_mfma_f32_16x16x32_bf16 v[92:95], v[154:157], v[202:205], v[92:95]
	v_mfma_f32_16x16x32_bf16 v[88:91], v[162:165], v[202:205], v[88:91]
	v_mfma_f32_16x16x32_bf16 v[76:79], v[154:157], v[210:213], v[76:79]
	v_mfma_f32_16x16x32_bf16 v[72:75], v[162:165], v[210:213], v[72:75]
	s_setprio 0
	s_setprio 1
	v_mfma_f32_16x16x32_bf16 v[116:119], v[166:169], v[182:185], v[116:119]
	v_mfma_f32_16x16x32_bf16 v[112:115], v[174:177], v[182:185], v[112:115]
	v_mfma_f32_16x16x32_bf16 v[100:103], v[166:169], v[190:193], v[100:103]
	v_mfma_f32_16x16x32_bf16 v[96:99], v[174:177], v[190:193], v[96:99]
	v_mfma_f32_16x16x32_bf16 v[84:87], v[166:169], v[198:201], v[84:87]
	v_mfma_f32_16x16x32_bf16 v[80:83], v[174:177], v[198:201], v[80:83]
	v_mfma_f32_16x16x32_bf16 v[68:71], v[166:169], v[206:209], v[68:71]
	v_mfma_f32_16x16x32_bf16 v[64:67], v[174:177], v[206:209], v[64:67]
	v_mfma_f32_16x16x32_bf16 v[116:119], v[170:173], v[186:189], v[116:119]
	v_mfma_f32_16x16x32_bf16 v[112:115], v[178:181], v[186:189], v[112:115]
	v_mfma_f32_16x16x32_bf16 v[100:103], v[170:173], v[194:197], v[100:103]
	v_mfma_f32_16x16x32_bf16 v[96:99], v[178:181], v[194:197], v[96:99]
	v_mfma_f32_16x16x32_bf16 v[84:87], v[170:173], v[202:205], v[84:87]
	v_mfma_f32_16x16x32_bf16 v[80:83], v[178:181], v[202:205], v[80:83]
	v_mfma_f32_16x16x32_bf16 v[68:71], v[170:173], v[210:213], v[68:71]
	v_mfma_f32_16x16x32_bf16 v[64:67], v[178:181], v[210:213], v[64:67]
	s_setprio 0
	s_barrier
	s_add_i32 s57, s57, s40
	s_mov_b64 s[98:99], s[22:23]
	s_mov_b32 m0, s57
	ds_read_b128 v[182:185], v152 offset:16384
	ds_read_b128 v[186:189], v152 offset:17408
	ds_read_b128 v[190:193], v152 offset:18432
	ds_read_b128 v[194:197], v152 offset:19456
	ds_read_b128 v[198:201], v152 offset:20480
	ds_read_b128 v[202:205], v152 offset:21504
	ds_read_b128 v[206:209], v152 offset:22528
	ds_read_b128 v[210:213], v152 offset:23552
	global_load_lds_dwordx4 v128, s[22:23]
	s_add_i32 m0, s57, 0x2000
	s_add_u32 s58, s22, 0xb0000
	s_addc_u32 s59, s23, 0
	s_add_i32 s57, s60, s40
	global_load_lds_dwordx4 v138, s[22:23]
	s_mov_b32 m0, s57
	s_mov_b64 s[100:101], s[24:25]
	global_load_lds_dwordx4 v128, s[58:59]
	s_add_i32 m0, s57, 0x2000
	s_nop 0
	global_load_lds_dwordx4 v138, s[58:59]
	s_mov_b32 m0, s41
	s_nop 0
	global_load_lds_dwordx4 v134, s[24:25]
	s_mov_b32 m0, s42
	s_nop 0
	global_load_lds_dwordx4 v136, s[24:25]
	s_waitcnt vmcnt(8)
	s_waitcnt lgkmcnt(0)
	s_barrier
	s_setprio 1
	s_waitcnt lgkmcnt(0)
	v_mfma_f32_16x16x32_bf16 v[60:63], v[146:149], v[182:185], v[60:63]
	v_mfma_f32_16x16x32_bf16 v[56:59], v[158:161], v[182:185], v[56:59]
	v_mfma_f32_16x16x32_bf16 v[44:47], v[146:149], v[190:193], v[44:47]
	v_mfma_f32_16x16x32_bf16 v[40:43], v[158:161], v[190:193], v[40:43]
	v_mfma_f32_16x16x32_bf16 v[28:31], v[146:149], v[198:201], v[28:31]
	v_mfma_f32_16x16x32_bf16 v[24:27], v[158:161], v[198:201], v[24:27]
	v_mfma_f32_16x16x32_bf16 v[12:15], v[146:149], v[206:209], v[12:15]
	v_mfma_f32_16x16x32_bf16 v[8:11], v[158:161], v[206:209], v[8:11]
	v_mfma_f32_16x16x32_bf16 v[60:63], v[154:157], v[186:189], v[60:63]
	v_mfma_f32_16x16x32_bf16 v[56:59], v[162:165], v[186:189], v[56:59]
	v_mfma_f32_16x16x32_bf16 v[44:47], v[154:157], v[194:197], v[44:47]
	v_mfma_f32_16x16x32_bf16 v[40:43], v[162:165], v[194:197], v[40:43]
	v_mfma_f32_16x16x32_bf16 v[28:31], v[154:157], v[202:205], v[28:31]
	v_mfma_f32_16x16x32_bf16 v[24:27], v[162:165], v[202:205], v[24:27]
	v_mfma_f32_16x16x32_bf16 v[12:15], v[154:157], v[210:213], v[12:15]
	v_mfma_f32_16x16x32_bf16 v[8:11], v[162:165], v[210:213], v[8:11]
	s_setprio 0
	s_setprio 1
	v_mfma_f32_16x16x32_bf16 v[52:55], v[166:169], v[182:185], v[52:55]
	v_mfma_f32_16x16x32_bf16 v[48:51], v[174:177], v[182:185], v[48:51]
	v_mfma_f32_16x16x32_bf16 v[36:39], v[166:169], v[190:193], v[36:39]
	v_mfma_f32_16x16x32_bf16 v[32:35], v[174:177], v[190:193], v[32:35]
	v_mfma_f32_16x16x32_bf16 v[20:23], v[166:169], v[198:201], v[20:23]
	v_mfma_f32_16x16x32_bf16 v[16:19], v[174:177], v[198:201], v[16:19]
	v_mfma_f32_16x16x32_bf16 v[4:7], v[166:169], v[206:209], v[4:7]
	v_mfma_f32_16x16x32_bf16 v[0:3], v[174:177], v[206:209], v[0:3]
	v_mfma_f32_16x16x32_bf16 v[52:55], v[170:173], v[186:189], v[52:55]
	v_mfma_f32_16x16x32_bf16 v[48:51], v[178:181], v[186:189], v[48:51]
	v_mfma_f32_16x16x32_bf16 v[36:39], v[170:173], v[194:197], v[36:39]
	v_mfma_f32_16x16x32_bf16 v[32:35], v[178:181], v[194:197], v[32:35]
	v_mfma_f32_16x16x32_bf16 v[20:23], v[170:173], v[202:205], v[20:23]
	v_mfma_f32_16x16x32_bf16 v[16:19], v[178:181], v[202:205], v[16:19]
	v_mfma_f32_16x16x32_bf16 v[4:7], v[170:173], v[210:213], v[4:7]
	v_mfma_f32_16x16x32_bf16 v[0:3], v[178:181], v[210:213], v[0:3]
	s_setprio 0
	s_barrier
	s_add_i32 s57, 0, 0x18000
	v_add_u32_e32 v153, s57, v151
	s_add_i32 s58, 0, 0x1c000
	ds_read_b128 v[146:149], v153
	ds_read_b128 v[154:157], v153 offset:1024
	ds_read_b128 v[158:161], v153 offset:2048
	ds_read_b128 v[162:165], v153 offset:3072
	v_add_u32_e32 v153, s58, v151
	ds_read_b128 v[166:169], v153
	ds_read_b128 v[170:173], v153 offset:1024
	ds_read_b128 v[174:177], v153 offset:2048
	ds_read_b128 v[178:181], v153 offset:3072
	s_add_u32 s24, s24, 0xb0000
	s_addc_u32 s25, s25, 0
	s_mov_b32 m0, s43
	ds_read_b128 v[182:185], v152 offset:32768
	ds_read_b128 v[186:189], v152 offset:33792
	ds_read_b128 v[190:193], v152 offset:34816
	ds_read_b128 v[194:197], v152 offset:35840
	ds_read_b128 v[198:201], v152 offset:36864
	ds_read_b128 v[202:205], v152 offset:37888
	ds_read_b128 v[206:209], v152 offset:38912
	ds_read_b128 v[210:213], v152 offset:39936
	global_load_lds_dwordx4 v134, s[24:25]
	s_mov_b32 m0, s44
	s_nop 0
	global_load_lds_dwordx4 v136, s[24:25]
	s_waitcnt vmcnt(8)
	s_waitcnt lgkmcnt(0)
	s_barrier
	s_setprio 1
	s_waitcnt lgkmcnt(0)
	v_mfma_f32_16x16x32_bf16 v[124:127], v[146:149], v[182:185], v[124:127]
	v_mfma_f32_16x16x32_bf16 v[120:123], v[158:161], v[182:185], v[120:123]
	v_mfma_f32_16x16x32_bf16 v[108:111], v[146:149], v[190:193], v[108:111]
	v_mfma_f32_16x16x32_bf16 v[104:107], v[158:161], v[190:193], v[104:107]
	v_mfma_f32_16x16x32_bf16 v[92:95], v[146:149], v[198:201], v[92:95]
	v_mfma_f32_16x16x32_bf16 v[88:91], v[158:161], v[198:201], v[88:91]
	v_mfma_f32_16x16x32_bf16 v[76:79], v[146:149], v[206:209], v[76:79]
	v_mfma_f32_16x16x32_bf16 v[72:75], v[158:161], v[206:209], v[72:75]
	v_mfma_f32_16x16x32_bf16 v[124:127], v[154:157], v[186:189], v[124:127]
	v_mfma_f32_16x16x32_bf16 v[120:123], v[162:165], v[186:189], v[120:123]
	v_mfma_f32_16x16x32_bf16 v[108:111], v[154:157], v[194:197], v[108:111]
	v_mfma_f32_16x16x32_bf16 v[104:107], v[162:165], v[194:197], v[104:107]
	v_mfma_f32_16x16x32_bf16 v[92:95], v[154:157], v[202:205], v[92:95]
	v_mfma_f32_16x16x32_bf16 v[88:91], v[162:165], v[202:205], v[88:91]
	v_mfma_f32_16x16x32_bf16 v[76:79], v[154:157], v[210:213], v[76:79]
	v_mfma_f32_16x16x32_bf16 v[72:75], v[162:165], v[210:213], v[72:75]
	s_setprio 0
	s_setprio 1
	v_mfma_f32_16x16x32_bf16 v[116:119], v[166:169], v[182:185], v[116:119]
	v_mfma_f32_16x16x32_bf16 v[112:115], v[174:177], v[182:185], v[112:115]
	v_mfma_f32_16x16x32_bf16 v[100:103], v[166:169], v[190:193], v[100:103]
	v_mfma_f32_16x16x32_bf16 v[96:99], v[174:177], v[190:193], v[96:99]
	v_mfma_f32_16x16x32_bf16 v[84:87], v[166:169], v[198:201], v[84:87]
	v_mfma_f32_16x16x32_bf16 v[80:83], v[174:177], v[198:201], v[80:83]
	v_mfma_f32_16x16x32_bf16 v[68:71], v[166:169], v[206:209], v[68:71]
	v_mfma_f32_16x16x32_bf16 v[64:67], v[174:177], v[206:209], v[64:67]
	v_mfma_f32_16x16x32_bf16 v[116:119], v[170:173], v[186:189], v[116:119]
	v_mfma_f32_16x16x32_bf16 v[112:115], v[178:181], v[186:189], v[112:115]
	v_mfma_f32_16x16x32_bf16 v[100:103], v[170:173], v[194:197], v[100:103]
	v_mfma_f32_16x16x32_bf16 v[96:99], v[178:181], v[194:197], v[96:99]
	v_mfma_f32_16x16x32_bf16 v[84:87], v[170:173], v[202:205], v[84:87]
	v_mfma_f32_16x16x32_bf16 v[80:83], v[178:181], v[202:205], v[80:83]
	v_mfma_f32_16x16x32_bf16 v[68:71], v[170:173], v[210:213], v[68:71]
	v_mfma_f32_16x16x32_bf16 v[64:67], v[178:181], v[210:213], v[64:67]
	s_setprio 0
	s_barrier
	s_add_i32 s24, s57, s40
	s_add_u32 s98, s98, s6
	s_addc_u32 s99, s99, s7
	s_mov_b32 m0, s24
	ds_read_b128 v[182:185], v152 offset:49152
	ds_read_b128 v[186:189], v152 offset:50176
	ds_read_b128 v[190:193], v152 offset:51200
	ds_read_b128 v[194:197], v152 offset:52224
	ds_read_b128 v[198:201], v152 offset:53248
	ds_read_b128 v[202:205], v152 offset:54272
	ds_read_b128 v[206:209], v152 offset:55296
	ds_read_b128 v[210:213], v152 offset:56320
	global_load_lds_dwordx4 v128, s[98:99]
	s_add_i32 m0, s24, 0x2000
	s_add_u32 s22, s22, 0xb0080
	s_addc_u32 s23, s23, 0
	s_add_i32 s24, s58, s40
	global_load_lds_dwordx4 v138, s[98:99]
	s_mov_b32 m0, s24
	s_nop 0
	global_load_lds_dwordx4 v128, s[22:23]
	s_add_i32 m0, s24, 0x2000
	s_nop 0
	global_load_lds_dwordx4 v138, s[22:23]
	s_add_u32 s100, s100, s6
	s_addc_u32 s101, s101, s7
	s_mov_b32 m0, s45
	s_nop 0
	global_load_lds_dwordx4 v134, s[100:101]
	s_mov_b32 m0, s48
	s_nop 0
	global_load_lds_dwordx4 v136, s[100:101]
	s_waitcnt vmcnt(8)
	s_waitcnt lgkmcnt(0)
	s_barrier
	s_setprio 1
	s_waitcnt lgkmcnt(0)
	v_mfma_f32_16x16x32_bf16 v[60:63], v[146:149], v[182:185], v[60:63]
	v_mfma_f32_16x16x32_bf16 v[56:59], v[158:161], v[182:185], v[56:59]
	v_mfma_f32_16x16x32_bf16 v[44:47], v[146:149], v[190:193], v[44:47]
	v_mfma_f32_16x16x32_bf16 v[40:43], v[158:161], v[190:193], v[40:43]
	v_mfma_f32_16x16x32_bf16 v[28:31], v[146:149], v[198:201], v[28:31]
	v_mfma_f32_16x16x32_bf16 v[24:27], v[158:161], v[198:201], v[24:27]
	v_mfma_f32_16x16x32_bf16 v[12:15], v[146:149], v[206:209], v[12:15]
	v_mfma_f32_16x16x32_bf16 v[8:11], v[158:161], v[206:209], v[8:11]
	v_mfma_f32_16x16x32_bf16 v[60:63], v[154:157], v[186:189], v[60:63]
	v_mfma_f32_16x16x32_bf16 v[56:59], v[162:165], v[186:189], v[56:59]
	v_mfma_f32_16x16x32_bf16 v[44:47], v[154:157], v[194:197], v[44:47]
	v_mfma_f32_16x16x32_bf16 v[40:43], v[162:165], v[194:197], v[40:43]
	v_mfma_f32_16x16x32_bf16 v[28:31], v[154:157], v[202:205], v[28:31]
	v_mfma_f32_16x16x32_bf16 v[24:27], v[162:165], v[202:205], v[24:27]
	v_mfma_f32_16x16x32_bf16 v[12:15], v[154:157], v[210:213], v[12:15]
	v_mfma_f32_16x16x32_bf16 v[8:11], v[162:165], v[210:213], v[8:11]
	s_setprio 0
	s_setprio 1
	v_mfma_f32_16x16x32_bf16 v[52:55], v[166:169], v[182:185], v[52:55]
	v_mfma_f32_16x16x32_bf16 v[48:51], v[174:177], v[182:185], v[48:51]
	v_mfma_f32_16x16x32_bf16 v[36:39], v[166:169], v[190:193], v[36:39]
	v_mfma_f32_16x16x32_bf16 v[32:35], v[174:177], v[190:193], v[32:35]
	v_mfma_f32_16x16x32_bf16 v[20:23], v[166:169], v[198:201], v[20:23]
	v_mfma_f32_16x16x32_bf16 v[16:19], v[174:177], v[198:201], v[16:19]
	v_mfma_f32_16x16x32_bf16 v[4:7], v[166:169], v[206:209], v[4:7]
	v_mfma_f32_16x16x32_bf16 v[0:3], v[174:177], v[206:209], v[0:3]
	v_mfma_f32_16x16x32_bf16 v[52:55], v[170:173], v[186:189], v[52:55]
	v_mfma_f32_16x16x32_bf16 v[48:51], v[178:181], v[186:189], v[48:51]
	v_mfma_f32_16x16x32_bf16 v[36:39], v[170:173], v[194:197], v[36:39]
	v_mfma_f32_16x16x32_bf16 v[32:35], v[178:181], v[194:197], v[32:35]
	v_mfma_f32_16x16x32_bf16 v[20:23], v[170:173], v[202:205], v[20:23]
	v_mfma_f32_16x16x32_bf16 v[16:19], v[178:181], v[202:205], v[16:19]
	v_mfma_f32_16x16x32_bf16 v[4:7], v[170:173], v[210:213], v[4:7]
	v_mfma_f32_16x16x32_bf16 v[0:3], v[178:181], v[210:213], v[0:3]
	s_setprio 0
	s_barrier
	s_add_i32 s56, s56, 2
	s_add_u32 s20, s20, 0x100
	s_addc_u32 s21, s21, 0
	s_add_u32 s54, s54, 0x100
	s_addc_u32 s55, s55, 0
	s_cmp_gt_u32 s56, 41
	s_cbranch_scc0 .LBB0_3694
	s_and_b64 vcc, exec, s[16:17]
	s_cbranch_vccz .LBB0_3698
	s_barrier
	s_andn2_b64 vcc, exec, s[12:13]
	s_cbranch_vccz .LBB0_3699
